# de-serialised residual+gain loads in Ph4/Ph6 exchange epilogues (all chains, fresh-register pool)
# speedup vs baseline: 1.1407x; 1.0126x over previous
.LBB0_199:
	s_or_b64 exec, exec, s[26:27]
	s_lshl_b64 s[40:41], s[0:1], 11
	s_add_u32 s28, s66, s40
	s_addc_u32 s29, s67, s41
	s_mul_i32 s40, s4, 0xc0
	s_ashr_i32 s41, s40, 31
	s_lshl_b64 s[46:47], s[40:41], 11
	s_add_u32 s36, s80, s46
	s_addc_u32 s37, s81, s47
	v_lshrrev_b32_e32 v196, 3, v197
	v_and_b32_e32 v198, 7, v197
	v_lshlrev_b32_e32 v138, 11, v196
	v_lshl_or_b32 v138, v198, 4, v138
	v_add_u32_e32 v139, 0x10000, v138
	v_add_u32_e32 v140, 0x20000, v138
	v_add_u32_e32 v141, 0x30000, v138
	v_add_u32_e32 v142, 0x40000, v138
	v_add_u32_e32 v143, 0x50000, v138
	global_load_dwordx4 v[96:99], v138, s[28:29]
	global_load_dwordx4 v[100:103], v139, s[28:29]
	global_load_dwordx4 v[104:107], v140, s[28:29]
	global_load_dwordx4 v[108:111], v141, s[28:29]
	global_load_dwordx4 v[112:115], v138, s[36:37]
	global_load_dwordx4 v[116:119], v139, s[36:37]
	global_load_dwordx4 v[120:123], v140, s[36:37]
	global_load_dwordx4 v[124:127], v141, s[36:37]
	global_load_dwordx4 v[128:131], v142, s[36:37]
	global_load_dwordx4 v[132:135], v143, s[36:37]
	s_add_u32 s28, s28, 0x80
	s_addc_u32 s29, s29, 0
	s_add_u32 s36, s36, 0x80
	s_addc_u32 s37, s37, 0
	s_mul_i32 s26, s4, 0xc0
	s_ashr_i32 s27, s26, 31
	v_bfe_u32 v217, v197, 5, 2
	v_and_b32_e32 v218, 3, v198
	v_xor_b32_e32 v218, v218, v217
	v_lshlrev_b32_e32 v218, 4, v218
	v_lshl_or_b32 v250, v196, 6, v218
	v_lshrrev_b32_e32 v217, 2, v198
	v_lshlrev_b32_e32 v218, 6, v217
	v_xor_b32_e32 v250, v250, v218
	v_mul_u32_u24_e32 v217, 0x5000, v217
	v_add_u32_e32 v250, v250, v217
	v_and_b32_e32 v196, 31, v197
	v_bfe_u32 v198, v197, 5, 1
	v_bfe_u32 v217, v197, 2, 2
	v_xor_b32_e32 v218, v198, v217
	v_xor_b32_e32 v221, 2, v218
	v_lshrrev_b32_e32 v198, 7, v197
	v_lshl_or_b32 v198, v198, 6, v196
	v_lshlrev_b32_e32 v198, 6, v198
	v_lshl_or_b32 v242, v218, 4, v198
	v_lshl_or_b32 v243, v221, 4, v198
	v_bfe_u32 v198, v197, 6, 1
	v_mul_u32_u24_e32 v198, 96, v198
	v_add_u32_e32 v198, v198, v196
	v_lshlrev_b32_e32 v198, 6, v198
	v_add_u32_e32 v198, 0x2000, v198
	v_lshl_or_b32 v244, v218, 4, v198
	v_lshl_or_b32 v245, v221, 4, v198
	v_mov_b64_e32 v[0:1], 0
	v_mov_b64_e32 v[2:3], 0
	v_mov_b64_e32 v[4:5], 0
	v_mov_b64_e32 v[6:7], 0
	v_mov_b64_e32 v[8:9], 0
	v_mov_b64_e32 v[10:11], 0
	v_mov_b64_e32 v[12:13], 0
	v_mov_b64_e32 v[14:15], 0
	v_mov_b64_e32 v[16:17], 0
	v_mov_b64_e32 v[18:19], 0
	v_mov_b64_e32 v[20:21], 0
	v_mov_b64_e32 v[22:23], 0
	v_mov_b64_e32 v[24:25], 0
	v_mov_b64_e32 v[26:27], 0
	v_mov_b64_e32 v[28:29], 0
	v_mov_b64_e32 v[30:31], 0
	v_mov_b64_e32 v[32:33], 0
	v_mov_b64_e32 v[34:35], 0
	v_mov_b64_e32 v[36:37], 0
	v_mov_b64_e32 v[38:39], 0
	v_mov_b64_e32 v[40:41], 0
	v_mov_b64_e32 v[42:43], 0
	v_mov_b64_e32 v[44:45], 0
	v_mov_b64_e32 v[46:47], 0
	v_mov_b64_e32 v[48:49], 0
	v_mov_b64_e32 v[50:51], 0
	v_mov_b64_e32 v[52:53], 0
	v_mov_b64_e32 v[54:55], 0
	v_mov_b64_e32 v[56:57], 0
	v_mov_b64_e32 v[58:59], 0
	v_mov_b64_e32 v[60:61], 0
	v_mov_b64_e32 v[62:63], 0
	v_mov_b64_e32 v[64:65], 0
	v_mov_b64_e32 v[66:67], 0
	v_mov_b64_e32 v[68:69], 0
	v_mov_b64_e32 v[70:71], 0
	v_mov_b64_e32 v[72:73], 0
	v_mov_b64_e32 v[74:75], 0
	v_mov_b64_e32 v[76:77], 0
	v_mov_b64_e32 v[78:79], 0
	v_mov_b64_e32 v[80:81], 0
	v_mov_b64_e32 v[82:83], 0
	v_mov_b64_e32 v[84:85], 0
	v_mov_b64_e32 v[86:87], 0
	v_mov_b64_e32 v[88:89], 0
	v_mov_b64_e32 v[90:91], 0
	v_mov_b64_e32 v[92:93], 0
	v_mov_b64_e32 v[94:95], 0
	s_mov_b32 s38, 0
	s_mov_b32 s39, 0x5000
	s_mov_b32 s5, 0
	s_waitcnt vmcnt(9)
	ds_write_b128 v250, v[96:99]
	s_waitcnt vmcnt(8)
	ds_write_b128 v250, v[100:103] offset:2048
	s_waitcnt vmcnt(7)
	ds_write_b128 v250, v[104:107] offset:4096
	s_waitcnt vmcnt(6)
	ds_write_b128 v250, v[108:111] offset:6144
	s_waitcnt vmcnt(5)
	ds_write_b128 v250, v[112:115] offset:8192
	s_waitcnt vmcnt(4)
	ds_write_b128 v250, v[116:119] offset:10240
	s_waitcnt vmcnt(3)
	ds_write_b128 v250, v[120:123] offset:12288
	s_waitcnt vmcnt(2)
	ds_write_b128 v250, v[124:127] offset:14336
	s_waitcnt vmcnt(1)
	ds_write_b128 v250, v[128:131] offset:16384
	s_waitcnt vmcnt(0)
	ds_write_b128 v250, v[132:135] offset:18432
	v_subrev_u32_e32 v196, 0x5000, v250
	v_add_u32_e32 v198, 0xa000, v250
	v_min_u32_e32 v250, v196, v198
	s_waitcnt lgkmcnt(0)
	s_barrier
.Lg1_loop:
	v_add_u32_e32 v246, s38, v242
	v_add_u32_e32 v247, s38, v243
	v_add_u32_e32 v248, s38, v244
	v_add_u32_e32 v249, s38, v245
	ds_read_b128 v[144:147], v246
	ds_read_b128 v[148:151], v246 offset:2048
	ds_read_b128 v[160:163], v248
	ds_read_b128 v[164:167], v248 offset:2048
	ds_read_b128 v[168:171], v248 offset:4096
	s_setprio 1
	s_waitcnt lgkmcnt(2)
	v_mfma_f32_32x32x16_bf16 v[80:95], v[144:147], v[160:163], v[80:95]
	global_load_dwordx4 v[96:99], v138, s[28:29]
	ds_read_b128 v[152:155], v247
	v_mfma_f32_32x32x16_bf16 v[32:47], v[148:151], v[160:163], v[32:47]
	global_load_dwordx4 v[100:103], v139, s[28:29]
	ds_read_b128 v[156:159], v247 offset:2048
	s_waitcnt lgkmcnt(3)
	v_mfma_f32_32x32x16_bf16 v[64:79], v[144:147], v[164:167], v[64:79]
	global_load_dwordx4 v[104:107], v140, s[28:29]
	ds_read_b128 v[172:175], v249
	v_mfma_f32_32x32x16_bf16 v[16:31], v[148:151], v[164:167], v[16:31]
	global_load_dwordx4 v[108:111], v141, s[28:29]
	ds_read_b128 v[176:179], v249 offset:2048
	s_waitcnt lgkmcnt(4)
	v_mfma_f32_32x32x16_bf16 v[48:63], v[144:147], v[168:171], v[48:63]
	global_load_dwordx4 v[112:115], v138, s[36:37]
	ds_read_b128 v[180:183], v249 offset:4096
	v_mfma_f32_32x32x16_bf16 v[0:15], v[148:151], v[168:171], v[0:15]
	global_load_dwordx4 v[116:119], v139, s[36:37]
	v_xad_u32 v246, v242, 64, s39
	v_xad_u32 v248, v244, 64, s39
	s_waitcnt lgkmcnt(2)
	v_mfma_f32_32x32x16_bf16 v[80:95], v[152:155], v[172:175], v[80:95]
	global_load_dwordx4 v[120:123], v140, s[36:37]
	ds_read_b128 v[144:147], v246
	v_mfma_f32_32x32x16_bf16 v[32:47], v[156:159], v[172:175], v[32:47]
	global_load_dwordx4 v[124:127], v141, s[36:37]
	ds_read_b128 v[148:151], v246 offset:2048
	s_waitcnt lgkmcnt(3)
	v_mfma_f32_32x32x16_bf16 v[64:79], v[152:155], v[176:179], v[64:79]
	global_load_dwordx4 v[128:131], v142, s[36:37]
	ds_read_b128 v[160:163], v248
	v_mfma_f32_32x32x16_bf16 v[16:31], v[156:159], v[176:179], v[16:31]
	global_load_dwordx4 v[132:135], v143, s[36:37]
	ds_read_b128 v[164:167], v248 offset:2048
	s_waitcnt lgkmcnt(4)
	v_mfma_f32_32x32x16_bf16 v[48:63], v[152:155], v[180:183], v[48:63]
	ds_read_b128 v[168:171], v248 offset:4096
	v_mfma_f32_32x32x16_bf16 v[0:15], v[156:159], v[180:183], v[0:15]
	s_setprio 0
	s_barrier
	v_xad_u32 v247, v243, 64, s39
	v_xad_u32 v249, v245, 64, s39
	s_setprio 1
	s_waitcnt lgkmcnt(2)
	v_mfma_f32_32x32x16_bf16 v[80:95], v[144:147], v[160:163], v[80:95]
	ds_read_b128 v[152:155], v247
	v_mfma_f32_32x32x16_bf16 v[32:47], v[148:151], v[160:163], v[32:47]
	ds_read_b128 v[156:159], v247 offset:2048
	s_waitcnt lgkmcnt(3)
	v_mfma_f32_32x32x16_bf16 v[64:79], v[144:147], v[164:167], v[64:79]
	ds_read_b128 v[172:175], v249
	s_waitcnt vmcnt(9)
	ds_write_b128 v250, v[96:99]
	v_mfma_f32_32x32x16_bf16 v[16:31], v[148:151], v[164:167], v[16:31]
	ds_read_b128 v[176:179], v249 offset:2048
	s_waitcnt vmcnt(8)
	ds_write_b128 v250, v[100:103] offset:2048
	s_waitcnt lgkmcnt(6)
	v_mfma_f32_32x32x16_bf16 v[48:63], v[144:147], v[168:171], v[48:63]
	ds_read_b128 v[180:183], v249 offset:4096
	s_waitcnt vmcnt(7)
	ds_write_b128 v250, v[104:107] offset:4096
	v_mfma_f32_32x32x16_bf16 v[0:15], v[148:151], v[168:171], v[0:15]
	s_waitcnt vmcnt(6)
	ds_write_b128 v250, v[108:111] offset:6144
	s_waitcnt lgkmcnt(6)
	v_mfma_f32_32x32x16_bf16 v[80:95], v[152:155], v[172:175], v[80:95]
	s_waitcnt vmcnt(5)
	ds_write_b128 v250, v[112:115] offset:8192
	v_mfma_f32_32x32x16_bf16 v[32:47], v[156:159], v[172:175], v[32:47]
	s_waitcnt vmcnt(4)
	ds_write_b128 v250, v[116:119] offset:10240
	s_waitcnt lgkmcnt(6)
	v_mfma_f32_32x32x16_bf16 v[64:79], v[152:155], v[176:179], v[64:79]
	s_waitcnt vmcnt(3)
	ds_write_b128 v250, v[120:123] offset:12288
	v_mfma_f32_32x32x16_bf16 v[16:31], v[156:159], v[176:179], v[16:31]
	s_waitcnt vmcnt(2)
	ds_write_b128 v250, v[124:127] offset:14336
	s_waitcnt lgkmcnt(6)
	v_mfma_f32_32x32x16_bf16 v[48:63], v[152:155], v[180:183], v[48:63]
	s_waitcnt vmcnt(1)
	ds_write_b128 v250, v[128:131] offset:16384
	v_mfma_f32_32x32x16_bf16 v[0:15], v[156:159], v[180:183], v[0:15]
	s_waitcnt vmcnt(0)
	ds_write_b128 v250, v[132:135] offset:18432
	s_setprio 0
	s_add_u32 s28, s28, 0x80
	s_addc_u32 s29, s29, 0
	s_add_u32 s36, s36, 0x80
	s_addc_u32 s37, s37, 0
	s_sub_i32 s38, s38, 0x5000
	s_cmp_lt_i32 s38, 0
	s_cselect_b32 s40, 0xf000, 0
	s_add_i32 s38, s38, s40
	s_sub_i32 s39, s39, 0x5000
	s_cmp_lt_i32 s39, 0
	s_cselect_b32 s40, 0xf000, 0
	s_add_i32 s39, s39, s40
	v_subrev_u32_e32 v196, 0x5000, v250
	v_add_u32_e32 v198, 0xa000, v250
	v_min_u32_e32 v250, v196, v198
	s_add_i32 s5, s5, 1
	s_cmp_lt_u32 s5, 15
	s_waitcnt lgkmcnt(0)
	s_barrier
	s_cbranch_scc1 .Lg1_loop
	v_add_u32_e32 v246, s38, v242
	v_add_u32_e32 v247, s38, v243
	v_add_u32_e32 v248, s38, v244
	v_add_u32_e32 v249, s38, v245
	ds_read_b128 v[144:147], v246
	ds_read_b128 v[148:151], v246 offset:2048
	ds_read_b128 v[160:163], v248
	ds_read_b128 v[164:167], v248 offset:2048
	ds_read_b128 v[168:171], v248 offset:4096
	s_setprio 1
	s_waitcnt lgkmcnt(2)
	v_mfma_f32_32x32x16_bf16 v[80:95], v[144:147], v[160:163], v[80:95]
	ds_read_b128 v[152:155], v247
	v_mfma_f32_32x32x16_bf16 v[32:47], v[148:151], v[160:163], v[32:47]
	ds_read_b128 v[156:159], v247 offset:2048
	s_waitcnt lgkmcnt(3)
	v_mfma_f32_32x32x16_bf16 v[64:79], v[144:147], v[164:167], v[64:79]
	ds_read_b128 v[172:175], v249
	v_mfma_f32_32x32x16_bf16 v[16:31], v[148:151], v[164:167], v[16:31]
	ds_read_b128 v[176:179], v249 offset:2048
	s_waitcnt lgkmcnt(4)
	v_mfma_f32_32x32x16_bf16 v[48:63], v[144:147], v[168:171], v[48:63]
	ds_read_b128 v[180:183], v249 offset:4096
	v_mfma_f32_32x32x16_bf16 v[0:15], v[148:151], v[168:171], v[0:15]
	v_xad_u32 v246, v242, 64, s39
	v_xad_u32 v248, v244, 64, s39
	s_waitcnt lgkmcnt(2)
	v_mfma_f32_32x32x16_bf16 v[80:95], v[152:155], v[172:175], v[80:95]
	ds_read_b128 v[144:147], v246
	v_mfma_f32_32x32x16_bf16 v[32:47], v[156:159], v[172:175], v[32:47]
	ds_read_b128 v[148:151], v246 offset:2048
	s_waitcnt lgkmcnt(3)
	v_mfma_f32_32x32x16_bf16 v[64:79], v[152:155], v[176:179], v[64:79]
	ds_read_b128 v[160:163], v248
	v_mfma_f32_32x32x16_bf16 v[16:31], v[156:159], v[176:179], v[16:31]
	ds_read_b128 v[164:167], v248 offset:2048
	s_waitcnt lgkmcnt(4)
	v_mfma_f32_32x32x16_bf16 v[48:63], v[152:155], v[180:183], v[48:63]
	ds_read_b128 v[168:171], v248 offset:4096
	v_mfma_f32_32x32x16_bf16 v[0:15], v[156:159], v[180:183], v[0:15]
	s_setprio 0
	v_xad_u32 v247, v243, 64, s39
	v_xad_u32 v249, v245, 64, s39
	s_setprio 1
	s_waitcnt lgkmcnt(2)
	v_mfma_f32_32x32x16_bf16 v[80:95], v[144:147], v[160:163], v[80:95]
	ds_read_b128 v[152:155], v247
	v_mfma_f32_32x32x16_bf16 v[32:47], v[148:151], v[160:163], v[32:47]
	ds_read_b128 v[156:159], v247 offset:2048
	s_waitcnt lgkmcnt(3)
	v_mfma_f32_32x32x16_bf16 v[64:79], v[144:147], v[164:167], v[64:79]
	ds_read_b128 v[172:175], v249
	v_mfma_f32_32x32x16_bf16 v[16:31], v[148:151], v[164:167], v[16:31]
	ds_read_b128 v[176:179], v249 offset:2048
	s_waitcnt lgkmcnt(4)
	v_mfma_f32_32x32x16_bf16 v[48:63], v[144:147], v[168:171], v[48:63]
	ds_read_b128 v[180:183], v249 offset:4096
	v_mfma_f32_32x32x16_bf16 v[0:15], v[148:151], v[168:171], v[0:15]
	s_waitcnt lgkmcnt(2)
	v_mfma_f32_32x32x16_bf16 v[80:95], v[152:155], v[172:175], v[80:95]
	v_mfma_f32_32x32x16_bf16 v[32:47], v[156:159], v[172:175], v[32:47]
	s_waitcnt lgkmcnt(1)
	v_mfma_f32_32x32x16_bf16 v[64:79], v[152:155], v[176:179], v[64:79]
	v_mfma_f32_32x32x16_bf16 v[16:31], v[156:159], v[176:179], v[16:31]
	s_waitcnt lgkmcnt(0)
	v_mfma_f32_32x32x16_bf16 v[48:63], v[152:155], v[180:183], v[48:63]
	v_mfma_f32_32x32x16_bf16 v[0:15], v[156:159], v[180:183], v[0:15]
	s_setprio 0
	s_nop 7
	s_nop 7

.LBB0_424:
	s_or_b64 exec, exec, s[48:49]
	s_lshl_b32 s0, s9, 7
	s_add_u32 s1, s66, s8
	s_addc_u32 s8, s67, 0
	s_lshl_b32 s9, s0, 1
	s_add_u32 s48, s1, s9
	s_addc_u32 s49, s8, 0
	s_or_b32 s68, s0, s68
	s_lshl_b32 s0, s7, 2
	s_add_i32 s39, s0, 0
	s_add_i32 s39, s39, 0x12200
	s_lshl_b32 s0, s6, 2
	v_readlane_b32 s1, v253, 62
	s_add_u32 s26, s1, s0
	v_readlane_b32 s0, v253, 63
	s_addc_u32 s27, s0, 0
	v_mov_b32_e32 v134, v130
	s_add_u32 s28, s48, s28
	s_waitcnt lgkmcnt(0)
	s_barrier
	s_addc_u32 s29, s49, s29
	v_ashrrev_i32_e32 v135, 31, v134
	v_lshl_add_u64 v[134:135], v[134:135], 1, s[28:29]
	global_load_ushort v190, v[134:135], off offset:64
	s_waitcnt vmcnt(8)
	v_lshlrev_b32_e32 v147, 16, v166
	v_add_co_u32_e64 v144, s[0:1], s96, v134
	v_lshlrev_b32_e32 v187, 16, v165
	s_nop 0
	v_addc_co_u32_e64 v145, s[0:1], 0, v135, s[0:1]
	v_lshlrev_b32_e32 v186, 16, v164
	v_lshlrev_b32_e32 v185, 16, v163
	v_lshlrev_b32_e32 v184, 16, v162
	v_lshlrev_b32_e32 v175, 16, v159
	v_lshlrev_b32_e32 v183, 16, v161
	v_lshlrev_b32_e32 v182, 16, v160
	s_waitcnt vmcnt(7)
	v_lshlrev_b32_e32 v146, 16, v167
	v_mov_b32_e32 v167, v158
	s_waitcnt vmcnt(6)
	v_lshlrev_b32_e32 v142, 16, v168
	s_waitcnt vmcnt(5)
	v_lshlrev_b32_e32 v140, 16, v169
	s_waitcnt vmcnt(4)
	v_lshlrev_b32_e32 v139, 16, v170
	s_waitcnt vmcnt(3)
	v_lshlrev_b32_e32 v136, 16, v171
	v_lshlrev_b32_e32 v174, 16, v131
	s_waitcnt vmcnt(1)
	v_lshlrev_b32_e32 v129, 16, v173
	v_lshlrev_b32_e32 v131, 16, v172
	s_waitcnt vmcnt(1)
	global_load_ushort v165, v[134:135], off offset:2112
	s_waitcnt vmcnt(2)
	global_load_ushort v164, v[144:145], off offset:64
	s_waitcnt vmcnt(3)
	global_load_ushort v163, v[144:145], off offset:2112
	v_add_co_u32_e64 v144, s[0:1], s94, v134
	s_waitcnt vmcnt(4)
	v_addc_co_u32_e64 v145, s[0:1], 0, v135, s[0:1]
	global_load_ushort v162, v[144:145], off offset:64
	s_waitcnt vmcnt(5)
	global_load_ushort v159, v[144:145], off offset:2112
	v_add_co_u32_e64 v144, s[0:1], s57, v134
	s_waitcnt vmcnt(6)
	v_addc_co_u32_e64 v145, s[0:1], 0, v135, s[0:1]
	global_load_ushort v161, v[144:145], off offset:64
	s_waitcnt vmcnt(7)
	global_load_ushort v160, v[144:145], off offset:2112
	v_add_co_u32_e64 v144, s[0:1], s35, v134
	s_waitcnt vmcnt(8)
	v_addc_co_u32_e64 v145, s[0:1], 0, v135, s[0:1]
	global_load_ushort v150, v[144:145], off offset:64
	v_add_co_u32_e64 v148, s[0:1], s58, v134
	s_waitcnt vmcnt(9)
	global_load_ushort v144, v[144:145], off offset:2112
	v_addc_co_u32_e64 v149, s[0:1], 0, v135, s[0:1]
	s_waitcnt vmcnt(10)
	global_load_ushort v151, v[148:149], off offset:64
	s_waitcnt vmcnt(11)
	global_load_ushort v145, v[148:149], off offset:2112
	v_add_co_u32_e64 v148, s[0:1], s95, v134
	s_waitcnt vmcnt(12)
	v_addc_co_u32_e64 v149, s[0:1], 0, v135, s[0:1]
	global_load_ushort v143, v[148:149], off offset:64
	v_add_co_u32_e64 v134, s[0:1], s59, v134
	s_nop 1
	v_addc_co_u32_e64 v135, s[0:1], 0, v135, s[0:1]
	global_load_ushort v141, v[134:135], off offset:64
	s_waitcnt vmcnt(14)
	global_load_ushort v137, v[148:149], off offset:2112
	s_waitcnt vmcnt(15)
	global_load_ushort v138, v[134:135], off offset:2112
	s_waitcnt vmcnt(16)
	s_waitcnt vmcnt(16)
	v_mov_b32_e32 v134, v128
	s_nop 0
	v_add_u32_e32 v134, s68, v134
	v_ashrrev_i32_e32 v135, 31, v134
	v_lshl_add_u64 v[148:149], v[134:135], 2, s[36:37]
	global_load_dword v240, v[148:149], off
	global_load_dword v241, v[148:149], off offset:128
	global_load_dword v242, v[148:149], off offset:256
	global_load_dword v243, v[148:149], off offset:384
	v_lshl_add_u32 v148, v167, 2, s38
	v_lshl_add_u32 v167, v167, 4, s39
	ds_read_b128 v[168:171], v167
	ds_read_b128 v[178:181], v167 offset:32
	v_ashrrev_i32_e32 v149, 31, v148
	v_lshlrev_b64 v[148:149], 11, v[148:149]
	v_lshl_add_u64 v[148:149], s[66:67], 0, v[148:149]
	s_waitcnt lgkmcnt(1)
	v_mul_f32_e32 v112, v112, v168
	v_lshl_add_u64 v[134:135], v[134:135], 1, v[148:149]
	s_waitcnt vmcnt(20)
	s_waitcnt vmcnt(3)
	v_fmac_f32_e32 v174, v240, v112
	v_cvt_pk_bf16_f32 v112, v174, s0
	v_lshlrev_b32_e32 v177, 16, v112
	global_store_short v[134:135], v112, off
	v_mul_f32_e32 v112, v113, v169
	v_fmac_f32_e32 v175, v240, v112
	v_cvt_pk_bf16_f32 v112, v175, s0
	v_lshlrev_b32_e32 v176, 16, v112
	global_store_short v[134:135], v112, off offset:2048
	v_mul_f32_e32 v112, v114, v170
	v_fmac_f32_e32 v182, v240, v112
	v_cvt_pk_bf16_f32 v114, v182, s0
	v_add_co_u32_e64 v112, s[0:1], s96, v134
	v_lshlrev_b32_e32 v175, 16, v114
	s_nop 0
	v_addc_co_u32_e64 v113, s[0:1], 0, v135, s[0:1]
	global_store_short v[112:113], v114, off
	v_mul_f32_e32 v114, v115, v171
	v_fmac_f32_e32 v183, v240, v114
	v_cvt_pk_bf16_f32 v114, v183, s0
	global_store_short v[112:113], v114, off offset:2048
	s_waitcnt lgkmcnt(0)
	v_mul_f32_e32 v112, v116, v178
	v_fmac_f32_e32 v184, v240, v112
	v_cvt_pk_bf16_f32 v116, v184, s0
	v_add_co_u32_e64 v112, s[0:1], s94, v134
	v_lshlrev_b32_e32 v174, 16, v114
	s_nop 0
	v_addc_co_u32_e64 v113, s[0:1], 0, v135, s[0:1]
	v_add_co_u32_e64 v114, s[0:1], s57, v134
	v_lshlrev_b32_e32 v173, 16, v116
	s_nop 0
	v_addc_co_u32_e64 v115, s[0:1], 0, v135, s[0:1]
	global_store_short v[114:115], v116, off offset:-4096
	v_mul_f32_e32 v116, v117, v179
	v_fmac_f32_e32 v185, v240, v116
	v_cvt_pk_bf16_f32 v117, v185, s0
	global_store_short v[112:113], v117, off offset:2048
	v_mul_f32_e32 v112, v118, v180
	v_fmac_f32_e32 v186, v240, v112
	v_cvt_pk_bf16_f32 v112, v186, s0
	v_lshlrev_b32_e32 v172, 16, v112
	global_store_short v[114:115], v112, off
	v_mul_f32_e32 v112, v119, v181
	v_fmac_f32_e32 v187, v240, v112
	v_cvt_pk_bf16_f32 v112, v187, s0
	v_lshlrev_b32_e32 v116, 16, v117
	v_lshlrev_b32_e32 v117, 16, v112
	global_store_short v[114:115], v112, off offset:2048
	ds_read_b128 v[112:115], v167 offset:64
	s_waitcnt lgkmcnt(0)
	v_mul_f32_e32 v112, v120, v112
	v_fmac_f32_e32 v147, v240, v112
	v_cvt_pk_bf16_f32 v112, v147, s0
	v_add_co_u32_e64 v118, s[0:1], s35, v134
	v_lshlrev_b32_e32 v170, 16, v112
	s_nop 0
	v_addc_co_u32_e64 v119, s[0:1], 0, v135, s[0:1]
	v_add_co_u32_e64 v148, s[0:1], s58, v134
	s_nop 1
	v_addc_co_u32_e64 v149, s[0:1], 0, v135, s[0:1]
	global_store_short v[148:149], v112, off offset:-4096
	v_mul_f32_e32 v112, v121, v113
	v_fmac_f32_e32 v146, v240, v112
	v_cvt_pk_bf16_f32 v112, v146, s0
	v_lshlrev_b32_e32 v171, 16, v112
	global_store_short v[118:119], v112, off offset:2048
	v_mul_f32_e32 v112, v122, v114
	v_fmac_f32_e32 v142, v240, v112
	v_cvt_pk_bf16_f32 v112, v142, s0
	v_lshlrev_b32_e32 v169, 16, v112
	global_store_short v[148:149], v112, off
	v_mul_f32_e32 v112, v123, v115
	v_fmac_f32_e32 v140, v240, v112
	v_cvt_pk_bf16_f32 v112, v140, s0
	v_lshlrev_b32_e32 v168, 16, v112
	global_store_short v[148:149], v112, off offset:2048
	ds_read_b128 v[112:115], v167 offset:96
	s_waitcnt lgkmcnt(0)
	v_mul_f32_e32 v112, v124, v112
	v_fmac_f32_e32 v139, v240, v112
	v_cvt_pk_bf16_f32 v112, v139, s0
	v_add_co_u32_e64 v118, s[0:1], s95, v134
	v_lshlrev_b32_e32 v167, 16, v112
	s_nop 0
	v_addc_co_u32_e64 v119, s[0:1], 0, v135, s[0:1]
	v_add_co_u32_e64 v120, s[0:1], s59, v134
	s_nop 1
	v_addc_co_u32_e64 v121, s[0:1], 0, v135, s[0:1]
	global_store_short v[120:121], v112, off offset:-4096
	v_mul_f32_e32 v112, v125, v113
	v_fmac_f32_e32 v136, v240, v112
	v_cvt_pk_bf16_f32 v112, v136, s0
	v_lshlrev_b32_e32 v124, 16, v112
	global_store_short v[118:119], v112, off offset:2048
	v_mul_f32_e32 v112, v126, v114
	v_fmac_f32_e32 v131, v240, v112
	v_cvt_pk_bf16_f32 v112, v131, s0
	v_lshlrev_b32_e32 v123, 16, v112
	global_store_short v[120:121], v112, off
	v_mul_f32_e32 v112, v127, v115
	v_fmac_f32_e32 v129, v240, v112
	v_cvt_pk_bf16_f32 v112, v129, s0
	v_lshlrev_b32_e32 v122, 16, v112
	global_store_short v[120:121], v112, off offset:2048
	v_mov_b32_e32 v112, v130
	v_mov_b32_e32 v127, v158
	v_ashrrev_i32_e32 v113, 31, v112
	v_lshl_add_u64 v[112:113], v[112:113], 1, s[28:29]
	global_load_ushort v149, v[112:113], off offset:128
	s_waitcnt vmcnt(37)
	global_load_ushort v147, v[112:113], off offset:2176
	s_waitcnt vmcnt(38)
	v_add_co_u32_e64 v114, s[0:1], s96, v112
	s_nop 1
	v_addc_co_u32_e64 v115, s[0:1], 0, v113, s[0:1]
	global_load_ushort v148, v[114:115], off offset:128
	s_waitcnt vmcnt(39)
	global_load_ushort v139, v[114:115], off offset:2176
	s_waitcnt vmcnt(40)
	v_add_co_u32_e64 v114, s[0:1], s94, v112
	s_nop 1
	v_addc_co_u32_e64 v115, s[0:1], 0, v113, s[0:1]
	global_load_ushort v142, v[114:115], off offset:128
	s_waitcnt vmcnt(41)
	global_load_ushort v136, v[114:115], off offset:2176
	s_waitcnt vmcnt(42)
	v_add_co_u32_e64 v114, s[0:1], s57, v112
	s_nop 1
	v_addc_co_u32_e64 v115, s[0:1], 0, v113, s[0:1]
	global_load_ushort v146, v[114:115], off offset:128
	s_waitcnt vmcnt(43)
	global_load_ushort v140, v[114:115], off offset:2176
	s_waitcnt vmcnt(44)
	v_add_co_u32_e64 v114, s[0:1], s35, v112
	s_nop 1
	v_addc_co_u32_e64 v115, s[0:1], 0, v113, s[0:1]
	global_load_ushort v129, v[114:115], off offset:128
	s_waitcnt vmcnt(45)
	global_load_ushort v125, v[114:115], off offset:2176
	s_waitcnt vmcnt(46)
	v_add_co_u32_e64 v114, s[0:1], s58, v112
	s_nop 1
	v_addc_co_u32_e64 v115, s[0:1], 0, v113, s[0:1]
	global_load_ushort v135, v[114:115], off offset:128
	s_waitcnt vmcnt(47)
	global_load_ushort v131, v[114:115], off offset:2176
	s_waitcnt vmcnt(48)
	v_add_co_u32_e64 v114, s[0:1], s95, v112
	s_nop 1
	v_addc_co_u32_e64 v115, s[0:1], 0, v113, s[0:1]
	global_load_ushort v120, v[114:115], off offset:128
	v_add_co_u32_e64 v112, s[0:1], s59, v112
	global_load_ushort v118, v[114:115], off offset:2176
	s_nop 0
	v_addc_co_u32_e64 v113, s[0:1], 0, v113, s[0:1]
	s_waitcnt vmcnt(50)
	s_waitcnt vmcnt(1)
	global_load_ushort v121, v[112:113], off offset:128
	s_waitcnt vmcnt(2)
	global_load_ushort v119, v[112:113], off offset:2176
	s_waitcnt vmcnt(3)
	v_mov_b32_e32 v112, v128
	s_nop 0
	v_ashrrev_i32_e32 v113, 31, v112
	v_lshl_add_u64 v[112:113], v[112:113], 0, s[68:69]
	v_lshl_add_u64 v[114:115], v[112:113], 2, s[36:37]
	v_lshl_add_u32 v114, v127, 2, s38
	v_lshl_add_u32 v127, v127, 4, s39
	ds_read_b128 v[178:181], v127
	ds_read_b128 v[182:185], v127 offset:32
	v_ashrrev_i32_e32 v115, 31, v114
	v_lshlrev_b64 v[114:115], 11, v[114:115]
	v_lshl_add_u64 v[114:115], s[66:67], 0, v[114:115]
	s_waitcnt lgkmcnt(1)
	v_mul_f32_e32 v96, v96, v178
	v_lshl_add_u64 v[112:113], v[112:113], 1, v[114:115]
	v_mul_f32_e32 v99, v99, v181
	s_waitcnt lgkmcnt(0)
	v_mul_f32_e32 v101, v101, v183
	s_waitcnt vmcnt(3)
	s_waitcnt vmcnt(34)
	s_waitcnt vmcnt(51)
	v_lshlrev_b32_e32 v166, 16, v190
	v_fmac_f32_e32 v166, v241, v96
	v_cvt_pk_bf16_f32 v96, v166, s0
	v_lshlrev_b32_e32 v114, 16, v96
	global_store_short v[112:113], v96, off offset:64
	v_mul_f32_e32 v96, v97, v179
	s_waitcnt vmcnt(51)
	v_lshlrev_b32_e32 v165, 16, v165
	v_fmac_f32_e32 v165, v241, v96
	v_cvt_pk_bf16_f32 v96, v165, s0
	v_lshlrev_b32_e32 v97, 16, v96
	global_store_short v[112:113], v96, off offset:2112
	v_mul_f32_e32 v96, v98, v180
	s_waitcnt vmcnt(51)
	v_lshlrev_b32_e32 v164, 16, v164
	v_fmac_f32_e32 v164, v241, v96
	v_cvt_pk_bf16_f32 v98, v164, s0
	v_add_co_u32_e64 v96, s[0:1], s96, v112
	v_mul_f32_e32 v115, v97, v97
	s_nop 0
	v_addc_co_u32_e64 v97, s[0:1], 0, v113, s[0:1]
	s_waitcnt vmcnt(50)
	v_lshlrev_b32_e32 v163, 16, v163
	v_fmac_f32_e32 v163, v241, v99
	s_nop 0
	v_cvt_pk_bf16_f32 v99, v163, s0
	global_store_short v[96:97], v98, off offset:64
	global_store_short v[96:97], v99, off offset:2112
	v_mul_f32_e32 v96, v100, v182
	s_waitcnt vmcnt(51)
	v_lshlrev_b32_e32 v162, 16, v162
	v_fmac_f32_e32 v162, v241, v96
	v_cvt_pk_bf16_f32 v100, v162, s0
	v_add_co_u32_e64 v96, s[0:1], s94, v112
	s_waitcnt vmcnt(50)
	v_lshlrev_b32_e32 v159, 16, v159
	v_fmac_f32_e32 v159, v241, v101
	s_nop 0
	v_addc_co_u32_e64 v97, s[0:1], 0, v113, s[0:1]
	v_lshlrev_b32_e32 v134, 16, v98
	s_nop 0
	v_cvt_pk_bf16_f32 v101, v159, s0
	v_mul_f32_e32 v98, v134, v134
	v_lshlrev_b32_e32 v134, 16, v99
	global_store_short v[96:97], v100, off offset:64
	global_store_short v[96:97], v101, off offset:2112
	v_mul_f32_e32 v96, v102, v184
	v_mul_f32_e32 v99, v134, v134
	v_lshlrev_b32_e32 v134, 16, v100
	s_waitcnt vmcnt(51)
	v_lshlrev_b32_e32 v161, 16, v161
	v_fmac_f32_e32 v161, v241, v96
	v_mul_f32_e32 v100, v134, v134
	v_lshlrev_b32_e32 v134, 16, v101
	v_cvt_pk_bf16_f32 v102, v161, s0
	v_add_co_u32_e64 v96, s[0:1], s57, v112
	v_mul_f32_e32 v101, v134, v134
	s_nop 0
	v_addc_co_u32_e64 v97, s[0:1], 0, v113, s[0:1]
	v_fmac_f32_e32 v101, v116, v116
	v_lshlrev_b32_e32 v116, 16, v102
	global_store_short v[96:97], v102, off offset:64
	v_mul_f32_e32 v102, v103, v185
	s_waitcnt vmcnt(51)
	v_lshlrev_b32_e32 v160, 16, v160
	v_fmac_f32_e32 v160, v241, v102
	v_cvt_pk_bf16_f32 v102, v160, s0
	ds_read_b128 v[160:163], v127 offset:64
	global_store_short v[96:97], v102, off offset:2112
	v_lshlrev_b32_e32 v103, 16, v102
	v_mul_f32_e32 v102, v103, v103
	v_fmac_f32_e32 v102, v117, v117
	s_waitcnt lgkmcnt(0)
	v_mul_f32_e32 v96, v104, v160
	s_waitcnt vmcnt(51)
	v_lshlrev_b32_e32 v150, 16, v150
	v_fmac_f32_e32 v150, v241, v96
	v_cvt_pk_bf16_f32 v103, v150, s0
	v_add_co_u32_e64 v96, s[0:1], s35, v112
	v_lshlrev_b32_e32 v104, 16, v103
	s_nop 0
	v_addc_co_u32_e64 v97, s[0:1], 0, v113, s[0:1]
	global_store_short v[96:97], v103, off offset:64
	v_mul_f32_e32 v103, v105, v161
	s_waitcnt vmcnt(51)
	v_lshlrev_b32_e32 v144, 16, v144
	v_fmac_f32_e32 v144, v241, v103
	v_cvt_pk_bf16_f32 v103, v144, s0
	global_store_short v[96:97], v103, off offset:2112
	v_mul_f32_e32 v96, v106, v162
	s_waitcnt vmcnt(51)
	v_lshlrev_b32_e32 v151, 16, v151
	v_fmac_f32_e32 v151, v241, v96
	v_mul_f32_e32 v117, v104, v104
	v_lshlrev_b32_e32 v104, 16, v103
	v_cvt_pk_bf16_f32 v103, v151, s0
	v_add_co_u32_e64 v96, s[0:1], s58, v112
	v_mul_f32_e32 v105, v104, v104
	s_nop 0
	v_addc_co_u32_e64 v97, s[0:1], 0, v113, s[0:1]
	v_lshlrev_b32_e32 v104, 16, v103
	global_store_short v[96:97], v103, off offset:64
	v_mul_f32_e32 v103, v107, v163
	ds_read_b128 v[160:163], v127 offset:96
	s_waitcnt vmcnt(51)
	v_lshlrev_b32_e32 v145, 16, v145
	v_fmac_f32_e32 v145, v241, v103
	v_cvt_pk_bf16_f32 v103, v145, s0
	global_store_short v[96:97], v103, off offset:2112
	v_lshlrev_b32_e32 v106, 16, v103
	s_waitcnt lgkmcnt(0)
	v_mul_f32_e32 v96, v108, v160
	s_waitcnt vmcnt(51)
	v_lshlrev_b32_e32 v143, 16, v143
	v_fmac_f32_e32 v143, v241, v96
	v_mul_f32_e32 v103, v106, v106
	v_cvt_pk_bf16_f32 v106, v143, s0
	v_add_co_u32_e64 v96, s[0:1], s95, v112
	v_lshlrev_b32_e32 v107, 16, v106
	s_nop 0
	v_addc_co_u32_e64 v97, s[0:1], 0, v113, s[0:1]
	global_store_short v[96:97], v106, off offset:64
	v_mul_f32_e32 v106, v107, v107
	v_mul_f32_e32 v107, v109, v161
	s_waitcnt vmcnt(50)
	v_lshlrev_b32_e32 v137, 16, v137
	v_fmac_f32_e32 v137, v241, v107
	v_cvt_pk_bf16_f32 v107, v137, s0
	global_store_short v[96:97], v107, off offset:2112
	v_mul_f32_e32 v96, v110, v162
	v_lshlrev_b32_e32 v108, 16, v107
	s_waitcnt vmcnt(52)
	v_lshlrev_b32_e32 v141, 16, v141
	v_fmac_f32_e32 v141, v241, v96
	v_mul_f32_e32 v107, v108, v108
	v_cvt_pk_bf16_f32 v108, v141, s0
	v_add_co_u32_e64 v96, s[0:1], s59, v112
	v_lshlrev_b32_e32 v109, 16, v108
	s_nop 0
	v_addc_co_u32_e64 v97, s[0:1], 0, v113, s[0:1]
	global_store_short v[96:97], v108, off offset:64
	v_mul_f32_e32 v108, v109, v109
	v_mul_f32_e32 v109, v111, v163
	s_waitcnt vmcnt(51)
	v_lshlrev_b32_e32 v138, 16, v138
	v_fmac_f32_e32 v138, v241, v109
	v_cvt_pk_bf16_f32 v109, v138, s0
	global_store_short v[96:97], v109, off offset:2112
	v_mov_b32_e32 v96, v130
	v_lshlrev_b32_e32 v110, 16, v109
	v_ashrrev_i32_e32 v97, 31, v96
	v_lshl_add_u64 v[96:97], v[96:97], 1, s[28:29]
	v_mul_f32_e32 v109, v110, v110
	global_load_ushort v190, v[96:97], off offset:192
	v_fmac_f32_e32 v108, v123, v123
	v_fmac_f32_e32 v109, v122, v122
	v_fmac_f32_e32 v107, v124, v124
	v_mov_b32_e32 v159, v158
	v_fmac_f32_e32 v106, v167, v167
	v_fmac_f32_e32 v115, v176, v176
	v_fmac_f32_e32 v99, v174, v174
	v_fmac_f32_e32 v100, v173, v173
	v_mul_f32_e32 v116, v116, v116
	v_fmac_f32_e32 v116, v172, v172
	v_fmac_f32_e32 v105, v171, v171
	v_fmac_f32_e32 v103, v168, v168
	v_mul_f32_e32 v104, v104, v104
	v_fmac_f32_e32 v104, v169, v169
	v_fmac_f32_e32 v117, v170, v170
	s_or_b32 s28, s38, 32
	s_ashr_i32 s29, s28, 31
	v_mul_f32_e32 v114, v114, v114
	v_fmac_f32_e32 v114, v177, v177
	v_fmac_f32_e32 v98, v175, v175
	s_waitcnt vmcnt(17)
	global_load_ushort v122, v[96:97], off offset:2240
	s_waitcnt vmcnt(18)
	v_add_co_u32_e64 v110, s[0:1], s96, v96
	s_nop 1
	v_addc_co_u32_e64 v111, s[0:1], 0, v97, s[0:1]
	global_load_ushort v126, v[110:111], off offset:192
	s_waitcnt vmcnt(19)
	global_load_ushort v124, v[110:111], off offset:2240
	s_waitcnt vmcnt(20)
	v_add_co_u32_e64 v110, s[0:1], s94, v96
	s_nop 1
	v_addc_co_u32_e64 v111, s[0:1], 0, v97, s[0:1]
	global_load_ushort v134, v[110:111], off offset:192
	s_waitcnt vmcnt(21)
	global_load_ushort v127, v[110:111], off offset:2240
	s_waitcnt vmcnt(22)
	v_add_co_u32_e64 v110, s[0:1], s57, v96
	s_nop 1
	v_addc_co_u32_e64 v111, s[0:1], 0, v97, s[0:1]
	global_load_ushort v145, v[110:111], off offset:192
	s_waitcnt vmcnt(23)
	global_load_ushort v143, v[110:111], off offset:2240
	s_waitcnt vmcnt(24)
	v_add_co_u32_e64 v110, s[0:1], s35, v96
	s_nop 1
	v_addc_co_u32_e64 v111, s[0:1], 0, v97, s[0:1]
	global_load_ushort v138, v[110:111], off offset:192
	s_waitcnt vmcnt(25)
	global_load_ushort v137, v[110:111], off offset:2240
	s_waitcnt vmcnt(26)
	v_add_co_u32_e64 v110, s[0:1], s58, v96
	s_nop 1
	v_addc_co_u32_e64 v111, s[0:1], 0, v97, s[0:1]
	global_load_ushort v144, v[110:111], off offset:192
	s_waitcnt vmcnt(27)
	global_load_ushort v141, v[110:111], off offset:2240
	v_add_co_u32_e64 v112, s[0:1], s95, v96
	s_waitcnt vmcnt(28)
	v_addc_co_u32_e64 v113, s[0:1], 0, v97, s[0:1]
	global_load_ushort v111, v[112:113], off offset:192
	v_add_co_u32_e64 v96, s[0:1], s59, v96
	s_waitcnt vmcnt(29)
	v_addc_co_u32_e64 v97, s[0:1], 0, v97, s[0:1]
	global_load_ushort v110, v[112:113], off offset:2240
	s_waitcnt vmcnt(30)
	global_load_ushort v113, v[96:97], off offset:192
	s_waitcnt vmcnt(31)
	global_load_ushort v112, v[96:97], off offset:2240
	s_waitcnt vmcnt(32)
	v_mov_b32_e32 v96, v128
	s_nop 0
	v_ashrrev_i32_e32 v97, 31, v96
	v_lshl_add_u64 v[96:97], v[96:97], 0, s[68:69]
	v_lshl_add_u64 v[150:151], v[96:97], 2, s[36:37]
	v_lshl_add_u32 v160, v159, 2, s38
	v_ashrrev_i32_e32 v161, 31, v160
	v_lshlrev_b64 v[160:161], 11, v[160:161]
	v_lshl_add_u64 v[160:161], s[66:67], 0, v[160:161]
	v_lshl_add_u32 v151, v159, 4, s39
	v_lshl_add_u64 v[96:97], v[96:97], 1, v[160:161]
	ds_read_b128 v[160:163], v151
	ds_read_b128 v[164:167], v151 offset:32
	s_waitcnt lgkmcnt(1)
	v_mul_f32_e32 v80, v80, v160
	s_waitcnt vmcnt(32)
	s_waitcnt vmcnt(47)
	v_lshlrev_b32_e32 v149, 16, v149
	v_fmac_f32_e32 v149, v242, v80
	v_cvt_pk_bf16_f32 v80, v149, s0
	v_lshlrev_b32_e32 v149, 16, v80
	global_store_short v[96:97], v80, off offset:128
	v_mul_f32_e32 v80, v81, v161
	s_waitcnt vmcnt(47)
	v_lshlrev_b32_e32 v147, 16, v147
	v_fmac_f32_e32 v147, v242, v80
	v_cvt_pk_bf16_f32 v80, v147, s0
	v_lshlrev_b32_e32 v81, 16, v80
	global_store_short v[96:97], v80, off offset:2176
	v_mul_f32_e32 v80, v82, v162
	s_waitcnt vmcnt(47)
	v_lshlrev_b32_e32 v148, 16, v148
	v_fmac_f32_e32 v148, v242, v80
	v_cvt_pk_bf16_f32 v82, v148, s0
	v_add_co_u32_e64 v80, s[0:1], s96, v96
	v_fmac_f32_e32 v115, v81, v81
	s_nop 0
	v_addc_co_u32_e64 v81, s[0:1], 0, v97, s[0:1]
	v_lshlrev_b32_e32 v147, 16, v82
	global_store_short v[80:81], v82, off offset:128
	v_mul_f32_e32 v82, v83, v163
	s_waitcnt vmcnt(47)
	v_lshlrev_b32_e32 v139, 16, v139
	v_fmac_f32_e32 v139, v242, v82
	v_cvt_pk_bf16_f32 v82, v139, s0
	global_store_short v[80:81], v82, off offset:2176
	s_waitcnt lgkmcnt(0)
	v_mul_f32_e32 v80, v84, v164
	s_waitcnt vmcnt(47)
	v_lshlrev_b32_e32 v142, 16, v142
	v_fmac_f32_e32 v142, v242, v80
	v_lshlrev_b32_e32 v83, 16, v82
	v_cvt_pk_bf16_f32 v82, v142, s0
	v_add_co_u32_e64 v80, s[0:1], s94, v96
	v_fmac_f32_e32 v99, v83, v83
	s_nop 0
	v_addc_co_u32_e64 v81, s[0:1], 0, v97, s[0:1]
	v_lshlrev_b32_e32 v83, 16, v82
	global_store_short v[80:81], v82, off offset:128
	v_mul_f32_e32 v82, v85, v165
	s_waitcnt vmcnt(47)
	v_lshlrev_b32_e32 v136, 16, v136
	v_fmac_f32_e32 v136, v242, v82
	v_cvt_pk_bf16_f32 v82, v136, s0
	global_store_short v[80:81], v82, off offset:2176
	v_mul_f32_e32 v80, v86, v166
	s_waitcnt vmcnt(47)
	v_lshlrev_b32_e32 v146, 16, v146
	v_fmac_f32_e32 v146, v242, v80
	v_fmac_f32_e32 v100, v83, v83
	v_lshlrev_b32_e32 v83, 16, v82
	v_cvt_pk_bf16_f32 v82, v146, s0
	v_add_co_u32_e64 v80, s[0:1], s57, v96
	v_fmac_f32_e32 v101, v83, v83
	s_nop 0
	v_addc_co_u32_e64 v81, s[0:1], 0, v97, s[0:1]
	v_lshlrev_b32_e32 v83, 16, v82
	global_store_short v[80:81], v82, off offset:128
	v_mul_f32_e32 v82, v87, v167
	s_waitcnt vmcnt(47)
	v_lshlrev_b32_e32 v140, 16, v140
	v_fmac_f32_e32 v140, v242, v82
	v_cvt_pk_bf16_f32 v82, v140, s0
	v_fmac_f32_e32 v116, v83, v83
	v_lshlrev_b32_e32 v83, 16, v82
	global_store_short v[80:81], v82, off offset:2176
	v_fmac_f32_e32 v102, v83, v83
	ds_read_b128 v[80:83], v151 offset:64
	v_fmac_f32_e32 v114, v149, v149
	v_fmac_f32_e32 v98, v147, v147
	s_waitcnt lgkmcnt(0)
	v_mul_f32_e32 v80, v88, v80
	s_waitcnt vmcnt(47)
	v_lshlrev_b32_e32 v129, 16, v129
	v_fmac_f32_e32 v129, v242, v80
	v_cvt_pk_bf16_f32 v80, v129, s0
	v_add_co_u32_e64 v84, s[0:1], s35, v96
	v_lshlrev_b32_e32 v86, 16, v80
	s_nop 0
	v_addc_co_u32_e64 v85, s[0:1], 0, v97, s[0:1]
	global_store_short v[84:85], v80, off offset:128
	v_mul_f32_e32 v80, v89, v81
	s_waitcnt vmcnt(47)
	v_lshlrev_b32_e32 v125, 16, v125
	v_fmac_f32_e32 v125, v242, v80
	v_cvt_pk_bf16_f32 v80, v125, s0
	v_lshlrev_b32_e32 v81, 16, v80
	global_store_short v[84:85], v80, off offset:2176
	v_mul_f32_e32 v80, v90, v82
	s_waitcnt vmcnt(47)
	v_lshlrev_b32_e32 v135, 16, v135
	v_fmac_f32_e32 v135, v242, v80
	v_cvt_pk_bf16_f32 v82, v135, s0
	v_add_co_u32_e64 v80, s[0:1], s58, v96
	v_fmac_f32_e32 v105, v81, v81
	s_nop 0
	v_addc_co_u32_e64 v81, s[0:1], 0, v97, s[0:1]
	v_lshlrev_b32_e32 v84, 16, v82
	global_store_short v[80:81], v82, off offset:128
	v_mul_f32_e32 v82, v91, v83
	s_waitcnt vmcnt(47)
	v_lshlrev_b32_e32 v131, 16, v131
	v_fmac_f32_e32 v131, v242, v82
	v_cvt_pk_bf16_f32 v82, v131, s0
	v_lshlrev_b32_e32 v83, 16, v82
	global_store_short v[80:81], v82, off offset:2176
	v_fmac_f32_e32 v103, v83, v83
	ds_read_b128 v[80:83], v151 offset:96
	v_fmac_f32_e32 v104, v84, v84
	v_fmac_f32_e32 v117, v86, v86
	v_mov_b32_e32 v125, v158
	s_waitcnt lgkmcnt(0)
	v_mul_f32_e32 v80, v92, v80
	s_waitcnt vmcnt(47)
	v_lshlrev_b32_e32 v120, 16, v120
	v_fmac_f32_e32 v120, v242, v80
	v_cvt_pk_bf16_f32 v80, v120, s0
	v_add_co_u32_e64 v84, s[0:1], s95, v96
	v_lshlrev_b32_e32 v86, 16, v80
	s_nop 0
	v_addc_co_u32_e64 v85, s[0:1], 0, v97, s[0:1]
	global_store_short v[84:85], v80, off offset:128
	v_mul_f32_e32 v80, v93, v81
	s_waitcnt vmcnt(47)
	v_lshlrev_b32_e32 v118, 16, v118
	v_fmac_f32_e32 v118, v242, v80
	v_cvt_pk_bf16_f32 v80, v118, s0
	v_lshlrev_b32_e32 v81, 16, v80
	global_store_short v[84:85], v80, off offset:2176
	v_mul_f32_e32 v80, v94, v82
	s_waitcnt vmcnt(47)
	v_lshlrev_b32_e32 v121, 16, v121
	v_fmac_f32_e32 v121, v242, v80
	v_cvt_pk_bf16_f32 v82, v121, s0
	v_add_co_u32_e64 v80, s[0:1], s59, v96
	v_fmac_f32_e32 v107, v81, v81
	s_nop 0
	v_addc_co_u32_e64 v81, s[0:1], 0, v97, s[0:1]
	v_lshlrev_b32_e32 v84, 16, v82
	global_store_short v[80:81], v82, off offset:128
	v_mul_f32_e32 v82, v95, v83
	s_waitcnt vmcnt(47)
	v_lshlrev_b32_e32 v119, 16, v119
	v_fmac_f32_e32 v119, v242, v82
	v_cvt_pk_bf16_f32 v82, v119, s0
	s_lshl_b64 s[0:1], s[28:29], 11
	global_store_short v[80:81], v82, off offset:2176
	v_mov_b32_e32 v80, v130
	s_add_u32 s50, s48, s0
	s_addc_u32 s51, s49, s1
	v_ashrrev_i32_e32 v81, 31, v80
	v_lshl_add_u64 v[80:81], v[80:81], 1, s[50:51]
	v_fmac_f32_e32 v106, v86, v86
	v_add_co_u32_e64 v86, s[0:1], s96, v80
	v_lshlrev_b32_e32 v83, 16, v82
	s_nop 0
	v_addc_co_u32_e64 v87, s[0:1], 0, v81, s[0:1]
	v_add_co_u32_e64 v88, s[0:1], s94, v80
	v_fmac_f32_e32 v109, v83, v83
	s_nop 0
	v_addc_co_u32_e64 v89, s[0:1], 0, v81, s[0:1]
	v_add_co_u32_e64 v90, s[0:1], s57, v80
	global_load_ushort v82, v[80:81], off
	global_load_ushort v83, v[80:81], off offset:2048
	v_addc_co_u32_e64 v91, s[0:1], 0, v81, s[0:1]
	v_add_co_u32_e64 v92, s[0:1], s35, v80
	v_fmac_f32_e32 v108, v84, v84
	s_nop 0
	v_addc_co_u32_e64 v93, s[0:1], 0, v81, s[0:1]
	v_add_co_u32_e64 v94, s[0:1], s58, v80
	global_load_ushort v84, v[86:87], off
	global_load_ushort v85, v[86:87], off offset:2048
	v_addc_co_u32_e64 v95, s[0:1], 0, v81, s[0:1]
	v_add_co_u32_e64 v96, s[0:1], s95, v80
	global_load_ushort v86, v[90:91], off offset:-4096
	global_load_ushort v87, v[88:89], off offset:2048
	s_nop 0
	global_load_ushort v88, v[90:91], off
	global_load_ushort v89, v[90:91], off offset:2048
	v_addc_co_u32_e64 v97, s[0:1], 0, v81, s[0:1]
	v_add_co_u32_e64 v80, s[0:1], s59, v80
	global_load_ushort v90, v[94:95], off offset:-4096
	global_load_ushort v91, v[92:93], off offset:2048
	s_nop 0
	global_load_ushort v92, v[94:95], off
	global_load_ushort v93, v[94:95], off offset:2048
	v_addc_co_u32_e64 v81, s[0:1], 0, v81, s[0:1]
	global_load_ushort v94, v[80:81], off offset:-4096
	global_load_ushort v95, v[96:97], off offset:2048
	s_nop 0
	global_load_ushort v96, v[80:81], off
	global_load_ushort v97, v[80:81], off offset:2048
	v_mov_b32_e32 v80, v128
	s_nop 0
	v_ashrrev_i32_e32 v81, 31, v80
	v_lshl_add_u64 v[80:81], v[80:81], 0, s[68:69]
	v_lshl_add_u64 v[118:119], v[80:81], 2, s[36:37]
	v_lshl_add_u32 v119, v125, 4, s39
	ds_read_b128 v[146:149], v119
	ds_read_b128 v[160:163], v119 offset:32
	v_lshl_add_u32 v120, v125, 2, s38
	v_ashrrev_i32_e32 v121, 31, v120
	v_lshlrev_b64 v[120:121], 11, v[120:121]
	s_waitcnt lgkmcnt(1)
	v_mul_f32_e32 v64, v64, v146
	v_lshl_add_u64 v[120:121], s[66:67], 0, v[120:121]
	v_lshl_add_u64 v[80:81], v[80:81], 1, v[120:121]
	s_waitcnt vmcnt(0)
	s_waitcnt vmcnt(47)
	v_lshlrev_b32_e32 v123, 16, v190
	v_fmac_f32_e32 v123, v243, v64
	v_mul_f32_e32 v64, v65, v147
	s_waitcnt vmcnt(46)
	v_lshlrev_b32_e32 v122, 16, v122
	v_fmac_f32_e32 v122, v243, v64
	v_mul_f32_e32 v64, v66, v148
	s_waitcnt vmcnt(45)
	v_lshlrev_b32_e32 v126, 16, v126
	v_fmac_f32_e32 v126, v243, v64
	v_cvt_pk_bf16_f32 v120, v123, s0
	v_cvt_pk_bf16_f32 v121, v122, s0
	v_cvt_pk_bf16_f32 v122, v126, s0
	v_add_co_u32_e64 v64, s[0:1], s96, v80
	v_mul_f32_e32 v66, v67, v149
	s_nop 0
	v_addc_co_u32_e64 v65, s[0:1], 0, v81, s[0:1]
	s_waitcnt vmcnt(44)
	v_lshlrev_b32_e32 v124, 16, v124
	v_fmac_f32_e32 v124, v243, v66
	s_nop 0
	v_cvt_pk_bf16_f32 v123, v124, s0
	global_store_short v[64:65], v122, off offset:192
	global_store_short v[64:65], v123, off offset:2240
	s_waitcnt lgkmcnt(0)
	v_mul_f32_e32 v64, v68, v160
	s_waitcnt vmcnt(45)
	v_lshlrev_b32_e32 v134, 16, v134
	v_fmac_f32_e32 v134, v243, v64
	v_cvt_pk_bf16_f32 v124, v134, s0
	v_add_co_u32_e64 v64, s[0:1], s94, v80
	v_mul_f32_e32 v66, v69, v161
	s_nop 0
	v_addc_co_u32_e64 v65, s[0:1], 0, v81, s[0:1]
	s_waitcnt vmcnt(44)
	v_lshlrev_b32_e32 v127, 16, v127
	v_fmac_f32_e32 v127, v243, v66
	s_nop 0
	v_cvt_pk_bf16_f32 v125, v127, s0
	global_store_short v[64:65], v124, off offset:192
	global_store_short v[64:65], v125, off offset:2240
	v_mul_f32_e32 v64, v70, v162
	s_waitcnt vmcnt(45)
	v_lshlrev_b32_e32 v145, 16, v145
	v_fmac_f32_e32 v145, v243, v64
	v_cvt_pk_bf16_f32 v70, v145, s0
	v_add_co_u32_e64 v64, s[0:1], s57, v80
	v_mul_f32_e32 v66, v71, v163
	s_nop 0
	v_addc_co_u32_e64 v65, s[0:1], 0, v81, s[0:1]
	s_waitcnt vmcnt(44)
	v_lshlrev_b32_e32 v143, 16, v143
	v_fmac_f32_e32 v143, v243, v66
	s_nop 0
	v_cvt_pk_bf16_f32 v71, v143, s0
	global_store_short v[64:65], v70, off offset:192
	global_store_short v[64:65], v71, off offset:2240
	ds_read_b128 v[64:67], v119 offset:64
	global_store_short v[80:81], v120, off offset:192
	global_store_short v[80:81], v121, off offset:2240
	s_waitcnt lgkmcnt(0)
	v_mul_f32_e32 v64, v72, v64
	s_waitcnt vmcnt(47)
	v_lshlrev_b32_e32 v138, 16, v138
	v_fmac_f32_e32 v138, v243, v64
	v_mul_f32_e32 v64, v73, v65
	v_cvt_pk_bf16_f32 v72, v138, s0
	v_add_co_u32_e64 v68, s[0:1], s35, v80
	s_waitcnt vmcnt(46)
	v_lshlrev_b32_e32 v137, 16, v137
	v_fmac_f32_e32 v137, v243, v64
	v_mul_f32_e32 v64, v74, v66
	v_addc_co_u32_e64 v69, s[0:1], 0, v81, s[0:1]
	s_waitcnt vmcnt(45)
	v_lshlrev_b32_e32 v144, 16, v144
	v_fmac_f32_e32 v144, v243, v64
	s_nop 0
	v_cvt_pk_bf16_f32 v73, v137, s0
	v_cvt_pk_bf16_f32 v74, v144, s0
	v_add_co_u32_e64 v64, s[0:1], s58, v80
	v_mul_f32_e32 v66, v75, v67
	s_nop 0
	v_addc_co_u32_e64 v65, s[0:1], 0, v81, s[0:1]
	s_waitcnt vmcnt(44)
	v_lshlrev_b32_e32 v141, 16, v141
	v_fmac_f32_e32 v141, v243, v66
	s_nop 0
	v_cvt_pk_bf16_f32 v75, v141, s0
	global_store_short v[64:65], v74, off offset:192
	global_store_short v[64:65], v75, off offset:2240
	ds_read_b128 v[64:67], v119 offset:96
	global_store_short v[68:69], v72, off offset:192
	global_store_short v[68:69], v73, off offset:2240
	s_waitcnt lgkmcnt(0)
	v_mul_f32_e32 v64, v76, v64
	s_waitcnt vmcnt(47)
	v_lshlrev_b32_e32 v111, 16, v111
	v_fmac_f32_e32 v111, v243, v64
	v_mul_f32_e32 v64, v77, v65
	v_cvt_pk_bf16_f32 v76, v111, s0
	v_add_co_u32_e64 v68, s[0:1], s95, v80
	s_waitcnt vmcnt(46)
	v_lshlrev_b32_e32 v110, 16, v110
	v_fmac_f32_e32 v110, v243, v64
	v_mul_f32_e32 v64, v78, v66
	v_addc_co_u32_e64 v69, s[0:1], 0, v81, s[0:1]
	s_waitcnt vmcnt(45)
	v_lshlrev_b32_e32 v113, 16, v113
	v_fmac_f32_e32 v113, v243, v64
	s_nop 0
	v_cvt_pk_bf16_f32 v77, v110, s0
	v_cvt_pk_bf16_f32 v66, v113, s0
	v_add_co_u32_e64 v64, s[0:1], s59, v80
	v_mul_f32_e32 v67, v79, v67
	s_nop 0
	v_addc_co_u32_e64 v65, s[0:1], 0, v81, s[0:1]
	s_waitcnt vmcnt(44)
	v_lshlrev_b32_e32 v112, 16, v112
	v_fmac_f32_e32 v112, v243, v67
	s_nop 0
	v_cvt_pk_bf16_f32 v67, v112, s0
	global_store_short v[64:65], v66, off offset:192
	global_store_short v[64:65], v67, off offset:2240
	v_lshlrev_b32_e32 v64, 16, v67
	v_fmac_f32_e32 v109, v64, v64
	v_lshlrev_b32_e32 v64, 16, v66
	v_fmac_f32_e32 v108, v64, v64
	v_lshlrev_b32_e32 v64, 16, v77
	v_fmac_f32_e32 v107, v64, v64
	v_lshlrev_b32_e32 v64, 16, v76
	v_fmac_f32_e32 v106, v64, v64
	v_lshlrev_b32_e32 v64, 16, v75
	v_fmac_f32_e32 v103, v64, v64
	v_lshlrev_b32_e32 v64, 16, v74
	v_fmac_f32_e32 v104, v64, v64
	v_lshlrev_b32_e32 v64, 16, v73
	v_fmac_f32_e32 v105, v64, v64
	v_lshlrev_b32_e32 v64, 16, v72
	v_fmac_f32_e32 v117, v64, v64
	v_lshlrev_b32_e32 v64, 16, v71
	v_fmac_f32_e32 v102, v64, v64
	v_lshlrev_b32_e32 v64, 16, v70
	v_fmac_f32_e32 v116, v64, v64
	v_lshlrev_b32_e32 v64, 16, v125
	v_fmac_f32_e32 v101, v64, v64
	v_lshlrev_b32_e32 v64, 16, v124
	v_fmac_f32_e32 v100, v64, v64
	v_lshlrev_b32_e32 v64, 16, v123
	v_fmac_f32_e32 v99, v64, v64
	v_lshlrev_b32_e32 v64, 16, v122
	v_fmac_f32_e32 v98, v64, v64
	v_lshlrev_b32_e32 v64, 16, v121
	v_fmac_f32_e32 v115, v64, v64
	v_lshlrev_b32_e32 v64, 16, v120
	v_fmac_f32_e32 v114, v64, v64
	v_cndmask_b32_e64 v65, v114, v117, s[46:47]
	ds_bpermute_b32 v65, v157, v65
	v_cndmask_b32_e64 v66, v115, v105, s[46:47]
	ds_bpermute_b32 v66, v157, v66
	v_cndmask_b32_e64 v67, v98, v104, s[46:47]
	global_store_short v[68:69], v76, off offset:192
	global_store_short v[68:69], v77, off offset:2240
	ds_bpermute_b32 v67, v157, v67
	v_cndmask_b32_e64 v68, v99, v103, s[46:47]
	ds_bpermute_b32 v68, v157, v68
	v_cndmask_b32_e64 v69, v100, v106, s[46:47]
	v_cndmask_b32_e64 v64, v117, v114, s[46:47]
	ds_bpermute_b32 v69, v157, v69
	v_cndmask_b32_e64 v70, v101, v107, s[46:47]
	s_waitcnt lgkmcnt(4)
	v_add_f32_e32 v64, v64, v65
	v_cndmask_b32_e64 v65, v105, v115, s[46:47]
	ds_bpermute_b32 v70, v157, v70
	v_cndmask_b32_e64 v71, v116, v108, s[46:47]
	s_waitcnt lgkmcnt(4)
	v_add_f32_e32 v65, v65, v66
	v_cndmask_b32_e64 v66, v104, v98, s[46:47]
	ds_bpermute_b32 v71, v157, v71
	v_cndmask_b32_e64 v72, v102, v109, s[46:47]
	s_waitcnt lgkmcnt(4)
	v_add_f32_e32 v66, v66, v67
	v_cndmask_b32_e64 v67, v103, v99, s[46:47]
	ds_bpermute_b32 v72, v157, v72
	s_waitcnt lgkmcnt(4)
	v_add_f32_e32 v67, v67, v68
	v_cndmask_b32_e64 v68, v106, v100, s[46:47]
	s_waitcnt lgkmcnt(3)
	v_add_f32_e32 v68, v68, v69
	v_cndmask_b32_e64 v69, v107, v101, s[46:47]
	s_waitcnt lgkmcnt(2)
	v_add_f32_e32 v69, v69, v70
	v_cndmask_b32_e64 v70, v108, v116, s[46:47]
	s_waitcnt lgkmcnt(1)
	v_add_f32_e32 v70, v70, v71
	v_cndmask_b32_e64 v71, v109, v102, s[46:47]
	s_waitcnt lgkmcnt(0)
	v_add_f32_e32 v71, v71, v72
	v_cndmask_b32_e64 v72, v68, v64, s[44:45]
	v_cndmask_b32_e64 v64, v64, v68, s[44:45]
	v_cndmask_b32_e64 v68, v69, v65, s[44:45]
	v_cndmask_b32_e64 v65, v65, v69, s[44:45]
	ds_bpermute_b32 v65, v156, v65
	ds_bpermute_b32 v64, v156, v64
	s_waitcnt lgkmcnt(1)
	v_add_f32_e32 v65, v68, v65
	v_cndmask_b32_e64 v68, v70, v66, s[44:45]
	v_cndmask_b32_e64 v66, v66, v70, s[44:45]
	ds_bpermute_b32 v66, v156, v66
	s_waitcnt lgkmcnt(1)
	v_add_f32_e32 v64, v72, v64
	s_waitcnt lgkmcnt(0)
	v_add_f32_e32 v66, v68, v66
	v_cndmask_b32_e64 v68, v71, v67, s[44:45]
	v_cndmask_b32_e64 v67, v67, v71, s[44:45]
	ds_bpermute_b32 v67, v156, v67
	s_waitcnt lgkmcnt(0)
	v_add_f32_e32 v67, v68, v67
	v_cndmask_b32_e64 v68, v66, v64, s[42:43]
	v_cndmask_b32_e64 v64, v64, v66, s[42:43]
	v_cndmask_b32_e64 v66, v67, v65, s[42:43]
	v_cndmask_b32_e64 v65, v65, v67, s[42:43]
	ds_bpermute_b32 v64, v155, v64
	ds_bpermute_b32 v65, v155, v65
	s_waitcnt lgkmcnt(1)
	v_add_f32_e32 v64, v68, v64
	s_waitcnt lgkmcnt(0)
	v_add_f32_e32 v65, v66, v65
	v_cndmask_b32_e64 v66, v65, v64, s[40:41]
	v_cndmask_b32_e64 v64, v64, v65, s[40:41]
	ds_bpermute_b32 v64, v154, v64
	s_waitcnt lgkmcnt(0)
	v_add_f32_e32 v64, v66, v64
	ds_bpermute_b32 v65, v153, v64
	s_and_saveexec_b64 s[0:1], vcc
	s_cbranch_execz .LBB0_426
	v_lshlrev_b64 v[66:67], 6, v[132:133]
	v_lshl_add_u64 v[66:67], s[26:27], 0, v[66:67]
	s_waitcnt lgkmcnt(0)
	v_add_f32_e32 v64, v64, v65
	global_store_dword v[66:67], v64, off
.LBB0_426:
	s_or_b64 exec, exec, s[0:1]
	v_mov_b32_e32 v64, v130
	v_lshlrev_b32_e32 v108, 16, v85
	s_waitcnt lgkmcnt(0)
	v_ashrrev_i32_e32 v65, 31, v64
	v_lshl_add_u64 v[64:65], v[64:65], 1, s[50:51]
	global_load_ushort v85, v[64:65], off offset:64
	v_lshlrev_b32_e32 v103, 16, v84
	v_lshlrev_b32_e32 v98, 16, v82
	v_lshlrev_b32_e32 v99, 16, v83
	v_lshlrev_b32_e32 v102, 16, v87
	v_lshlrev_b32_e32 v101, 16, v88
	v_lshlrev_b32_e32 v100, 16, v89
	v_lshlrev_b32_e32 v89, 16, v90
	v_lshlrev_b32_e32 v88, 16, v91
	v_lshlrev_b32_e32 v87, 16, v92
	v_mov_b32_e32 v92, v158
	v_lshlrev_b32_e32 v109, 16, v86
	v_lshlrev_b32_e32 v86, 16, v93
	v_lshlrev_b32_e32 v68, 16, v97
	v_lshlrev_b32_e32 v71, 16, v95
	v_lshlrev_b32_e32 v73, 16, v94
	v_lshlrev_b32_e32 v70, 16, v96
	s_waitcnt vmcnt(18)
	global_load_ushort v84, v[64:65], off offset:2112
	s_waitcnt vmcnt(19)
	v_add_co_u32_e64 v66, s[0:1], s96, v64
	s_nop 1
	v_addc_co_u32_e64 v67, s[0:1], 0, v65, s[0:1]
	global_load_ushort v83, v[66:67], off offset:64
	s_waitcnt vmcnt(20)
	global_load_ushort v82, v[66:67], off offset:2112
	s_waitcnt vmcnt(21)
	v_add_co_u32_e64 v66, s[0:1], s94, v64
	s_nop 1
	v_addc_co_u32_e64 v67, s[0:1], 0, v65, s[0:1]
	global_load_ushort v81, v[66:67], off offset:64
	s_waitcnt vmcnt(22)
	global_load_ushort v78, v[66:67], off offset:2112
	s_waitcnt vmcnt(23)
	v_add_co_u32_e64 v66, s[0:1], s57, v64
	s_nop 1
	v_addc_co_u32_e64 v67, s[0:1], 0, v65, s[0:1]
	global_load_ushort v80, v[66:67], off offset:64
	s_waitcnt vmcnt(24)
	global_load_ushort v79, v[66:67], off offset:2112
	s_waitcnt vmcnt(25)
	v_add_co_u32_e64 v66, s[0:1], s35, v64
	s_nop 1
	v_addc_co_u32_e64 v67, s[0:1], 0, v65, s[0:1]
	global_load_ushort v76, v[66:67], off offset:64
	s_waitcnt vmcnt(26)
	global_load_ushort v74, v[66:67], off offset:2112
	s_waitcnt vmcnt(27)
	v_add_co_u32_e64 v66, s[0:1], s58, v64
	s_nop 1
	v_addc_co_u32_e64 v67, s[0:1], 0, v65, s[0:1]
	global_load_ushort v77, v[66:67], off offset:64
	s_waitcnt vmcnt(28)
	global_load_ushort v75, v[66:67], off offset:2112
	s_waitcnt vmcnt(29)
	v_add_co_u32_e64 v66, s[0:1], s95, v64
	s_nop 1
	v_addc_co_u32_e64 v67, s[0:1], 0, v65, s[0:1]
	v_add_co_u32_e64 v64, s[0:1], s59, v64
	global_load_ushort v72, v[66:67], off offset:64
	s_nop 0
	v_addc_co_u32_e64 v65, s[0:1], 0, v65, s[0:1]
	global_load_ushort v66, v[66:67], off offset:2112
	s_waitcnt vmcnt(31)
	global_load_ushort v69, v[64:65], off offset:64
	s_waitcnt vmcnt(32)
	global_load_ushort v189, v[64:65], off offset:2112
	s_waitcnt vmcnt(33)
	s_waitcnt vmcnt(33)
	v_mov_b32_e32 v64, v128
	s_nop 0
	v_add_u32_e32 v64, s68, v64
	v_ashrrev_i32_e32 v65, 31, v64
	v_lshl_add_u64 v[90:91], v[64:65], 2, s[36:37]
	v_lshl_add_u32 v90, v92, 2, s28
	v_ashrrev_i32_e32 v91, 31, v90
	v_lshlrev_b64 v[90:91], 11, v[90:91]
	v_lshl_add_u64 v[90:91], s[66:67], 0, v[90:91]
	v_lshl_add_u32 v111, v92, 4, s39
	v_lshl_add_u64 v[64:65], v[64:65], 1, v[90:91]
	ds_read_b128 v[90:93], v111 offset:128
	ds_read_b128 v[104:107], v111 offset:160
	s_waitcnt lgkmcnt(1)
	v_mul_f32_e32 v48, v48, v90
	s_waitcnt vmcnt(33)
	v_fmac_f32_e32 v98, v240, v48
	v_cvt_pk_bf16_f32 v48, v98, s0
	v_lshlrev_b32_e32 v97, 16, v48
	global_store_short v[64:65], v48, off
	v_mul_f32_e32 v48, v49, v91
	v_fmac_f32_e32 v99, v240, v48
	v_cvt_pk_bf16_f32 v48, v99, s0
	v_lshlrev_b32_e32 v95, 16, v48
	global_store_short v[64:65], v48, off offset:2048
	v_mul_f32_e32 v48, v50, v92
	v_fmac_f32_e32 v103, v240, v48
	v_cvt_pk_bf16_f32 v50, v103, s0
	v_add_co_u32_e64 v48, s[0:1], s96, v64
	v_lshlrev_b32_e32 v94, 16, v50
	s_nop 0
	v_addc_co_u32_e64 v49, s[0:1], 0, v65, s[0:1]
	global_store_short v[48:49], v50, off
	v_mul_f32_e32 v50, v51, v93
	v_fmac_f32_e32 v108, v240, v50
	v_cvt_pk_bf16_f32 v50, v108, s0
	global_store_short v[48:49], v50, off offset:2048
	s_waitcnt lgkmcnt(0)
	v_mul_f32_e32 v48, v52, v104
	v_fmac_f32_e32 v109, v240, v48
	v_cvt_pk_bf16_f32 v52, v109, s0
	v_add_co_u32_e64 v48, s[0:1], s94, v64
	v_lshlrev_b32_e32 v99, 16, v50
	s_nop 0
	v_addc_co_u32_e64 v49, s[0:1], 0, v65, s[0:1]
	v_add_co_u32_e64 v50, s[0:1], s57, v64
	v_lshlrev_b32_e32 v98, 16, v52
	s_nop 0
	v_addc_co_u32_e64 v51, s[0:1], 0, v65, s[0:1]
	global_store_short v[50:51], v52, off offset:-4096
	v_mul_f32_e32 v52, v53, v105
	v_fmac_f32_e32 v102, v240, v52
	v_cvt_pk_bf16_f32 v53, v102, s0
	global_store_short v[48:49], v53, off offset:2048
	v_mul_f32_e32 v48, v54, v106
	v_fmac_f32_e32 v101, v240, v48
	v_cvt_pk_bf16_f32 v48, v101, s0
	v_lshlrev_b32_e32 v96, 16, v48
	global_store_short v[50:51], v48, off
	v_mul_f32_e32 v48, v55, v107
	v_fmac_f32_e32 v100, v240, v48
	v_cvt_pk_bf16_f32 v48, v100, s0
	v_lshlrev_b32_e32 v52, 16, v53
	v_lshlrev_b32_e32 v53, 16, v48
	global_store_short v[50:51], v48, off offset:2048
	ds_read_b128 v[48:51], v111 offset:192
	s_waitcnt lgkmcnt(0)
	v_mul_f32_e32 v48, v56, v48
	v_fmac_f32_e32 v89, v240, v48
	v_cvt_pk_bf16_f32 v48, v89, s0
	v_add_co_u32_e64 v54, s[0:1], s35, v64
	v_lshlrev_b32_e32 v92, 16, v48
	s_nop 0
	v_addc_co_u32_e64 v55, s[0:1], 0, v65, s[0:1]
	v_add_co_u32_e64 v100, s[0:1], s58, v64
	s_nop 1
	v_addc_co_u32_e64 v101, s[0:1], 0, v65, s[0:1]
	global_store_short v[100:101], v48, off offset:-4096
	v_mul_f32_e32 v48, v57, v49
	v_fmac_f32_e32 v88, v240, v48
	v_cvt_pk_bf16_f32 v48, v88, s0
	v_lshlrev_b32_e32 v93, 16, v48
	global_store_short v[54:55], v48, off offset:2048
	v_mul_f32_e32 v48, v58, v50
	v_fmac_f32_e32 v87, v240, v48
	v_cvt_pk_bf16_f32 v48, v87, s0
	v_lshlrev_b32_e32 v91, 16, v48
	global_store_short v[100:101], v48, off
	v_mul_f32_e32 v48, v59, v51
	v_fmac_f32_e32 v86, v240, v48
	v_cvt_pk_bf16_f32 v48, v86, s0
	v_lshlrev_b32_e32 v90, 16, v48
	global_store_short v[100:101], v48, off offset:2048
	ds_read_b128 v[48:51], v111 offset:224
	v_mov_b32_e32 v101, v158
	s_waitcnt lgkmcnt(0)
	v_mul_f32_e32 v48, v60, v48
	v_fmac_f32_e32 v73, v240, v48
	v_cvt_pk_bf16_f32 v48, v73, s0
	v_add_co_u32_e64 v54, s[0:1], s95, v64
	v_lshlrev_b32_e32 v89, 16, v48
	s_nop 0
	v_addc_co_u32_e64 v55, s[0:1], 0, v65, s[0:1]
	v_add_co_u32_e64 v56, s[0:1], s59, v64
	s_nop 1
	v_addc_co_u32_e64 v57, s[0:1], 0, v65, s[0:1]
	global_store_short v[56:57], v48, off offset:-4096
	v_mul_f32_e32 v48, v61, v49
	v_fmac_f32_e32 v71, v240, v48
	v_cvt_pk_bf16_f32 v48, v71, s0
	v_lshlrev_b32_e32 v88, 16, v48
	global_store_short v[54:55], v48, off offset:2048
	v_mul_f32_e32 v48, v62, v50
	v_fmac_f32_e32 v70, v240, v48
	v_cvt_pk_bf16_f32 v48, v70, s0
	v_lshlrev_b32_e32 v87, 16, v48
	global_store_short v[56:57], v48, off
	v_mul_f32_e32 v48, v63, v51
	v_fmac_f32_e32 v68, v240, v48
	v_cvt_pk_bf16_f32 v48, v68, s0
	v_lshlrev_b32_e32 v86, 16, v48
	global_store_short v[56:57], v48, off offset:2048
	v_mov_b32_e32 v48, v130
	s_nop 0
	v_ashrrev_i32_e32 v49, 31, v48
	v_lshl_add_u64 v[48:49], v[48:49], 1, s[50:51]
	global_load_ushort v73, v[48:49], off offset:128
	s_waitcnt vmcnt(50)
	global_load_ushort v70, v[48:49], off offset:2176
	s_waitcnt vmcnt(51)
	v_add_co_u32_e64 v50, s[0:1], s96, v48
	s_nop 1
	v_addc_co_u32_e64 v51, s[0:1], 0, v49, s[0:1]
	global_load_ushort v71, v[50:51], off offset:128
	s_waitcnt vmcnt(52)
	global_load_ushort v63, v[50:51], off offset:2176
	s_waitcnt vmcnt(53)
	v_add_co_u32_e64 v50, s[0:1], s94, v48
	s_nop 1
	v_addc_co_u32_e64 v51, s[0:1], 0, v49, s[0:1]
	global_load_ushort v65, v[50:51], off offset:128
	s_waitcnt vmcnt(54)
	global_load_ushort v62, v[50:51], off offset:2176
	s_waitcnt vmcnt(55)
	v_add_co_u32_e64 v50, s[0:1], s57, v48
	s_nop 1
	v_addc_co_u32_e64 v51, s[0:1], 0, v49, s[0:1]
	global_load_ushort v68, v[50:51], off offset:128
	s_waitcnt vmcnt(56)
	global_load_ushort v64, v[50:51], off offset:2176
	s_waitcnt vmcnt(57)
	v_add_co_u32_e64 v50, s[0:1], s35, v48
	s_nop 1
	v_addc_co_u32_e64 v51, s[0:1], 0, v49, s[0:1]
	global_load_ushort v59, v[50:51], off offset:128
	s_waitcnt vmcnt(58)
	global_load_ushort v58, v[50:51], off offset:2176
	s_waitcnt vmcnt(59)
	v_add_co_u32_e64 v50, s[0:1], s58, v48
	s_nop 1
	v_addc_co_u32_e64 v51, s[0:1], 0, v49, s[0:1]
	global_load_ushort v61, v[50:51], off offset:128
	s_waitcnt vmcnt(60)
	global_load_ushort v60, v[50:51], off offset:2176
	s_waitcnt vmcnt(61)
	v_add_co_u32_e64 v50, s[0:1], s95, v48
	s_nop 1
	v_addc_co_u32_e64 v51, s[0:1], 0, v49, s[0:1]
	global_load_ushort v56, v[50:51], off offset:128
	v_add_co_u32_e64 v48, s[0:1], s59, v48
	global_load_ushort v54, v[50:51], off offset:2176
	s_nop 0
	v_addc_co_u32_e64 v49, s[0:1], 0, v49, s[0:1]
	s_waitcnt vmcnt(1)
	global_load_ushort v57, v[48:49], off offset:128
	s_waitcnt vmcnt(2)
	global_load_ushort v55, v[48:49], off offset:2176
	s_waitcnt vmcnt(3)
	v_mov_b32_e32 v48, v128
	s_nop 0
	v_ashrrev_i32_e32 v49, 31, v48
	v_lshl_add_u64 v[48:49], v[48:49], 0, s[68:69]
	v_lshl_add_u64 v[50:51], v[48:49], 2, s[36:37]
	v_lshl_add_u32 v50, v101, 2, s28
	v_lshl_add_u32 v101, v101, 4, s39
	ds_read_b128 v[102:105], v101 offset:128
	ds_read_b128 v[106:109], v101 offset:160
	v_ashrrev_i32_e32 v51, 31, v50
	v_lshlrev_b64 v[50:51], 11, v[50:51]
	v_lshl_add_u64 v[50:51], s[66:67], 0, v[50:51]
	s_waitcnt lgkmcnt(1)
	v_mul_f32_e32 v32, v32, v102
	v_lshl_add_u64 v[48:49], v[48:49], 1, v[50:51]
	v_mul_f32_e32 v35, v35, v105
	s_waitcnt lgkmcnt(0)
	v_mul_f32_e32 v37, v37, v107
	s_waitcnt vmcnt(3)
	s_waitcnt vmcnt(47)
	v_lshlrev_b32_e32 v85, 16, v85
	v_fmac_f32_e32 v85, v241, v32
	v_cvt_pk_bf16_f32 v32, v85, s0
	v_lshlrev_b32_e32 v50, 16, v32
	global_store_short v[48:49], v32, off offset:64
	v_mul_f32_e32 v32, v33, v103
	s_waitcnt vmcnt(47)
	v_lshlrev_b32_e32 v84, 16, v84
	v_fmac_f32_e32 v84, v241, v32
	v_cvt_pk_bf16_f32 v32, v84, s0
	v_lshlrev_b32_e32 v33, 16, v32
	global_store_short v[48:49], v32, off offset:2112
	v_mul_f32_e32 v32, v34, v104
	s_waitcnt vmcnt(47)
	v_lshlrev_b32_e32 v83, 16, v83
	v_fmac_f32_e32 v83, v241, v32
	v_cvt_pk_bf16_f32 v34, v83, s0
	v_add_co_u32_e64 v32, s[0:1], s96, v48
	v_mul_f32_e32 v51, v33, v33
	s_nop 0
	v_addc_co_u32_e64 v33, s[0:1], 0, v49, s[0:1]
	s_waitcnt vmcnt(46)
	v_lshlrev_b32_e32 v82, 16, v82
	v_fmac_f32_e32 v82, v241, v35
	s_nop 0
	v_cvt_pk_bf16_f32 v35, v82, s0
	global_store_short v[32:33], v34, off offset:64
	global_store_short v[32:33], v35, off offset:2112
	v_mul_f32_e32 v32, v36, v106
	s_waitcnt vmcnt(47)
	v_lshlrev_b32_e32 v81, 16, v81
	v_fmac_f32_e32 v81, v241, v32
	v_cvt_pk_bf16_f32 v36, v81, s0
	v_add_co_u32_e64 v32, s[0:1], s94, v48
	s_waitcnt vmcnt(46)
	v_lshlrev_b32_e32 v78, 16, v78
	v_fmac_f32_e32 v78, v241, v37
	s_nop 0
	v_addc_co_u32_e64 v33, s[0:1], 0, v49, s[0:1]
	global_store_short v[32:33], v36, off offset:64
	s_nop 0
	v_cvt_pk_bf16_f32 v37, v78, s0
	global_store_short v[32:33], v37, off offset:2112
	v_mul_f32_e32 v32, v38, v108
	s_waitcnt vmcnt(47)
	v_lshlrev_b32_e32 v80, 16, v80
	v_fmac_f32_e32 v80, v241, v32
	v_lshlrev_b32_e32 v78, 16, v37
	v_cvt_pk_bf16_f32 v38, v80, s0
	v_add_co_u32_e64 v32, s[0:1], s57, v48
	v_mul_f32_e32 v37, v78, v78
	s_nop 0
	v_addc_co_u32_e64 v33, s[0:1], 0, v49, s[0:1]
	v_fmac_f32_e32 v37, v52, v52
	v_lshlrev_b32_e32 v52, 16, v38
	global_store_short v[32:33], v38, off offset:64
	v_mul_f32_e32 v38, v39, v109
	v_lshlrev_b32_e32 v81, 16, v36
	s_waitcnt vmcnt(47)
	v_lshlrev_b32_e32 v79, 16, v79
	v_fmac_f32_e32 v79, v241, v38
	v_mul_f32_e32 v36, v81, v81
	v_cvt_pk_bf16_f32 v38, v79, s0
	ds_read_b128 v[78:81], v101 offset:192
	global_store_short v[32:33], v38, off offset:2112
	v_lshlrev_b32_e32 v39, 16, v38
	v_mul_f32_e32 v38, v39, v39
	v_fmac_f32_e32 v38, v53, v53
	s_waitcnt lgkmcnt(0)
	v_mul_f32_e32 v32, v40, v78
	s_waitcnt vmcnt(47)
	v_lshlrev_b32_e32 v76, 16, v76
	v_fmac_f32_e32 v76, v241, v32
	v_cvt_pk_bf16_f32 v39, v76, s0
	v_add_co_u32_e64 v32, s[0:1], s35, v48
	v_lshlrev_b32_e32 v40, 16, v39
	s_nop 0
	v_addc_co_u32_e64 v33, s[0:1], 0, v49, s[0:1]
	global_store_short v[32:33], v39, off offset:64
	v_mul_f32_e32 v39, v41, v79
	s_waitcnt vmcnt(47)
	v_lshlrev_b32_e32 v74, 16, v74
	v_fmac_f32_e32 v74, v241, v39
	v_cvt_pk_bf16_f32 v39, v74, s0
	global_store_short v[32:33], v39, off offset:2112
	v_mul_f32_e32 v32, v42, v80
	s_waitcnt vmcnt(47)
	v_lshlrev_b32_e32 v77, 16, v77
	v_fmac_f32_e32 v77, v241, v32
	v_mul_f32_e32 v53, v40, v40
	v_lshlrev_b32_e32 v40, 16, v39
	v_cvt_pk_bf16_f32 v39, v77, s0
	v_add_co_u32_e64 v32, s[0:1], s58, v48
	v_mul_f32_e32 v41, v40, v40
	s_nop 0
	v_addc_co_u32_e64 v33, s[0:1], 0, v49, s[0:1]
	v_lshlrev_b32_e32 v40, 16, v39
	global_store_short v[32:33], v39, off offset:64
	v_mul_f32_e32 v39, v43, v81
	s_waitcnt vmcnt(47)
	v_lshlrev_b32_e32 v75, 16, v75
	v_fmac_f32_e32 v75, v241, v39
	v_cvt_pk_bf16_f32 v39, v75, s0
	ds_read_b128 v[74:77], v101 offset:224
	global_store_short v[32:33], v39, off offset:2112
	v_lshlrev_b32_e32 v42, 16, v39
	v_mul_f32_e32 v39, v42, v42
	v_lshlrev_b32_e32 v83, 16, v34
	s_waitcnt lgkmcnt(0)
	v_mul_f32_e32 v32, v44, v74
	s_waitcnt vmcnt(47)
	v_lshlrev_b32_e32 v72, 16, v72
	v_fmac_f32_e32 v72, v241, v32
	v_cvt_pk_bf16_f32 v42, v72, s0
	v_add_co_u32_e64 v32, s[0:1], s95, v48
	v_lshlrev_b32_e32 v43, 16, v42
	s_nop 0
	v_addc_co_u32_e64 v33, s[0:1], 0, v49, s[0:1]
	global_store_short v[32:33], v42, off offset:64
	v_mul_f32_e32 v42, v43, v43
	v_mul_f32_e32 v43, v45, v75
	s_waitcnt vmcnt(47)
	v_lshlrev_b32_e32 v66, 16, v66
	v_fmac_f32_e32 v66, v241, v43
	v_cvt_pk_bf16_f32 v43, v66, s0
	global_store_short v[32:33], v43, off offset:2112
	v_mul_f32_e32 v32, v46, v76
	v_lshlrev_b32_e32 v44, 16, v43
	s_waitcnt vmcnt(47)
	v_lshlrev_b32_e32 v69, 16, v69
	v_fmac_f32_e32 v69, v241, v32
	v_mul_f32_e32 v43, v44, v44
	v_cvt_pk_bf16_f32 v44, v69, s0
	v_add_co_u32_e64 v32, s[0:1], s59, v48
	v_lshlrev_b32_e32 v45, 16, v44
	s_nop 0
	v_addc_co_u32_e64 v33, s[0:1], 0, v49, s[0:1]
	global_store_short v[32:33], v44, off offset:64
	v_mul_f32_e32 v44, v45, v45
	v_mul_f32_e32 v45, v47, v77
	s_waitcnt vmcnt(47)
	v_lshlrev_b32_e32 v67, 16, v189
	v_fmac_f32_e32 v67, v241, v45
	v_cvt_pk_bf16_f32 v45, v67, s0
	global_store_short v[32:33], v45, off offset:2112
	v_lshlrev_b32_e32 v46, 16, v45
	v_ashrrev_i32_e32 v131, 31, v130
	v_lshl_add_u64 v[32:33], v[130:131], 1, s[50:51]
	v_mul_f32_e32 v45, v46, v46
	global_load_ushort v67, v[32:33], off offset:192
	v_lshlrev_b32_e32 v82, 16, v35
	v_mul_f32_e32 v34, v83, v83
	v_mul_f32_e32 v35, v82, v82
	v_fmac_f32_e32 v45, v86, v86
	v_mov_b32_e32 v86, v158
	v_mul_f32_e32 v40, v40, v40
	v_fmac_f32_e32 v40, v91, v91
	v_fmac_f32_e32 v39, v90, v90
	v_fmac_f32_e32 v42, v89, v89
	v_fmac_f32_e32 v43, v88, v88
	v_fmac_f32_e32 v44, v87, v87
	v_fmac_f32_e32 v51, v95, v95
	v_fmac_f32_e32 v35, v99, v99
	v_fmac_f32_e32 v36, v98, v98
	v_mul_f32_e32 v52, v52, v52
	v_fmac_f32_e32 v52, v96, v96
	v_fmac_f32_e32 v41, v93, v93
	v_fmac_f32_e32 v53, v92, v92
	v_mul_f32_e32 v50, v50, v50
	v_fmac_f32_e32 v50, v97, v97
	v_fmac_f32_e32 v34, v94, v94
	s_waitcnt vmcnt(20)
	global_load_ushort v66, v[32:33], off offset:2240
	s_waitcnt vmcnt(21)
	v_add_co_u32_e64 v46, s[0:1], s96, v32
	s_nop 1
	v_addc_co_u32_e64 v47, s[0:1], 0, v33, s[0:1]
	global_load_ushort v72, v[46:47], off offset:192
	s_waitcnt vmcnt(22)
	global_load_ushort v69, v[46:47], off offset:2240
	s_waitcnt vmcnt(23)
	v_add_co_u32_e64 v46, s[0:1], s94, v32
	s_nop 1
	v_addc_co_u32_e64 v47, s[0:1], 0, v33, s[0:1]
	global_load_ushort v75, v[46:47], off offset:192
	s_waitcnt vmcnt(24)
	global_load_ushort v74, v[46:47], off offset:2240
	s_waitcnt vmcnt(25)
	v_add_co_u32_e64 v46, s[0:1], s57, v32
	s_nop 1
	v_addc_co_u32_e64 v47, s[0:1], 0, v33, s[0:1]
	global_load_ushort v81, v[46:47], off offset:192
	s_waitcnt vmcnt(26)
	global_load_ushort v79, v[46:47], off offset:2240
	s_waitcnt vmcnt(27)
	v_add_co_u32_e64 v46, s[0:1], s35, v32
	s_nop 1
	v_addc_co_u32_e64 v47, s[0:1], 0, v33, s[0:1]
	global_load_ushort v77, v[46:47], off offset:192
	s_waitcnt vmcnt(28)
	global_load_ushort v76, v[46:47], off offset:2240
	s_waitcnt vmcnt(29)
	v_add_co_u32_e64 v46, s[0:1], s58, v32
	s_nop 1
	v_addc_co_u32_e64 v47, s[0:1], 0, v33, s[0:1]
	global_load_ushort v80, v[46:47], off offset:192
	s_waitcnt vmcnt(30)
	global_load_ushort v78, v[46:47], off offset:2240
	v_add_co_u32_e64 v48, s[0:1], s95, v32
	s_waitcnt vmcnt(31)
	v_addc_co_u32_e64 v49, s[0:1], 0, v33, s[0:1]
	global_load_ushort v47, v[48:49], off offset:192
	v_add_co_u32_e64 v32, s[0:1], s59, v32
	s_waitcnt vmcnt(32)
	v_addc_co_u32_e64 v33, s[0:1], 0, v33, s[0:1]
	global_load_ushort v46, v[48:49], off offset:2240
	s_waitcnt vmcnt(33)
	global_load_ushort v49, v[32:33], off offset:192
	s_waitcnt vmcnt(34)
	global_load_ushort v48, v[32:33], off offset:2240
	s_waitcnt vmcnt(35)
	v_mov_b32_e32 v32, v128
	s_nop 0
	v_ashrrev_i32_e32 v33, 31, v32
	v_lshl_add_u64 v[32:33], v[32:33], 0, s[68:69]
	v_lshl_add_u64 v[82:83], v[32:33], 2, s[36:37]
	v_lshl_add_u32 v84, v86, 2, s28
	v_ashrrev_i32_e32 v85, 31, v84
	v_lshlrev_b64 v[84:85], 11, v[84:85]
	v_lshl_add_u64 v[84:85], s[66:67], 0, v[84:85]
	v_lshl_add_u32 v83, v86, 4, s39
	v_lshl_add_u64 v[32:33], v[32:33], 1, v[84:85]
	ds_read_b128 v[84:87], v83 offset:128
	ds_read_b128 v[88:91], v83 offset:160
	s_waitcnt lgkmcnt(1)
	v_mul_f32_e32 v16, v16, v84
	s_waitcnt vmcnt(35)
	s_waitcnt vmcnt(47)
	v_lshlrev_b32_e32 v73, 16, v73
	v_fmac_f32_e32 v73, v242, v16
	v_cvt_pk_bf16_f32 v16, v73, s0
	v_lshlrev_b32_e32 v73, 16, v16
	global_store_short v[32:33], v16, off offset:128
	v_mul_f32_e32 v16, v17, v85
	s_waitcnt vmcnt(47)
	v_lshlrev_b32_e32 v70, 16, v70
	v_fmac_f32_e32 v70, v242, v16
	v_cvt_pk_bf16_f32 v16, v70, s0
	v_lshlrev_b32_e32 v17, 16, v16
	global_store_short v[32:33], v16, off offset:2176
	v_mul_f32_e32 v16, v18, v86
	s_waitcnt vmcnt(47)
	v_lshlrev_b32_e32 v71, 16, v71
	v_fmac_f32_e32 v71, v242, v16
	v_cvt_pk_bf16_f32 v18, v71, s0
	v_add_co_u32_e64 v16, s[0:1], s96, v32
	v_fmac_f32_e32 v51, v17, v17
	s_nop 0
	v_addc_co_u32_e64 v17, s[0:1], 0, v33, s[0:1]
	v_lshlrev_b32_e32 v70, 16, v18
	global_store_short v[16:17], v18, off offset:128
	v_mul_f32_e32 v18, v19, v87
	s_waitcnt vmcnt(47)
	v_lshlrev_b32_e32 v63, 16, v63
	v_fmac_f32_e32 v63, v242, v18
	v_cvt_pk_bf16_f32 v18, v63, s0
	global_store_short v[16:17], v18, off offset:2176
	s_waitcnt lgkmcnt(0)
	v_mul_f32_e32 v16, v20, v88
	s_waitcnt vmcnt(47)
	v_lshlrev_b32_e32 v65, 16, v65
	v_fmac_f32_e32 v65, v242, v16
	v_lshlrev_b32_e32 v19, 16, v18
	v_cvt_pk_bf16_f32 v18, v65, s0
	v_add_co_u32_e64 v16, s[0:1], s94, v32
	v_fmac_f32_e32 v35, v19, v19
	s_nop 0
	v_addc_co_u32_e64 v17, s[0:1], 0, v33, s[0:1]
	v_lshlrev_b32_e32 v19, 16, v18
	global_store_short v[16:17], v18, off offset:128
	v_mul_f32_e32 v18, v21, v89
	s_waitcnt vmcnt(47)
	v_lshlrev_b32_e32 v62, 16, v62
	v_fmac_f32_e32 v62, v242, v18
	v_cvt_pk_bf16_f32 v18, v62, s0
	global_store_short v[16:17], v18, off offset:2176
	v_mul_f32_e32 v16, v22, v90
	s_waitcnt vmcnt(47)
	v_lshlrev_b32_e32 v68, 16, v68
	v_fmac_f32_e32 v68, v242, v16
	v_fmac_f32_e32 v36, v19, v19
	v_lshlrev_b32_e32 v19, 16, v18
	v_cvt_pk_bf16_f32 v18, v68, s0
	v_add_co_u32_e64 v16, s[0:1], s57, v32
	v_fmac_f32_e32 v37, v19, v19
	s_nop 0
	v_addc_co_u32_e64 v17, s[0:1], 0, v33, s[0:1]
	v_lshlrev_b32_e32 v19, 16, v18
	global_store_short v[16:17], v18, off offset:128
	v_mul_f32_e32 v18, v23, v91
	s_waitcnt vmcnt(47)
	v_lshlrev_b32_e32 v64, 16, v64
	v_fmac_f32_e32 v64, v242, v18
	v_cvt_pk_bf16_f32 v18, v64, s0
	v_fmac_f32_e32 v52, v19, v19
	v_lshlrev_b32_e32 v19, 16, v18
	global_store_short v[16:17], v18, off offset:2176
	v_fmac_f32_e32 v38, v19, v19
	ds_read_b128 v[16:19], v83 offset:192
	v_fmac_f32_e32 v50, v73, v73
	v_fmac_f32_e32 v34, v70, v70
	s_waitcnt lgkmcnt(0)
	v_mul_f32_e32 v16, v24, v16
	s_waitcnt vmcnt(47)
	v_lshlrev_b32_e32 v59, 16, v59
	v_fmac_f32_e32 v59, v242, v16
	v_cvt_pk_bf16_f32 v16, v59, s0
	v_add_co_u32_e64 v20, s[0:1], s35, v32
	v_lshlrev_b32_e32 v22, 16, v16
	s_nop 0
	v_addc_co_u32_e64 v21, s[0:1], 0, v33, s[0:1]
	global_store_short v[20:21], v16, off offset:128
	v_mul_f32_e32 v16, v25, v17
	s_waitcnt vmcnt(47)
	v_lshlrev_b32_e32 v58, 16, v58
	v_fmac_f32_e32 v58, v242, v16
	v_cvt_pk_bf16_f32 v16, v58, s0
	v_lshlrev_b32_e32 v17, 16, v16
	global_store_short v[20:21], v16, off offset:2176
	v_mul_f32_e32 v16, v26, v18
	s_waitcnt vmcnt(47)
	v_lshlrev_b32_e32 v61, 16, v61
	v_fmac_f32_e32 v61, v242, v16
	v_cvt_pk_bf16_f32 v18, v61, s0
	v_add_co_u32_e64 v16, s[0:1], s58, v32
	v_fmac_f32_e32 v41, v17, v17
	s_nop 0
	v_addc_co_u32_e64 v17, s[0:1], 0, v33, s[0:1]
	v_lshlrev_b32_e32 v20, 16, v18
	global_store_short v[16:17], v18, off offset:128
	v_mul_f32_e32 v18, v27, v19
	s_waitcnt vmcnt(47)
	v_lshlrev_b32_e32 v60, 16, v60
	v_fmac_f32_e32 v60, v242, v18
	v_cvt_pk_bf16_f32 v18, v60, s0
	v_lshlrev_b32_e32 v19, 16, v18
	global_store_short v[16:17], v18, off offset:2176
	v_fmac_f32_e32 v39, v19, v19
	ds_read_b128 v[16:19], v83 offset:224
	v_fmac_f32_e32 v40, v20, v20
	v_fmac_f32_e32 v53, v22, v22
	s_waitcnt lgkmcnt(0)
	v_mul_f32_e32 v16, v28, v16
	s_waitcnt vmcnt(47)
	v_lshlrev_b32_e32 v56, 16, v56
	v_fmac_f32_e32 v56, v242, v16
	v_cvt_pk_bf16_f32 v16, v56, s0
	v_add_co_u32_e64 v20, s[0:1], s95, v32
	v_lshlrev_b32_e32 v22, 16, v16
	s_nop 0
	v_addc_co_u32_e64 v21, s[0:1], 0, v33, s[0:1]
	global_store_short v[20:21], v16, off offset:128
	v_mul_f32_e32 v16, v29, v17
	s_waitcnt vmcnt(47)
	v_lshlrev_b32_e32 v54, 16, v54
	v_fmac_f32_e32 v54, v242, v16
	v_cvt_pk_bf16_f32 v16, v54, s0
	v_lshlrev_b32_e32 v17, 16, v16
	global_store_short v[20:21], v16, off offset:2176
	v_mul_f32_e32 v16, v30, v18
	s_waitcnt vmcnt(47)
	v_lshlrev_b32_e32 v57, 16, v57
	v_fmac_f32_e32 v57, v242, v16
	v_cvt_pk_bf16_f32 v18, v57, s0
	v_add_co_u32_e64 v16, s[0:1], s59, v32
	v_fmac_f32_e32 v43, v17, v17
	s_nop 0
	v_addc_co_u32_e64 v17, s[0:1], 0, v33, s[0:1]
	v_lshlrev_b32_e32 v20, 16, v18
	global_store_short v[16:17], v18, off offset:128
	v_mul_f32_e32 v18, v31, v19
	s_waitcnt vmcnt(47)
	v_lshlrev_b32_e32 v55, 16, v55
	v_fmac_f32_e32 v55, v242, v18
	v_cvt_pk_bf16_f32 v18, v55, s0
	global_store_short v[16:17], v18, off offset:2176
	v_lshlrev_b32_e32 v19, 16, v18
	v_ashrrev_i32_e32 v129, 31, v128
	v_lshl_add_u64 v[16:17], v[128:129], 0, s[68:69]
	v_fmac_f32_e32 v45, v19, v19
	v_lshl_add_u64 v[18:19], v[16:17], 2, s[36:37]
	v_fmac_f32_e32 v44, v20, v20
	v_lshl_add_u32 v20, v158, 2, s28
	v_ashrrev_i32_e32 v21, 31, v20
	v_lshlrev_b64 v[20:21], 11, v[20:21]
	v_lshl_add_u64 v[20:21], s[66:67], 0, v[20:21]
	v_lshl_add_u32 v19, v158, 4, s39
	v_fmac_f32_e32 v42, v22, v22
	v_lshl_add_u64 v[16:17], v[16:17], 1, v[20:21]
	ds_read_b128 v[20:23], v19 offset:128
	ds_read_b128 v[24:27], v19 offset:160
	s_waitcnt lgkmcnt(1)
	v_mul_f32_e32 v0, v0, v20
	s_waitcnt vmcnt(51)
	s_waitcnt vmcnt(31)
	v_lshlrev_b32_e32 v67, 16, v67
	v_fmac_f32_e32 v67, v243, v0
	v_mul_f32_e32 v0, v1, v21
	s_waitcnt vmcnt(30)
	v_lshlrev_b32_e32 v66, 16, v66
	v_fmac_f32_e32 v66, v243, v0
	v_mul_f32_e32 v0, v2, v22
	s_waitcnt vmcnt(29)
	v_lshlrev_b32_e32 v72, 16, v72
	v_fmac_f32_e32 v72, v243, v0
	v_cvt_pk_bf16_f32 v20, v67, s0
	v_cvt_pk_bf16_f32 v21, v66, s0
	v_cvt_pk_bf16_f32 v22, v72, s0
	v_add_co_u32_e64 v0, s[0:1], s96, v16
	v_mul_f32_e32 v2, v3, v23
	s_nop 0
	v_addc_co_u32_e64 v1, s[0:1], 0, v17, s[0:1]
	s_waitcnt vmcnt(28)
	v_lshlrev_b32_e32 v69, 16, v69
	v_fmac_f32_e32 v69, v243, v2
	s_nop 0
	v_cvt_pk_bf16_f32 v23, v69, s0
	global_store_short v[0:1], v22, off offset:192
	global_store_short v[0:1], v23, off offset:2240
	s_waitcnt lgkmcnt(0)
	v_mul_f32_e32 v0, v4, v24
	s_waitcnt vmcnt(29)
	v_lshlrev_b32_e32 v75, 16, v75
	v_fmac_f32_e32 v75, v243, v0
	v_cvt_pk_bf16_f32 v24, v75, s0
	v_add_co_u32_e64 v0, s[0:1], s94, v16
	v_mul_f32_e32 v2, v5, v25
	s_nop 0
	v_addc_co_u32_e64 v1, s[0:1], 0, v17, s[0:1]
	s_waitcnt vmcnt(28)
	v_lshlrev_b32_e32 v74, 16, v74
	v_fmac_f32_e32 v74, v243, v2
	s_nop 0
	v_cvt_pk_bf16_f32 v25, v74, s0
	global_store_short v[0:1], v24, off offset:192
	global_store_short v[0:1], v25, off offset:2240
	v_mul_f32_e32 v0, v6, v26
	s_waitcnt vmcnt(29)
	v_lshlrev_b32_e32 v81, 16, v81
	v_fmac_f32_e32 v81, v243, v0
	v_cvt_pk_bf16_f32 v6, v81, s0
	v_add_co_u32_e64 v0, s[0:1], s57, v16
	v_mul_f32_e32 v2, v7, v27
	s_nop 0
	v_addc_co_u32_e64 v1, s[0:1], 0, v17, s[0:1]
	s_waitcnt vmcnt(28)
	v_lshlrev_b32_e32 v79, 16, v79
	v_fmac_f32_e32 v79, v243, v2
	s_nop 0
	v_cvt_pk_bf16_f32 v7, v79, s0
	global_store_short v[0:1], v6, off offset:192
	global_store_short v[0:1], v7, off offset:2240
	ds_read_b128 v[0:3], v19 offset:192
	global_store_short v[16:17], v20, off offset:192
	global_store_short v[16:17], v21, off offset:2240
	s_waitcnt lgkmcnt(0)
	v_mul_f32_e32 v0, v8, v0
	s_waitcnt vmcnt(31)
	v_lshlrev_b32_e32 v77, 16, v77
	v_fmac_f32_e32 v77, v243, v0
	v_mul_f32_e32 v0, v9, v1
	v_cvt_pk_bf16_f32 v8, v77, s0
	v_add_co_u32_e64 v4, s[0:1], s35, v16
	s_waitcnt vmcnt(30)
	v_lshlrev_b32_e32 v76, 16, v76
	v_fmac_f32_e32 v76, v243, v0
	v_mul_f32_e32 v0, v10, v2
	v_addc_co_u32_e64 v5, s[0:1], 0, v17, s[0:1]
	s_waitcnt vmcnt(29)
	v_lshlrev_b32_e32 v80, 16, v80
	v_fmac_f32_e32 v80, v243, v0
	s_nop 0
	v_cvt_pk_bf16_f32 v9, v76, s0
	v_cvt_pk_bf16_f32 v10, v80, s0
	v_add_co_u32_e64 v0, s[0:1], s58, v16
	v_mul_f32_e32 v2, v11, v3
	s_nop 0
	v_addc_co_u32_e64 v1, s[0:1], 0, v17, s[0:1]
	s_waitcnt vmcnt(28)
	v_lshlrev_b32_e32 v78, 16, v78
	v_fmac_f32_e32 v78, v243, v2
	s_nop 0
	v_cvt_pk_bf16_f32 v11, v78, s0
	global_store_short v[0:1], v10, off offset:192
	global_store_short v[0:1], v11, off offset:2240
	ds_read_b128 v[0:3], v19 offset:224
	global_store_short v[4:5], v8, off offset:192
	global_store_short v[4:5], v9, off offset:2240
	s_waitcnt lgkmcnt(0)
	v_mul_f32_e32 v0, v12, v0
	s_waitcnt vmcnt(31)
	v_lshlrev_b32_e32 v47, 16, v47
	v_fmac_f32_e32 v47, v243, v0
	v_mul_f32_e32 v0, v13, v1
	v_cvt_pk_bf16_f32 v12, v47, s0
	v_add_co_u32_e64 v4, s[0:1], s95, v16
	s_waitcnt vmcnt(30)
	v_lshlrev_b32_e32 v46, 16, v46
	v_fmac_f32_e32 v46, v243, v0
	v_mul_f32_e32 v0, v14, v2
	v_addc_co_u32_e64 v5, s[0:1], 0, v17, s[0:1]
	s_waitcnt vmcnt(29)
	v_lshlrev_b32_e32 v49, 16, v49
	v_fmac_f32_e32 v49, v243, v0
	s_nop 0
	v_cvt_pk_bf16_f32 v13, v46, s0
	v_cvt_pk_bf16_f32 v2, v49, s0
	v_add_co_u32_e64 v0, s[0:1], s59, v16
	v_mul_f32_e32 v3, v15, v3
	s_nop 0
	v_addc_co_u32_e64 v1, s[0:1], 0, v17, s[0:1]
	s_waitcnt vmcnt(28)
	v_lshlrev_b32_e32 v48, 16, v48
	v_fmac_f32_e32 v48, v243, v3
	s_nop 0
	v_cvt_pk_bf16_f32 v3, v48, s0
	global_store_short v[0:1], v2, off offset:192
	global_store_short v[0:1], v3, off offset:2240
	v_lshlrev_b32_e32 v0, 16, v20
	v_fmac_f32_e32 v50, v0, v0
	v_lshlrev_b32_e32 v0, 16, v21
	v_fmac_f32_e32 v51, v0, v0
	v_lshlrev_b32_e32 v0, 16, v22
	v_fmac_f32_e32 v34, v0, v0
	v_lshlrev_b32_e32 v0, 16, v23
	v_fmac_f32_e32 v35, v0, v0
	v_lshlrev_b32_e32 v0, 16, v24
	v_fmac_f32_e32 v36, v0, v0
	v_lshlrev_b32_e32 v0, 16, v25
	v_fmac_f32_e32 v37, v0, v0
	v_lshlrev_b32_e32 v0, 16, v6
	v_fmac_f32_e32 v52, v0, v0
	v_lshlrev_b32_e32 v0, 16, v7
	v_fmac_f32_e32 v38, v0, v0
	v_lshlrev_b32_e32 v0, 16, v8
	v_fmac_f32_e32 v53, v0, v0
	v_lshlrev_b32_e32 v0, 16, v9
	v_fmac_f32_e32 v41, v0, v0
	v_lshlrev_b32_e32 v0, 16, v10
	v_fmac_f32_e32 v40, v0, v0
	v_lshlrev_b32_e32 v0, 16, v11
	v_fmac_f32_e32 v39, v0, v0
	v_lshlrev_b32_e32 v0, 16, v12
	v_fmac_f32_e32 v42, v0, v0
	v_lshlrev_b32_e32 v0, 16, v13
	v_cndmask_b32_e64 v1, v50, v53, s[46:47]
	v_fmac_f32_e32 v43, v0, v0
	v_lshlrev_b32_e32 v0, 16, v2
	ds_bpermute_b32 v1, v157, v1
	v_cndmask_b32_e64 v2, v51, v41, s[46:47]
	v_fmac_f32_e32 v44, v0, v0
	v_lshlrev_b32_e32 v0, 16, v3
	ds_bpermute_b32 v2, v157, v2
	v_cndmask_b32_e64 v3, v34, v40, s[46:47]
	global_store_short v[4:5], v12, off offset:192
	global_store_short v[4:5], v13, off offset:2240
	ds_bpermute_b32 v3, v157, v3
	v_cndmask_b32_e64 v4, v35, v39, s[46:47]
	ds_bpermute_b32 v4, v157, v4
	v_cndmask_b32_e64 v5, v36, v42, s[46:47]
	v_fmac_f32_e32 v45, v0, v0
	v_cndmask_b32_e64 v0, v53, v50, s[46:47]
	ds_bpermute_b32 v5, v157, v5
	v_cndmask_b32_e64 v6, v37, v43, s[46:47]
	s_waitcnt lgkmcnt(4)
	v_add_f32_e32 v0, v0, v1
	v_cndmask_b32_e64 v1, v41, v51, s[46:47]
	ds_bpermute_b32 v6, v157, v6
	v_cndmask_b32_e64 v7, v52, v44, s[46:47]
	s_waitcnt lgkmcnt(4)
	v_add_f32_e32 v1, v1, v2
	v_cndmask_b32_e64 v2, v40, v34, s[46:47]
	ds_bpermute_b32 v7, v157, v7
	v_cndmask_b32_e64 v8, v38, v45, s[46:47]
	s_waitcnt lgkmcnt(4)
	v_add_f32_e32 v2, v2, v3
	v_cndmask_b32_e64 v3, v39, v35, s[46:47]
	ds_bpermute_b32 v8, v157, v8
	s_waitcnt lgkmcnt(4)
	v_add_f32_e32 v3, v3, v4
	v_cndmask_b32_e64 v4, v42, v36, s[46:47]
	s_waitcnt lgkmcnt(3)
	v_add_f32_e32 v4, v4, v5
	v_cndmask_b32_e64 v5, v43, v37, s[46:47]
	s_waitcnt lgkmcnt(2)
	v_add_f32_e32 v5, v5, v6
	v_cndmask_b32_e64 v6, v44, v52, s[46:47]
	s_waitcnt lgkmcnt(1)
	v_add_f32_e32 v6, v6, v7
	v_cndmask_b32_e64 v7, v45, v38, s[46:47]
	s_waitcnt lgkmcnt(0)
	v_add_f32_e32 v7, v7, v8
	v_cndmask_b32_e64 v8, v4, v0, s[44:45]
	v_cndmask_b32_e64 v0, v0, v4, s[44:45]
	v_cndmask_b32_e64 v4, v5, v1, s[44:45]
	v_cndmask_b32_e64 v1, v1, v5, s[44:45]
	ds_bpermute_b32 v1, v156, v1
	ds_bpermute_b32 v0, v156, v0
	s_waitcnt lgkmcnt(1)
	v_add_f32_e32 v1, v4, v1
	v_cndmask_b32_e64 v4, v6, v2, s[44:45]
	v_cndmask_b32_e64 v2, v2, v6, s[44:45]
	ds_bpermute_b32 v2, v156, v2
	s_waitcnt lgkmcnt(1)
	v_add_f32_e32 v0, v8, v0
	s_waitcnt lgkmcnt(0)
	v_add_f32_e32 v2, v4, v2
	v_cndmask_b32_e64 v4, v7, v3, s[44:45]
	v_cndmask_b32_e64 v3, v3, v7, s[44:45]
	ds_bpermute_b32 v3, v156, v3
	s_waitcnt lgkmcnt(0)
	v_add_f32_e32 v3, v4, v3
	v_cndmask_b32_e64 v4, v2, v0, s[42:43]
	v_cndmask_b32_e64 v0, v0, v2, s[42:43]
	v_cndmask_b32_e64 v2, v3, v1, s[42:43]
	v_cndmask_b32_e64 v1, v1, v3, s[42:43]
	ds_bpermute_b32 v0, v155, v0
	ds_bpermute_b32 v1, v155, v1
	s_waitcnt lgkmcnt(1)
	v_add_f32_e32 v0, v4, v0
	s_waitcnt lgkmcnt(0)
	v_add_f32_e32 v1, v2, v1
	v_cndmask_b32_e64 v2, v1, v0, s[40:41]
	v_cndmask_b32_e64 v0, v0, v1, s[40:41]
	ds_bpermute_b32 v0, v154, v0
	s_waitcnt lgkmcnt(0)
	v_add_f32_e32 v0, v2, v0
	ds_bpermute_b32 v1, v153, v0
	s_and_saveexec_b64 s[0:1], vcc
	s_cbranch_execz .LBB0_405
	v_or_b32_e32 v2, s28, v152
	v_ashrrev_i32_e32 v3, 31, v2
	v_lshlrev_b64 v[2:3], 6, v[2:3]
	v_lshl_add_u64 v[2:3], s[26:27], 0, v[2:3]
	s_waitcnt lgkmcnt(0)
	v_add_f32_e32 v0, v0, v1
	global_store_dword v[2:3], v0, off
	s_branch .LBB0_405

.LBB0_488:
	s_or_b64 exec, exec, s[26:27]
	s_lshl_b32 s6, s7, 8
	s_lshl_b64 s[40:41], s[0:1], 11
	s_add_u32 s42, s66, s40
	s_addc_u32 s43, s67, s41
	s_lshl_b32 s7, s7, 19
	s_add_u32 s44, s2, s7
	s_addc_u32 s45, s3, 0
	v_lshrrev_b32_e32 v196, 3, v197
	v_and_b32_e32 v198, 7, v197
	v_lshlrev_b32_e32 v178, 11, v196
	v_lshl_or_b32 v178, v198, 4, v178
	v_add_u32_e32 v179, 0x10000, v178
	v_add_u32_e32 v180, 0x20000, v178
	v_add_u32_e32 v181, 0x30000, v178
	v_add_u32_e32 v182, 0x40000, v178
	v_add_u32_e32 v183, 0x50000, v178
	v_add_u32_e32 v184, 0x60000, v178
	v_add_u32_e32 v185, 0x70000, v178
	global_load_dwordx4 v[128:131], v178, s[42:43]
	global_load_dwordx4 v[132:135], v179, s[42:43]
	global_load_dwordx4 v[136:139], v180, s[42:43]
	global_load_dwordx4 v[140:143], v181, s[42:43]
	global_load_dwordx4 v[144:147], v178, s[44:45]
	global_load_dwordx4 v[148:151], v179, s[44:45]
	global_load_dwordx4 v[152:155], v180, s[44:45]
	global_load_dwordx4 v[156:159], v181, s[44:45]
	global_load_dwordx4 v[160:163], v182, s[44:45]
	global_load_dwordx4 v[164:167], v183, s[44:45]
	global_load_dwordx4 v[168:171], v184, s[44:45]
	global_load_dwordx4 v[172:175], v185, s[44:45]
	s_add_u32 s42, s42, 0x80
	s_addc_u32 s43, s43, 0
	s_add_u32 s44, s44, 0x80
	s_addc_u32 s45, s45, 0
	v_bfe_u32 v217, v197, 5, 2
	v_and_b32_e32 v218, 3, v198
	v_xor_b32_e32 v218, v218, v217
	v_lshlrev_b32_e32 v218, 4, v218
	v_lshl_or_b32 v177, v196, 6, v218
	v_lshrrev_b32_e32 v217, 2, v198
	v_lshlrev_b32_e32 v218, 6, v217
	v_xor_b32_e32 v177, v177, v218
	v_mul_u32_u24_e32 v217, 0x6000, v217
	v_add_u32_e32 v177, v177, v217
	v_and_b32_e32 v196, 31, v197
	v_bfe_u32 v198, v197, 5, 1
	v_bfe_u32 v217, v197, 2, 2
	v_xor_b32_e32 v218, v198, v217
	v_xor_b32_e32 v221, 2, v218
	v_lshrrev_b32_e32 v198, 7, v197
	v_lshl_or_b32 v198, v198, 6, v196
	v_lshlrev_b32_e32 v198, 6, v198
	v_lshl_or_b32 v186, v218, 4, v198
	v_lshl_or_b32 v187, v221, 4, v198
	v_bfe_u32 v198, v197, 6, 1
	v_mul_u32_u24_e32 v198, 128, v198
	v_add_u32_e32 v198, v198, v196
	v_lshlrev_b32_e32 v198, 6, v198
	v_add_u32_e32 v198, 0x2000, v198
	v_lshl_or_b32 v188, v218, 4, v198
	v_lshl_or_b32 v189, v221, 4, v198
	v_mov_b64_e32 v[0:1], 0
	v_mov_b64_e32 v[2:3], 0
	v_mov_b64_e32 v[4:5], 0
	v_mov_b64_e32 v[6:7], 0
	v_mov_b64_e32 v[8:9], 0
	v_mov_b64_e32 v[10:11], 0
	v_mov_b64_e32 v[12:13], 0
	v_mov_b64_e32 v[14:15], 0
	v_mov_b64_e32 v[16:17], 0
	v_mov_b64_e32 v[18:19], 0
	v_mov_b64_e32 v[20:21], 0
	v_mov_b64_e32 v[22:23], 0
	v_mov_b64_e32 v[24:25], 0
	v_mov_b64_e32 v[26:27], 0
	v_mov_b64_e32 v[28:29], 0
	v_mov_b64_e32 v[30:31], 0
	v_mov_b64_e32 v[32:33], 0
	v_mov_b64_e32 v[34:35], 0
	v_mov_b64_e32 v[36:37], 0
	v_mov_b64_e32 v[38:39], 0
	v_mov_b64_e32 v[40:41], 0
	v_mov_b64_e32 v[42:43], 0
	v_mov_b64_e32 v[44:45], 0
	v_mov_b64_e32 v[46:47], 0
	v_mov_b64_e32 v[48:49], 0
	v_mov_b64_e32 v[50:51], 0
	v_mov_b64_e32 v[52:53], 0
	v_mov_b64_e32 v[54:55], 0
	v_mov_b64_e32 v[56:57], 0
	v_mov_b64_e32 v[58:59], 0
	v_mov_b64_e32 v[60:61], 0
	v_mov_b64_e32 v[62:63], 0
	v_mov_b64_e32 v[64:65], 0
	v_mov_b64_e32 v[66:67], 0
	v_mov_b64_e32 v[68:69], 0
	v_mov_b64_e32 v[70:71], 0
	v_mov_b64_e32 v[72:73], 0
	v_mov_b64_e32 v[74:75], 0
	v_mov_b64_e32 v[76:77], 0
	v_mov_b64_e32 v[78:79], 0
	v_mov_b64_e32 v[80:81], 0
	v_mov_b64_e32 v[82:83], 0
	v_mov_b64_e32 v[84:85], 0
	v_mov_b64_e32 v[86:87], 0
	v_mov_b64_e32 v[88:89], 0
	v_mov_b64_e32 v[90:91], 0
	v_mov_b64_e32 v[92:93], 0
	v_mov_b64_e32 v[94:95], 0
	v_mov_b64_e32 v[96:97], 0
	v_mov_b64_e32 v[98:99], 0
	v_mov_b64_e32 v[100:101], 0
	v_mov_b64_e32 v[102:103], 0
	v_mov_b64_e32 v[104:105], 0
	v_mov_b64_e32 v[106:107], 0
	v_mov_b64_e32 v[108:109], 0
	v_mov_b64_e32 v[110:111], 0
	v_mov_b64_e32 v[112:113], 0
	v_mov_b64_e32 v[114:115], 0
	v_mov_b64_e32 v[116:117], 0
	v_mov_b64_e32 v[118:119], 0
	v_mov_b64_e32 v[120:121], 0
	v_mov_b64_e32 v[122:123], 0
	v_mov_b64_e32 v[124:125], 0
	v_mov_b64_e32 v[126:127], 0
	s_mov_b32 s36, 0
	s_mov_b32 s37, 0x6000
	s_mov_b32 s1, 0
	s_waitcnt vmcnt(11)
	ds_write_b128 v177, v[128:131]
	s_waitcnt vmcnt(10)
	ds_write_b128 v177, v[132:135] offset:2048
	s_waitcnt vmcnt(9)
	ds_write_b128 v177, v[136:139] offset:4096
	s_waitcnt vmcnt(8)
	ds_write_b128 v177, v[140:143] offset:6144
	s_waitcnt vmcnt(7)
	ds_write_b128 v177, v[144:147] offset:8192
	s_waitcnt vmcnt(6)
	ds_write_b128 v177, v[148:151] offset:10240
	s_waitcnt vmcnt(5)
	ds_write_b128 v177, v[152:155] offset:12288
	s_waitcnt vmcnt(4)
	ds_write_b128 v177, v[156:159] offset:14336
	s_waitcnt vmcnt(3)
	ds_write_b128 v177, v[160:163] offset:16384
	s_waitcnt vmcnt(2)
	ds_write_b128 v177, v[164:167] offset:18432
	s_waitcnt vmcnt(1)
	ds_write_b128 v177, v[168:171] offset:20480
	s_waitcnt vmcnt(0)
	ds_write_b128 v177, v[172:175] offset:22528
	v_subrev_u32_e32 v196, 0x6000, v177
	v_add_u32_e32 v198, 0xc000, v177
	v_min_u32_e32 v177, v196, v198
	s_waitcnt lgkmcnt(0)
	s_barrier
.Lg5_loop:
	v_add_u32_e32 v190, s36, v186
	v_add_u32_e32 v191, s36, v187
	v_add_u32_e32 v250, s36, v188
	v_add_u32_e32 v251, s36, v189
	ds_read_b128 v[200:203], v190
	ds_read_b128 v[204:207], v190 offset:2048
	ds_read_b128 v[222:225], v250
	ds_read_b128 v[226:229], v250 offset:2048
	ds_read_b128 v[230:233], v250 offset:4096
	ds_read_b128 v[234:237], v250 offset:6144
	s_setprio 1
	s_waitcnt lgkmcnt(3)
	v_mfma_f32_32x32x16_bf16 v[112:127], v[200:203], v[222:225], v[112:127]
	global_load_dwordx4 v[128:131], v178, s[42:43]
	ds_read_b128 v[208:211], v191
	v_mfma_f32_32x32x16_bf16 v[48:63], v[204:207], v[222:225], v[48:63]
	global_load_dwordx4 v[132:135], v179, s[42:43]
	ds_read_b128 v[212:215], v191 offset:2048
	s_waitcnt lgkmcnt(4)
	v_mfma_f32_32x32x16_bf16 v[96:111], v[200:203], v[226:229], v[96:111]
	global_load_dwordx4 v[136:139], v180, s[42:43]
	ds_read_b128 v[238:241], v251
	v_mfma_f32_32x32x16_bf16 v[32:47], v[204:207], v[226:229], v[32:47]
	global_load_dwordx4 v[140:143], v181, s[42:43]
	ds_read_b128 v[242:245], v251 offset:2048
	s_waitcnt lgkmcnt(5)
	v_mfma_f32_32x32x16_bf16 v[80:95], v[200:203], v[230:233], v[80:95]
	global_load_dwordx4 v[144:147], v178, s[44:45]
	ds_read_b128 v[246:249], v251 offset:4096
	v_mfma_f32_32x32x16_bf16 v[16:31], v[204:207], v[230:233], v[16:31]
	global_load_dwordx4 v[148:151], v179, s[44:45]
	ds_read_b128 v[192:195], v251 offset:6144
	s_waitcnt lgkmcnt(6)
	v_mfma_f32_32x32x16_bf16 v[64:79], v[200:203], v[234:237], v[64:79]
	global_load_dwordx4 v[152:155], v180, s[44:45]
	v_mfma_f32_32x32x16_bf16 v[0:15], v[204:207], v[234:237], v[0:15]
	global_load_dwordx4 v[156:159], v181, s[44:45]
	v_xad_u32 v190, v186, 64, s37
	v_xad_u32 v250, v188, 64, s37
	s_waitcnt lgkmcnt(3)
	v_mfma_f32_32x32x16_bf16 v[112:127], v[208:211], v[238:241], v[112:127]
	global_load_dwordx4 v[160:163], v182, s[44:45]
	ds_read_b128 v[200:203], v190
	v_mfma_f32_32x32x16_bf16 v[48:63], v[212:215], v[238:241], v[48:63]
	global_load_dwordx4 v[164:167], v183, s[44:45]
	ds_read_b128 v[204:207], v190 offset:2048
	s_waitcnt lgkmcnt(4)
	v_mfma_f32_32x32x16_bf16 v[96:111], v[208:211], v[242:245], v[96:111]
	global_load_dwordx4 v[168:171], v184, s[44:45]
	ds_read_b128 v[222:225], v250
	v_mfma_f32_32x32x16_bf16 v[32:47], v[212:215], v[242:245], v[32:47]
	global_load_dwordx4 v[172:175], v185, s[44:45]
	ds_read_b128 v[226:229], v250 offset:2048
	s_waitcnt lgkmcnt(5)
	v_mfma_f32_32x32x16_bf16 v[80:95], v[208:211], v[246:249], v[80:95]
	ds_read_b128 v[230:233], v250 offset:4096
	v_mfma_f32_32x32x16_bf16 v[16:31], v[212:215], v[246:249], v[16:31]
	ds_read_b128 v[234:237], v250 offset:6144
	s_waitcnt lgkmcnt(6)
	v_mfma_f32_32x32x16_bf16 v[64:79], v[208:211], v[192:195], v[64:79]
	v_mfma_f32_32x32x16_bf16 v[0:15], v[212:215], v[192:195], v[0:15]
	s_setprio 0
	s_barrier
	v_xad_u32 v191, v187, 64, s37
	v_xad_u32 v251, v189, 64, s37
	s_setprio 1
	s_waitcnt lgkmcnt(3)
	v_mfma_f32_32x32x16_bf16 v[112:127], v[200:203], v[222:225], v[112:127]
	ds_read_b128 v[208:211], v191
	v_mfma_f32_32x32x16_bf16 v[48:63], v[204:207], v[222:225], v[48:63]
	ds_read_b128 v[212:215], v191 offset:2048
	s_waitcnt lgkmcnt(4)
	v_mfma_f32_32x32x16_bf16 v[96:111], v[200:203], v[226:229], v[96:111]
	ds_read_b128 v[238:241], v251
	s_waitcnt vmcnt(11)
	ds_write_b128 v177, v[128:131]
	v_mfma_f32_32x32x16_bf16 v[32:47], v[204:207], v[226:229], v[32:47]
	ds_read_b128 v[242:245], v251 offset:2048
	s_waitcnt vmcnt(10)
	ds_write_b128 v177, v[132:135] offset:2048
	s_waitcnt lgkmcnt(7)
	v_mfma_f32_32x32x16_bf16 v[80:95], v[200:203], v[230:233], v[80:95]
	ds_read_b128 v[246:249], v251 offset:4096
	s_waitcnt vmcnt(9)
	ds_write_b128 v177, v[136:139] offset:4096
	v_mfma_f32_32x32x16_bf16 v[16:31], v[204:207], v[230:233], v[16:31]
	ds_read_b128 v[192:195], v251 offset:6144
	s_waitcnt vmcnt(8)
	ds_write_b128 v177, v[140:143] offset:6144
	s_waitcnt lgkmcnt(10)
	v_mfma_f32_32x32x16_bf16 v[64:79], v[200:203], v[234:237], v[64:79]
	s_waitcnt vmcnt(7)
	ds_write_b128 v177, v[144:147] offset:8192
	v_mfma_f32_32x32x16_bf16 v[0:15], v[204:207], v[234:237], v[0:15]
	s_waitcnt vmcnt(6)
	ds_write_b128 v177, v[148:151] offset:10240
	s_waitcnt lgkmcnt(9)
	v_mfma_f32_32x32x16_bf16 v[112:127], v[208:211], v[238:241], v[112:127]
	s_waitcnt vmcnt(5)
	ds_write_b128 v177, v[152:155] offset:12288
	v_mfma_f32_32x32x16_bf16 v[48:63], v[212:215], v[238:241], v[48:63]
	s_waitcnt vmcnt(4)
	ds_write_b128 v177, v[156:159] offset:14336
	s_waitcnt lgkmcnt(9)
	v_mfma_f32_32x32x16_bf16 v[96:111], v[208:211], v[242:245], v[96:111]
	s_waitcnt vmcnt(3)
	ds_write_b128 v177, v[160:163] offset:16384
	v_mfma_f32_32x32x16_bf16 v[32:47], v[212:215], v[242:245], v[32:47]
	s_waitcnt vmcnt(2)
	ds_write_b128 v177, v[164:167] offset:18432
	s_waitcnt lgkmcnt(9)
	v_mfma_f32_32x32x16_bf16 v[80:95], v[208:211], v[246:249], v[80:95]
	s_waitcnt vmcnt(1)
	ds_write_b128 v177, v[168:171] offset:20480
	v_mfma_f32_32x32x16_bf16 v[16:31], v[212:215], v[246:249], v[16:31]
	s_waitcnt vmcnt(0)
	ds_write_b128 v177, v[172:175] offset:22528
	s_waitcnt lgkmcnt(9)
	v_mfma_f32_32x32x16_bf16 v[64:79], v[208:211], v[192:195], v[64:79]
	v_mfma_f32_32x32x16_bf16 v[0:15], v[212:215], v[192:195], v[0:15]
	s_setprio 0
	s_add_u32 s42, s42, 0x80
	s_addc_u32 s43, s43, 0
	s_add_u32 s44, s44, 0x80
	s_addc_u32 s45, s45, 0
	s_sub_i32 s36, s36, 0x6000
	s_cmp_lt_i32 s36, 0
	s_cselect_b32 s38, 0x12000, 0
	s_add_i32 s36, s36, s38
	s_sub_i32 s37, s37, 0x6000
	s_cmp_lt_i32 s37, 0
	s_cselect_b32 s38, 0x12000, 0
	s_add_i32 s37, s37, s38
	v_subrev_u32_e32 v196, 0x6000, v177
	v_add_u32_e32 v198, 0xc000, v177
	v_min_u32_e32 v177, v196, v198
	s_add_i32 s1, s1, 1
	s_cmp_lt_u32 s1, 15
	s_waitcnt lgkmcnt(0)
	s_barrier
	s_cbranch_scc1 .Lg5_loop
	v_add_u32_e32 v190, s36, v186
	v_add_u32_e32 v191, s36, v187
	v_add_u32_e32 v250, s36, v188
	v_add_u32_e32 v251, s36, v189
	ds_read_b128 v[200:203], v190
	ds_read_b128 v[204:207], v190 offset:2048
	ds_read_b128 v[222:225], v250
	ds_read_b128 v[226:229], v250 offset:2048
	ds_read_b128 v[230:233], v250 offset:4096
	ds_read_b128 v[234:237], v250 offset:6144
	s_setprio 1
	s_waitcnt lgkmcnt(3)
	v_mfma_f32_32x32x16_bf16 v[112:127], v[200:203], v[222:225], v[112:127]
	ds_read_b128 v[208:211], v191
	v_mfma_f32_32x32x16_bf16 v[48:63], v[204:207], v[222:225], v[48:63]
	ds_read_b128 v[212:215], v191 offset:2048
	s_waitcnt lgkmcnt(4)
	v_mfma_f32_32x32x16_bf16 v[96:111], v[200:203], v[226:229], v[96:111]
	ds_read_b128 v[238:241], v251
	v_mfma_f32_32x32x16_bf16 v[32:47], v[204:207], v[226:229], v[32:47]
	ds_read_b128 v[242:245], v251 offset:2048
	s_waitcnt lgkmcnt(5)
	v_mfma_f32_32x32x16_bf16 v[80:95], v[200:203], v[230:233], v[80:95]
	ds_read_b128 v[246:249], v251 offset:4096
	v_mfma_f32_32x32x16_bf16 v[16:31], v[204:207], v[230:233], v[16:31]
	ds_read_b128 v[192:195], v251 offset:6144
	s_waitcnt lgkmcnt(6)
	v_mfma_f32_32x32x16_bf16 v[64:79], v[200:203], v[234:237], v[64:79]
	v_mfma_f32_32x32x16_bf16 v[0:15], v[204:207], v[234:237], v[0:15]
	v_xad_u32 v190, v186, 64, s37
	v_xad_u32 v250, v188, 64, s37
	s_waitcnt lgkmcnt(3)
	v_mfma_f32_32x32x16_bf16 v[112:127], v[208:211], v[238:241], v[112:127]
	ds_read_b128 v[200:203], v190
	v_mfma_f32_32x32x16_bf16 v[48:63], v[212:215], v[238:241], v[48:63]
	ds_read_b128 v[204:207], v190 offset:2048
	s_waitcnt lgkmcnt(4)
	v_mfma_f32_32x32x16_bf16 v[96:111], v[208:211], v[242:245], v[96:111]
	ds_read_b128 v[222:225], v250
	v_mfma_f32_32x32x16_bf16 v[32:47], v[212:215], v[242:245], v[32:47]
	ds_read_b128 v[226:229], v250 offset:2048
	s_waitcnt lgkmcnt(5)
	v_mfma_f32_32x32x16_bf16 v[80:95], v[208:211], v[246:249], v[80:95]
	ds_read_b128 v[230:233], v250 offset:4096
	v_mfma_f32_32x32x16_bf16 v[16:31], v[212:215], v[246:249], v[16:31]
	ds_read_b128 v[234:237], v250 offset:6144
	s_waitcnt lgkmcnt(6)
	v_mfma_f32_32x32x16_bf16 v[64:79], v[208:211], v[192:195], v[64:79]
	v_mfma_f32_32x32x16_bf16 v[0:15], v[212:215], v[192:195], v[0:15]
	s_setprio 0
	v_xad_u32 v191, v187, 64, s37
	v_xad_u32 v251, v189, 64, s37
	s_setprio 1
	s_waitcnt lgkmcnt(3)
	v_mfma_f32_32x32x16_bf16 v[112:127], v[200:203], v[222:225], v[112:127]
	ds_read_b128 v[208:211], v191
	v_mfma_f32_32x32x16_bf16 v[48:63], v[204:207], v[222:225], v[48:63]
	ds_read_b128 v[212:215], v191 offset:2048
	s_waitcnt lgkmcnt(4)
	v_mfma_f32_32x32x16_bf16 v[96:111], v[200:203], v[226:229], v[96:111]
	ds_read_b128 v[238:241], v251
	v_mfma_f32_32x32x16_bf16 v[32:47], v[204:207], v[226:229], v[32:47]
	ds_read_b128 v[242:245], v251 offset:2048
	s_waitcnt lgkmcnt(5)
	v_mfma_f32_32x32x16_bf16 v[80:95], v[200:203], v[230:233], v[80:95]
	ds_read_b128 v[246:249], v251 offset:4096
	v_mfma_f32_32x32x16_bf16 v[16:31], v[204:207], v[230:233], v[16:31]
	ds_read_b128 v[192:195], v251 offset:6144
	s_waitcnt lgkmcnt(6)
	v_mfma_f32_32x32x16_bf16 v[64:79], v[200:203], v[234:237], v[64:79]
	v_mfma_f32_32x32x16_bf16 v[0:15], v[204:207], v[234:237], v[0:15]
	s_waitcnt lgkmcnt(3)
	v_mfma_f32_32x32x16_bf16 v[112:127], v[208:211], v[238:241], v[112:127]
	v_mfma_f32_32x32x16_bf16 v[48:63], v[212:215], v[238:241], v[48:63]
	s_waitcnt lgkmcnt(2)
	v_mfma_f32_32x32x16_bf16 v[96:111], v[208:211], v[242:245], v[96:111]
	v_mfma_f32_32x32x16_bf16 v[32:47], v[212:215], v[242:245], v[32:47]
	s_waitcnt lgkmcnt(1)
	v_mfma_f32_32x32x16_bf16 v[80:95], v[208:211], v[246:249], v[80:95]
	v_mfma_f32_32x32x16_bf16 v[16:31], v[212:215], v[246:249], v[16:31]
	s_waitcnt lgkmcnt(0)
	v_mfma_f32_32x32x16_bf16 v[64:79], v[208:211], v[192:195], v[64:79]
	v_mfma_f32_32x32x16_bf16 v[0:15], v[212:215], v[192:195], v[0:15]
	s_setprio 0
	s_nop 7
	s_nop 7
	s_branch .LBB0_482

.LBB0_569:
	s_or_b64 exec, exec, s[48:49]
	s_lshl_b32 s0, s9, 7
	s_add_u32 s1, s66, s8
	s_addc_u32 s8, s67, 0
	s_lshl_b32 s9, s0, 1
	s_add_u32 s46, s1, s9
	s_addc_u32 s47, s8, 0
	s_or_b32 s68, s0, s68
	s_lshl_b32 s0, s7, 2
	s_add_i32 s37, s0, 0
	s_add_i32 s37, s37, 0x12200
	s_lshl_b32 s0, s6, 2
	v_readlane_b32 s1, v254, 5
	s_add_u32 s26, s1, s0
	v_readlane_b32 s0, v254, 6
	s_addc_u32 s27, s0, 0
	v_mov_b32_e32 v134, v130
	s_add_u32 s28, s46, s28
	s_waitcnt lgkmcnt(0)
	s_barrier
	s_addc_u32 s29, s47, s29
	v_ashrrev_i32_e32 v135, 31, v134
	v_lshl_add_u64 v[134:135], v[134:135], 1, s[28:29]
	global_load_ushort v190, v[134:135], off offset:64
	s_waitcnt vmcnt(8)
	v_lshlrev_b32_e32 v147, 16, v166
	v_add_co_u32_e64 v144, s[0:1], s96, v134
	v_lshlrev_b32_e32 v187, 16, v165
	s_nop 0
	v_addc_co_u32_e64 v145, s[0:1], 0, v135, s[0:1]
	v_lshlrev_b32_e32 v186, 16, v164
	v_lshlrev_b32_e32 v185, 16, v163
	v_lshlrev_b32_e32 v184, 16, v162
	v_lshlrev_b32_e32 v175, 16, v159
	v_lshlrev_b32_e32 v183, 16, v161
	v_lshlrev_b32_e32 v182, 16, v160
	s_waitcnt vmcnt(7)
	v_lshlrev_b32_e32 v146, 16, v167
	v_mov_b32_e32 v167, v158
	s_waitcnt vmcnt(6)
	v_lshlrev_b32_e32 v142, 16, v168
	s_waitcnt vmcnt(5)
	v_lshlrev_b32_e32 v140, 16, v169
	s_waitcnt vmcnt(4)
	v_lshlrev_b32_e32 v139, 16, v170
	s_waitcnt vmcnt(3)
	v_lshlrev_b32_e32 v136, 16, v171
	v_lshlrev_b32_e32 v174, 16, v131
	s_waitcnt vmcnt(1)
	v_lshlrev_b32_e32 v129, 16, v173
	v_lshlrev_b32_e32 v131, 16, v172
	s_waitcnt vmcnt(1)
	global_load_ushort v165, v[134:135], off offset:2112
	s_waitcnt vmcnt(2)
	global_load_ushort v164, v[144:145], off offset:64
	s_waitcnt vmcnt(3)
	global_load_ushort v163, v[144:145], off offset:2112
	v_add_co_u32_e64 v144, s[0:1], s94, v134
	s_waitcnt vmcnt(4)
	v_addc_co_u32_e64 v145, s[0:1], 0, v135, s[0:1]
	global_load_ushort v162, v[144:145], off offset:64
	s_waitcnt vmcnt(5)
	global_load_ushort v159, v[144:145], off offset:2112
	v_add_co_u32_e64 v144, s[0:1], s57, v134
	s_waitcnt vmcnt(6)
	v_addc_co_u32_e64 v145, s[0:1], 0, v135, s[0:1]
	global_load_ushort v161, v[144:145], off offset:64
	s_waitcnt vmcnt(7)
	global_load_ushort v160, v[144:145], off offset:2112
	v_add_co_u32_e64 v144, s[0:1], s35, v134
	s_waitcnt vmcnt(8)
	v_addc_co_u32_e64 v145, s[0:1], 0, v135, s[0:1]
	global_load_ushort v150, v[144:145], off offset:64
	v_add_co_u32_e64 v148, s[0:1], s58, v134
	s_waitcnt vmcnt(9)
	global_load_ushort v144, v[144:145], off offset:2112
	v_addc_co_u32_e64 v149, s[0:1], 0, v135, s[0:1]
	s_waitcnt vmcnt(10)
	global_load_ushort v151, v[148:149], off offset:64
	s_waitcnt vmcnt(11)
	global_load_ushort v145, v[148:149], off offset:2112
	v_add_co_u32_e64 v148, s[0:1], s95, v134
	s_waitcnt vmcnt(12)
	v_addc_co_u32_e64 v149, s[0:1], 0, v135, s[0:1]
	v_add_co_u32_e64 v134, s[0:1], s59, v134
	global_load_ushort v143, v[148:149], off offset:64
	s_nop 0
	v_addc_co_u32_e64 v135, s[0:1], 0, v135, s[0:1]
	global_load_ushort v141, v[134:135], off offset:64
	s_waitcnt vmcnt(14)
	global_load_ushort v189, v[134:135], off offset:2112
	s_waitcnt vmcnt(15)
	global_load_ushort v137, v[148:149], off offset:2112
	s_waitcnt vmcnt(16)
	v_mov_b32_e32 v134, v128
	s_waitcnt vmcnt(16)
	v_add_u32_e32 v134, s68, v134
	v_ashrrev_i32_e32 v135, 31, v134
	v_lshl_add_u64 v[148:149], v[134:135], 2, s[50:51]
	global_load_dword v240, v[148:149], off
	global_load_dword v241, v[148:149], off offset:128
	global_load_dword v242, v[148:149], off offset:256
	global_load_dword v243, v[148:149], off offset:384
	v_lshl_add_u32 v148, v167, 2, s36
	v_lshl_add_u32 v167, v167, 4, s37
	ds_read_b128 v[168:171], v167
	ds_read_b128 v[178:181], v167 offset:32
	v_ashrrev_i32_e32 v149, 31, v148
	v_lshlrev_b64 v[148:149], 11, v[148:149]
	v_lshl_add_u64 v[148:149], s[66:67], 0, v[148:149]
	s_waitcnt lgkmcnt(1)
	v_mul_f32_e32 v112, v112, v168
	v_lshl_add_u64 v[134:135], v[134:135], 1, v[148:149]
	s_waitcnt vmcnt(20)
	s_waitcnt vmcnt(3)
	v_fmac_f32_e32 v174, v240, v112
	v_cvt_pk_bf16_f32 v112, v174, s0
	v_lshlrev_b32_e32 v177, 16, v112
	global_store_short v[134:135], v112, off
	v_mul_f32_e32 v112, v113, v169
	v_fmac_f32_e32 v175, v240, v112
	v_cvt_pk_bf16_f32 v112, v175, s0
	v_lshlrev_b32_e32 v176, 16, v112
	global_store_short v[134:135], v112, off offset:2048
	v_mul_f32_e32 v112, v114, v170
	v_fmac_f32_e32 v182, v240, v112
	v_cvt_pk_bf16_f32 v114, v182, s0
	v_add_co_u32_e64 v112, s[0:1], s96, v134
	v_lshlrev_b32_e32 v175, 16, v114
	s_nop 0
	v_addc_co_u32_e64 v113, s[0:1], 0, v135, s[0:1]
	global_store_short v[112:113], v114, off
	v_mul_f32_e32 v114, v115, v171
	v_fmac_f32_e32 v183, v240, v114
	v_cvt_pk_bf16_f32 v114, v183, s0
	global_store_short v[112:113], v114, off offset:2048
	s_waitcnt lgkmcnt(0)
	v_mul_f32_e32 v112, v116, v178
	v_fmac_f32_e32 v184, v240, v112
	v_cvt_pk_bf16_f32 v116, v184, s0
	v_add_co_u32_e64 v112, s[0:1], s94, v134
	v_lshlrev_b32_e32 v174, 16, v114
	s_nop 0
	v_addc_co_u32_e64 v113, s[0:1], 0, v135, s[0:1]
	v_add_co_u32_e64 v114, s[0:1], s57, v134
	v_lshlrev_b32_e32 v173, 16, v116
	s_nop 0
	v_addc_co_u32_e64 v115, s[0:1], 0, v135, s[0:1]
	global_store_short v[114:115], v116, off offset:-4096
	v_mul_f32_e32 v116, v117, v179
	v_fmac_f32_e32 v185, v240, v116
	v_cvt_pk_bf16_f32 v117, v185, s0
	global_store_short v[112:113], v117, off offset:2048
	v_mul_f32_e32 v112, v118, v180
	v_fmac_f32_e32 v186, v240, v112
	v_cvt_pk_bf16_f32 v112, v186, s0
	v_lshlrev_b32_e32 v172, 16, v112
	global_store_short v[114:115], v112, off
	v_mul_f32_e32 v112, v119, v181
	v_fmac_f32_e32 v187, v240, v112
	v_cvt_pk_bf16_f32 v112, v187, s0
	v_lshlrev_b32_e32 v116, 16, v117
	v_lshlrev_b32_e32 v117, 16, v112
	global_store_short v[114:115], v112, off offset:2048
	ds_read_b128 v[112:115], v167 offset:64
	s_waitcnt lgkmcnt(0)
	v_mul_f32_e32 v112, v120, v112
	v_fmac_f32_e32 v147, v240, v112
	v_cvt_pk_bf16_f32 v112, v147, s0
	v_add_co_u32_e64 v118, s[0:1], s35, v134
	v_lshlrev_b32_e32 v170, 16, v112
	s_nop 0
	v_addc_co_u32_e64 v119, s[0:1], 0, v135, s[0:1]
	v_add_co_u32_e64 v148, s[0:1], s58, v134
	s_nop 1
	v_addc_co_u32_e64 v149, s[0:1], 0, v135, s[0:1]
	global_store_short v[148:149], v112, off offset:-4096
	v_mul_f32_e32 v112, v121, v113
	v_fmac_f32_e32 v146, v240, v112
	v_cvt_pk_bf16_f32 v112, v146, s0
	v_lshlrev_b32_e32 v171, 16, v112
	global_store_short v[118:119], v112, off offset:2048
	v_mul_f32_e32 v112, v122, v114
	v_fmac_f32_e32 v142, v240, v112
	v_cvt_pk_bf16_f32 v112, v142, s0
	v_lshlrev_b32_e32 v169, 16, v112
	global_store_short v[148:149], v112, off
	v_mul_f32_e32 v112, v123, v115
	v_fmac_f32_e32 v140, v240, v112
	v_cvt_pk_bf16_f32 v112, v140, s0
	v_lshlrev_b32_e32 v168, 16, v112
	global_store_short v[148:149], v112, off offset:2048
	ds_read_b128 v[112:115], v167 offset:96
	s_waitcnt lgkmcnt(0)
	v_mul_f32_e32 v112, v124, v112
	v_fmac_f32_e32 v139, v240, v112
	v_cvt_pk_bf16_f32 v112, v139, s0
	v_add_co_u32_e64 v118, s[0:1], s95, v134
	v_lshlrev_b32_e32 v167, 16, v112
	s_nop 0
	v_addc_co_u32_e64 v119, s[0:1], 0, v135, s[0:1]
	v_add_co_u32_e64 v120, s[0:1], s59, v134
	s_nop 1
	v_addc_co_u32_e64 v121, s[0:1], 0, v135, s[0:1]
	global_store_short v[120:121], v112, off offset:-4096
	v_mul_f32_e32 v112, v125, v113
	v_fmac_f32_e32 v136, v240, v112
	v_cvt_pk_bf16_f32 v112, v136, s0
	v_lshlrev_b32_e32 v124, 16, v112
	global_store_short v[118:119], v112, off offset:2048
	v_mul_f32_e32 v112, v126, v114
	v_fmac_f32_e32 v131, v240, v112
	v_cvt_pk_bf16_f32 v112, v131, s0
	v_lshlrev_b32_e32 v123, 16, v112
	global_store_short v[120:121], v112, off
	v_mul_f32_e32 v112, v127, v115
	v_fmac_f32_e32 v129, v240, v112
	v_cvt_pk_bf16_f32 v112, v129, s0
	v_lshlrev_b32_e32 v122, 16, v112
	global_store_short v[120:121], v112, off offset:2048
	v_mov_b32_e32 v112, v130
	v_mov_b32_e32 v127, v158
	v_ashrrev_i32_e32 v113, 31, v112
	v_lshl_add_u64 v[112:113], v[112:113], 1, s[28:29]
	global_load_ushort v149, v[112:113], off offset:128
	s_waitcnt vmcnt(37)
	global_load_ushort v147, v[112:113], off offset:2176
	s_waitcnt vmcnt(38)
	v_add_co_u32_e64 v114, s[0:1], s96, v112
	s_nop 1
	v_addc_co_u32_e64 v115, s[0:1], 0, v113, s[0:1]
	global_load_ushort v148, v[114:115], off offset:128
	s_waitcnt vmcnt(39)
	global_load_ushort v139, v[114:115], off offset:2176
	s_waitcnt vmcnt(40)
	v_add_co_u32_e64 v114, s[0:1], s94, v112
	s_nop 1
	v_addc_co_u32_e64 v115, s[0:1], 0, v113, s[0:1]
	global_load_ushort v142, v[114:115], off offset:128
	s_waitcnt vmcnt(41)
	global_load_ushort v136, v[114:115], off offset:2176
	s_waitcnt vmcnt(42)
	v_add_co_u32_e64 v114, s[0:1], s57, v112
	s_nop 1
	v_addc_co_u32_e64 v115, s[0:1], 0, v113, s[0:1]
	global_load_ushort v146, v[114:115], off offset:128
	s_waitcnt vmcnt(43)
	global_load_ushort v140, v[114:115], off offset:2176
	s_waitcnt vmcnt(44)
	v_add_co_u32_e64 v114, s[0:1], s35, v112
	s_nop 1
	v_addc_co_u32_e64 v115, s[0:1], 0, v113, s[0:1]
	global_load_ushort v129, v[114:115], off offset:128
	s_waitcnt vmcnt(45)
	global_load_ushort v125, v[114:115], off offset:2176
	s_waitcnt vmcnt(46)
	v_add_co_u32_e64 v114, s[0:1], s58, v112
	s_nop 1
	v_addc_co_u32_e64 v115, s[0:1], 0, v113, s[0:1]
	global_load_ushort v135, v[114:115], off offset:128
	s_waitcnt vmcnt(47)
	global_load_ushort v131, v[114:115], off offset:2176
	s_waitcnt vmcnt(48)
	v_add_co_u32_e64 v114, s[0:1], s95, v112
	s_nop 1
	v_addc_co_u32_e64 v115, s[0:1], 0, v113, s[0:1]
	global_load_ushort v120, v[114:115], off offset:128
	v_add_co_u32_e64 v112, s[0:1], s59, v112
	global_load_ushort v118, v[114:115], off offset:2176
	s_nop 0
	v_addc_co_u32_e64 v113, s[0:1], 0, v113, s[0:1]
	s_waitcnt vmcnt(50)
	s_waitcnt vmcnt(1)
	global_load_ushort v121, v[112:113], off offset:128
	s_waitcnt vmcnt(2)
	global_load_ushort v119, v[112:113], off offset:2176
	s_waitcnt vmcnt(3)
	v_mov_b32_e32 v112, v128
	s_nop 0
	v_ashrrev_i32_e32 v113, 31, v112
	v_lshl_add_u64 v[112:113], v[112:113], 0, s[68:69]
	v_lshl_add_u64 v[114:115], v[112:113], 2, s[50:51]
	v_lshl_add_u32 v114, v127, 2, s36
	v_lshl_add_u32 v127, v127, 4, s37
	ds_read_b128 v[178:181], v127
	ds_read_b128 v[182:185], v127 offset:32
	v_ashrrev_i32_e32 v115, 31, v114
	v_lshlrev_b64 v[114:115], 11, v[114:115]
	v_lshl_add_u64 v[114:115], s[66:67], 0, v[114:115]
	s_waitcnt lgkmcnt(1)
	v_mul_f32_e32 v96, v96, v178
	v_lshl_add_u64 v[112:113], v[112:113], 1, v[114:115]
	v_mul_f32_e32 v99, v99, v181
	s_waitcnt lgkmcnt(0)
	v_mul_f32_e32 v101, v101, v183
	s_waitcnt vmcnt(3)
	s_waitcnt vmcnt(34)
	s_waitcnt vmcnt(51)
	v_lshlrev_b32_e32 v166, 16, v190
	v_fmac_f32_e32 v166, v241, v96
	v_cvt_pk_bf16_f32 v96, v166, s0
	v_lshlrev_b32_e32 v114, 16, v96
	global_store_short v[112:113], v96, off offset:64
	v_mul_f32_e32 v96, v97, v179
	s_waitcnt vmcnt(51)
	v_lshlrev_b32_e32 v165, 16, v165
	v_fmac_f32_e32 v165, v241, v96
	v_cvt_pk_bf16_f32 v96, v165, s0
	v_lshlrev_b32_e32 v97, 16, v96
	global_store_short v[112:113], v96, off offset:2112
	v_mul_f32_e32 v96, v98, v180
	s_waitcnt vmcnt(51)
	v_lshlrev_b32_e32 v164, 16, v164
	v_fmac_f32_e32 v164, v241, v96
	v_cvt_pk_bf16_f32 v98, v164, s0
	v_add_co_u32_e64 v96, s[0:1], s96, v112
	v_mul_f32_e32 v115, v97, v97
	s_nop 0
	v_addc_co_u32_e64 v97, s[0:1], 0, v113, s[0:1]
	s_waitcnt vmcnt(50)
	v_lshlrev_b32_e32 v163, 16, v163
	v_fmac_f32_e32 v163, v241, v99
	s_nop 0
	v_cvt_pk_bf16_f32 v99, v163, s0
	global_store_short v[96:97], v98, off offset:64
	global_store_short v[96:97], v99, off offset:2112
	v_mul_f32_e32 v96, v100, v182
	s_waitcnt vmcnt(51)
	v_lshlrev_b32_e32 v162, 16, v162
	v_fmac_f32_e32 v162, v241, v96
	v_cvt_pk_bf16_f32 v100, v162, s0
	v_add_co_u32_e64 v96, s[0:1], s94, v112
	s_waitcnt vmcnt(50)
	v_lshlrev_b32_e32 v159, 16, v159
	v_fmac_f32_e32 v159, v241, v101
	s_nop 0
	v_addc_co_u32_e64 v97, s[0:1], 0, v113, s[0:1]
	v_lshlrev_b32_e32 v134, 16, v98
	s_nop 0
	v_cvt_pk_bf16_f32 v101, v159, s0
	v_mul_f32_e32 v98, v134, v134
	v_lshlrev_b32_e32 v134, 16, v99
	global_store_short v[96:97], v100, off offset:64
	global_store_short v[96:97], v101, off offset:2112
	v_mul_f32_e32 v96, v102, v184
	v_mul_f32_e32 v99, v134, v134
	v_lshlrev_b32_e32 v134, 16, v100
	s_waitcnt vmcnt(51)
	v_lshlrev_b32_e32 v161, 16, v161
	v_fmac_f32_e32 v161, v241, v96
	v_mul_f32_e32 v100, v134, v134
	v_lshlrev_b32_e32 v134, 16, v101
	v_cvt_pk_bf16_f32 v102, v161, s0
	v_add_co_u32_e64 v96, s[0:1], s57, v112
	v_mul_f32_e32 v101, v134, v134
	s_nop 0
	v_addc_co_u32_e64 v97, s[0:1], 0, v113, s[0:1]
	v_fmac_f32_e32 v101, v116, v116
	v_lshlrev_b32_e32 v116, 16, v102
	global_store_short v[96:97], v102, off offset:64
	v_mul_f32_e32 v102, v103, v185
	s_waitcnt vmcnt(51)
	v_lshlrev_b32_e32 v160, 16, v160
	v_fmac_f32_e32 v160, v241, v102
	v_cvt_pk_bf16_f32 v102, v160, s0
	ds_read_b128 v[160:163], v127 offset:64
	global_store_short v[96:97], v102, off offset:2112
	v_lshlrev_b32_e32 v103, 16, v102
	v_mul_f32_e32 v102, v103, v103
	v_fmac_f32_e32 v102, v117, v117
	s_waitcnt lgkmcnt(0)
	v_mul_f32_e32 v96, v104, v160
	s_waitcnt vmcnt(51)
	v_lshlrev_b32_e32 v150, 16, v150
	v_fmac_f32_e32 v150, v241, v96
	v_cvt_pk_bf16_f32 v103, v150, s0
	v_add_co_u32_e64 v96, s[0:1], s35, v112
	v_lshlrev_b32_e32 v104, 16, v103
	s_nop 0
	v_addc_co_u32_e64 v97, s[0:1], 0, v113, s[0:1]
	global_store_short v[96:97], v103, off offset:64
	v_mul_f32_e32 v103, v105, v161
	s_waitcnt vmcnt(51)
	v_lshlrev_b32_e32 v144, 16, v144
	v_fmac_f32_e32 v144, v241, v103
	v_cvt_pk_bf16_f32 v103, v144, s0
	global_store_short v[96:97], v103, off offset:2112
	v_mul_f32_e32 v96, v106, v162
	s_waitcnt vmcnt(51)
	v_lshlrev_b32_e32 v151, 16, v151
	v_fmac_f32_e32 v151, v241, v96
	v_mul_f32_e32 v117, v104, v104
	v_lshlrev_b32_e32 v104, 16, v103
	v_cvt_pk_bf16_f32 v103, v151, s0
	v_add_co_u32_e64 v96, s[0:1], s58, v112
	v_mul_f32_e32 v105, v104, v104
	s_nop 0
	v_addc_co_u32_e64 v97, s[0:1], 0, v113, s[0:1]
	v_lshlrev_b32_e32 v104, 16, v103
	global_store_short v[96:97], v103, off offset:64
	v_mul_f32_e32 v103, v107, v163
	ds_read_b128 v[160:163], v127 offset:96
	s_waitcnt vmcnt(51)
	v_lshlrev_b32_e32 v145, 16, v145
	v_fmac_f32_e32 v145, v241, v103
	v_cvt_pk_bf16_f32 v103, v145, s0
	global_store_short v[96:97], v103, off offset:2112
	v_lshlrev_b32_e32 v106, 16, v103
	s_waitcnt lgkmcnt(0)
	v_mul_f32_e32 v96, v108, v160
	s_waitcnt vmcnt(51)
	v_lshlrev_b32_e32 v143, 16, v143
	v_fmac_f32_e32 v143, v241, v96
	v_mul_f32_e32 v103, v106, v106
	v_cvt_pk_bf16_f32 v106, v143, s0
	v_add_co_u32_e64 v96, s[0:1], s95, v112
	v_lshlrev_b32_e32 v107, 16, v106
	s_nop 0
	v_addc_co_u32_e64 v97, s[0:1], 0, v113, s[0:1]
	global_store_short v[96:97], v106, off offset:64
	v_mul_f32_e32 v106, v107, v107
	v_mul_f32_e32 v107, v109, v161
	s_waitcnt vmcnt(49)
	v_lshlrev_b32_e32 v137, 16, v137
	v_fmac_f32_e32 v137, v241, v107
	v_cvt_pk_bf16_f32 v107, v137, s0
	global_store_short v[96:97], v107, off offset:2112
	v_mul_f32_e32 v96, v110, v162
	v_lshlrev_b32_e32 v108, 16, v107
	s_waitcnt vmcnt(52)
	v_lshlrev_b32_e32 v141, 16, v141
	v_fmac_f32_e32 v141, v241, v96
	v_mul_f32_e32 v107, v108, v108
	v_cvt_pk_bf16_f32 v108, v141, s0
	v_add_co_u32_e64 v96, s[0:1], s59, v112
	v_lshlrev_b32_e32 v109, 16, v108
	s_nop 0
	v_addc_co_u32_e64 v97, s[0:1], 0, v113, s[0:1]
	global_store_short v[96:97], v108, off offset:64
	v_mul_f32_e32 v108, v109, v109
	v_mul_f32_e32 v109, v111, v163
	s_waitcnt vmcnt(52)
	v_lshlrev_b32_e32 v138, 16, v189
	v_fmac_f32_e32 v138, v241, v109
	v_cvt_pk_bf16_f32 v109, v138, s0
	global_store_short v[96:97], v109, off offset:2112
	v_mov_b32_e32 v96, v130
	v_lshlrev_b32_e32 v110, 16, v109
	v_ashrrev_i32_e32 v97, 31, v96
	v_lshl_add_u64 v[96:97], v[96:97], 1, s[28:29]
	v_mul_f32_e32 v109, v110, v110
	global_load_ushort v190, v[96:97], off offset:192
	v_fmac_f32_e32 v108, v123, v123
	v_fmac_f32_e32 v109, v122, v122
	v_fmac_f32_e32 v107, v124, v124
	v_mov_b32_e32 v159, v158
	v_fmac_f32_e32 v106, v167, v167
	v_fmac_f32_e32 v115, v176, v176
	v_fmac_f32_e32 v99, v174, v174
	v_fmac_f32_e32 v100, v173, v173
	v_mul_f32_e32 v116, v116, v116
	v_fmac_f32_e32 v116, v172, v172
	v_fmac_f32_e32 v105, v171, v171
	v_fmac_f32_e32 v103, v168, v168
	v_mul_f32_e32 v104, v104, v104
	v_fmac_f32_e32 v104, v169, v169
	v_fmac_f32_e32 v117, v170, v170
	s_or_b32 s28, s36, 32
	s_ashr_i32 s29, s28, 31
	v_mul_f32_e32 v114, v114, v114
	v_fmac_f32_e32 v114, v177, v177
	v_fmac_f32_e32 v98, v175, v175
	s_waitcnt vmcnt(17)
	global_load_ushort v122, v[96:97], off offset:2240
	s_waitcnt vmcnt(18)
	v_add_co_u32_e64 v110, s[0:1], s96, v96
	s_nop 1
	v_addc_co_u32_e64 v111, s[0:1], 0, v97, s[0:1]
	global_load_ushort v126, v[110:111], off offset:192
	s_waitcnt vmcnt(19)
	global_load_ushort v124, v[110:111], off offset:2240
	s_waitcnt vmcnt(20)
	v_add_co_u32_e64 v110, s[0:1], s94, v96
	s_nop 1
	v_addc_co_u32_e64 v111, s[0:1], 0, v97, s[0:1]
	global_load_ushort v134, v[110:111], off offset:192
	s_waitcnt vmcnt(21)
	global_load_ushort v127, v[110:111], off offset:2240
	s_waitcnt vmcnt(22)
	v_add_co_u32_e64 v110, s[0:1], s57, v96
	s_nop 1
	v_addc_co_u32_e64 v111, s[0:1], 0, v97, s[0:1]
	global_load_ushort v145, v[110:111], off offset:192
	s_waitcnt vmcnt(23)
	global_load_ushort v143, v[110:111], off offset:2240
	s_waitcnt vmcnt(24)
	v_add_co_u32_e64 v110, s[0:1], s35, v96
	s_nop 1
	v_addc_co_u32_e64 v111, s[0:1], 0, v97, s[0:1]
	global_load_ushort v138, v[110:111], off offset:192
	s_waitcnt vmcnt(25)
	global_load_ushort v137, v[110:111], off offset:2240
	s_waitcnt vmcnt(26)
	v_add_co_u32_e64 v110, s[0:1], s58, v96
	s_nop 1
	v_addc_co_u32_e64 v111, s[0:1], 0, v97, s[0:1]
	global_load_ushort v144, v[110:111], off offset:192
	s_waitcnt vmcnt(27)
	global_load_ushort v141, v[110:111], off offset:2240
	v_add_co_u32_e64 v112, s[0:1], s95, v96
	s_waitcnt vmcnt(28)
	v_addc_co_u32_e64 v113, s[0:1], 0, v97, s[0:1]
	global_load_ushort v111, v[112:113], off offset:192
	v_add_co_u32_e64 v96, s[0:1], s59, v96
	s_waitcnt vmcnt(29)
	v_addc_co_u32_e64 v97, s[0:1], 0, v97, s[0:1]
	global_load_ushort v110, v[112:113], off offset:2240
	s_waitcnt vmcnt(30)
	global_load_ushort v113, v[96:97], off offset:192
	s_waitcnt vmcnt(31)
	global_load_ushort v112, v[96:97], off offset:2240
	s_waitcnt vmcnt(32)
	v_mov_b32_e32 v96, v128
	s_nop 0
	v_ashrrev_i32_e32 v97, 31, v96
	v_lshl_add_u64 v[96:97], v[96:97], 0, s[68:69]
	v_lshl_add_u64 v[150:151], v[96:97], 2, s[50:51]
	v_lshl_add_u32 v160, v159, 2, s36
	v_ashrrev_i32_e32 v161, 31, v160
	v_lshlrev_b64 v[160:161], 11, v[160:161]
	v_lshl_add_u64 v[160:161], s[66:67], 0, v[160:161]
	v_lshl_add_u32 v151, v159, 4, s37
	v_lshl_add_u64 v[96:97], v[96:97], 1, v[160:161]
	ds_read_b128 v[160:163], v151
	ds_read_b128 v[164:167], v151 offset:32
	s_waitcnt lgkmcnt(1)
	v_mul_f32_e32 v80, v80, v160
	s_waitcnt vmcnt(32)
	s_waitcnt vmcnt(47)
	v_lshlrev_b32_e32 v149, 16, v149
	v_fmac_f32_e32 v149, v242, v80
	v_cvt_pk_bf16_f32 v80, v149, s0
	v_lshlrev_b32_e32 v149, 16, v80
	global_store_short v[96:97], v80, off offset:128
	v_mul_f32_e32 v80, v81, v161
	s_waitcnt vmcnt(47)
	v_lshlrev_b32_e32 v147, 16, v147
	v_fmac_f32_e32 v147, v242, v80
	v_cvt_pk_bf16_f32 v80, v147, s0
	v_lshlrev_b32_e32 v81, 16, v80
	global_store_short v[96:97], v80, off offset:2176
	v_mul_f32_e32 v80, v82, v162
	s_waitcnt vmcnt(47)
	v_lshlrev_b32_e32 v148, 16, v148
	v_fmac_f32_e32 v148, v242, v80
	v_cvt_pk_bf16_f32 v82, v148, s0
	v_add_co_u32_e64 v80, s[0:1], s96, v96
	v_fmac_f32_e32 v115, v81, v81
	s_nop 0
	v_addc_co_u32_e64 v81, s[0:1], 0, v97, s[0:1]
	v_lshlrev_b32_e32 v147, 16, v82
	global_store_short v[80:81], v82, off offset:128
	v_mul_f32_e32 v82, v83, v163
	s_waitcnt vmcnt(47)
	v_lshlrev_b32_e32 v139, 16, v139
	v_fmac_f32_e32 v139, v242, v82
	v_cvt_pk_bf16_f32 v82, v139, s0
	global_store_short v[80:81], v82, off offset:2176
	s_waitcnt lgkmcnt(0)
	v_mul_f32_e32 v80, v84, v164
	s_waitcnt vmcnt(47)
	v_lshlrev_b32_e32 v142, 16, v142
	v_fmac_f32_e32 v142, v242, v80
	v_lshlrev_b32_e32 v83, 16, v82
	v_cvt_pk_bf16_f32 v82, v142, s0
	v_add_co_u32_e64 v80, s[0:1], s94, v96
	v_fmac_f32_e32 v99, v83, v83
	s_nop 0
	v_addc_co_u32_e64 v81, s[0:1], 0, v97, s[0:1]
	v_lshlrev_b32_e32 v83, 16, v82
	global_store_short v[80:81], v82, off offset:128
	v_mul_f32_e32 v82, v85, v165
	s_waitcnt vmcnt(47)
	v_lshlrev_b32_e32 v136, 16, v136
	v_fmac_f32_e32 v136, v242, v82
	v_cvt_pk_bf16_f32 v82, v136, s0
	global_store_short v[80:81], v82, off offset:2176
	v_mul_f32_e32 v80, v86, v166
	s_waitcnt vmcnt(47)
	v_lshlrev_b32_e32 v146, 16, v146
	v_fmac_f32_e32 v146, v242, v80
	v_fmac_f32_e32 v100, v83, v83
	v_lshlrev_b32_e32 v83, 16, v82
	v_cvt_pk_bf16_f32 v82, v146, s0
	v_add_co_u32_e64 v80, s[0:1], s57, v96
	v_fmac_f32_e32 v101, v83, v83
	s_nop 0
	v_addc_co_u32_e64 v81, s[0:1], 0, v97, s[0:1]
	v_lshlrev_b32_e32 v83, 16, v82
	global_store_short v[80:81], v82, off offset:128
	v_mul_f32_e32 v82, v87, v167
	s_waitcnt vmcnt(47)
	v_lshlrev_b32_e32 v140, 16, v140
	v_fmac_f32_e32 v140, v242, v82
	v_cvt_pk_bf16_f32 v82, v140, s0
	v_fmac_f32_e32 v116, v83, v83
	v_lshlrev_b32_e32 v83, 16, v82
	global_store_short v[80:81], v82, off offset:2176
	v_fmac_f32_e32 v102, v83, v83
	ds_read_b128 v[80:83], v151 offset:64
	v_fmac_f32_e32 v114, v149, v149
	v_fmac_f32_e32 v98, v147, v147
	s_waitcnt lgkmcnt(0)
	v_mul_f32_e32 v80, v88, v80
	s_waitcnt vmcnt(47)
	v_lshlrev_b32_e32 v129, 16, v129
	v_fmac_f32_e32 v129, v242, v80
	v_cvt_pk_bf16_f32 v80, v129, s0
	v_add_co_u32_e64 v84, s[0:1], s35, v96
	v_lshlrev_b32_e32 v86, 16, v80
	s_nop 0
	v_addc_co_u32_e64 v85, s[0:1], 0, v97, s[0:1]
	global_store_short v[84:85], v80, off offset:128
	v_mul_f32_e32 v80, v89, v81
	s_waitcnt vmcnt(47)
	v_lshlrev_b32_e32 v125, 16, v125
	v_fmac_f32_e32 v125, v242, v80
	v_cvt_pk_bf16_f32 v80, v125, s0
	v_lshlrev_b32_e32 v81, 16, v80
	global_store_short v[84:85], v80, off offset:2176
	v_mul_f32_e32 v80, v90, v82
	s_waitcnt vmcnt(47)
	v_lshlrev_b32_e32 v135, 16, v135
	v_fmac_f32_e32 v135, v242, v80
	v_cvt_pk_bf16_f32 v82, v135, s0
	v_add_co_u32_e64 v80, s[0:1], s58, v96
	v_fmac_f32_e32 v105, v81, v81
	s_nop 0
	v_addc_co_u32_e64 v81, s[0:1], 0, v97, s[0:1]
	v_lshlrev_b32_e32 v84, 16, v82
	global_store_short v[80:81], v82, off offset:128
	v_mul_f32_e32 v82, v91, v83
	s_waitcnt vmcnt(47)
	v_lshlrev_b32_e32 v131, 16, v131
	v_fmac_f32_e32 v131, v242, v82
	v_cvt_pk_bf16_f32 v82, v131, s0
	v_lshlrev_b32_e32 v83, 16, v82
	global_store_short v[80:81], v82, off offset:2176
	v_fmac_f32_e32 v103, v83, v83
	ds_read_b128 v[80:83], v151 offset:96
	v_fmac_f32_e32 v104, v84, v84
	v_fmac_f32_e32 v117, v86, v86
	v_mov_b32_e32 v125, v158
	s_waitcnt lgkmcnt(0)
	v_mul_f32_e32 v80, v92, v80
	s_waitcnt vmcnt(47)
	v_lshlrev_b32_e32 v120, 16, v120
	v_fmac_f32_e32 v120, v242, v80
	v_cvt_pk_bf16_f32 v80, v120, s0
	v_add_co_u32_e64 v84, s[0:1], s95, v96
	v_lshlrev_b32_e32 v86, 16, v80
	s_nop 0
	v_addc_co_u32_e64 v85, s[0:1], 0, v97, s[0:1]
	global_store_short v[84:85], v80, off offset:128
	v_mul_f32_e32 v80, v93, v81
	s_waitcnt vmcnt(47)
	v_lshlrev_b32_e32 v118, 16, v118
	v_fmac_f32_e32 v118, v242, v80
	v_cvt_pk_bf16_f32 v80, v118, s0
	v_lshlrev_b32_e32 v81, 16, v80
	global_store_short v[84:85], v80, off offset:2176
	v_mul_f32_e32 v80, v94, v82
	s_waitcnt vmcnt(47)
	v_lshlrev_b32_e32 v121, 16, v121
	v_fmac_f32_e32 v121, v242, v80
	v_cvt_pk_bf16_f32 v82, v121, s0
	v_add_co_u32_e64 v80, s[0:1], s59, v96
	v_fmac_f32_e32 v107, v81, v81
	s_nop 0
	v_addc_co_u32_e64 v81, s[0:1], 0, v97, s[0:1]
	v_lshlrev_b32_e32 v84, 16, v82
	global_store_short v[80:81], v82, off offset:128
	v_mul_f32_e32 v82, v95, v83
	s_waitcnt vmcnt(47)
	v_lshlrev_b32_e32 v119, 16, v119
	v_fmac_f32_e32 v119, v242, v82
	v_cvt_pk_bf16_f32 v82, v119, s0
	s_lshl_b64 s[0:1], s[28:29], 11
	global_store_short v[80:81], v82, off offset:2176
	v_mov_b32_e32 v80, v130
	s_add_u32 s46, s46, s0
	s_addc_u32 s47, s47, s1
	v_ashrrev_i32_e32 v81, 31, v80
	v_lshl_add_u64 v[80:81], v[80:81], 1, s[46:47]
	v_fmac_f32_e32 v106, v86, v86
	v_add_co_u32_e64 v86, s[0:1], s96, v80
	v_lshlrev_b32_e32 v83, 16, v82
	s_nop 0
	v_addc_co_u32_e64 v87, s[0:1], 0, v81, s[0:1]
	v_add_co_u32_e64 v88, s[0:1], s94, v80
	v_fmac_f32_e32 v109, v83, v83
	s_nop 0
	v_addc_co_u32_e64 v89, s[0:1], 0, v81, s[0:1]
	v_add_co_u32_e64 v90, s[0:1], s57, v80
	global_load_ushort v82, v[80:81], off
	global_load_ushort v83, v[80:81], off offset:2048
	v_addc_co_u32_e64 v91, s[0:1], 0, v81, s[0:1]
	v_add_co_u32_e64 v92, s[0:1], s35, v80
	v_fmac_f32_e32 v108, v84, v84
	s_nop 0
	v_addc_co_u32_e64 v93, s[0:1], 0, v81, s[0:1]
	v_add_co_u32_e64 v94, s[0:1], s58, v80
	global_load_ushort v84, v[86:87], off
	global_load_ushort v85, v[86:87], off offset:2048
	v_addc_co_u32_e64 v95, s[0:1], 0, v81, s[0:1]
	v_add_co_u32_e64 v96, s[0:1], s95, v80
	global_load_ushort v86, v[90:91], off offset:-4096
	global_load_ushort v87, v[88:89], off offset:2048
	s_nop 0
	global_load_ushort v88, v[90:91], off
	global_load_ushort v89, v[90:91], off offset:2048
	v_addc_co_u32_e64 v97, s[0:1], 0, v81, s[0:1]
	v_add_co_u32_e64 v80, s[0:1], s59, v80
	global_load_ushort v90, v[94:95], off offset:-4096
	global_load_ushort v91, v[92:93], off offset:2048
	s_nop 0
	global_load_ushort v92, v[94:95], off
	global_load_ushort v93, v[94:95], off offset:2048
	v_addc_co_u32_e64 v81, s[0:1], 0, v81, s[0:1]
	global_load_ushort v94, v[80:81], off offset:-4096
	global_load_ushort v95, v[96:97], off offset:2048
	s_nop 0
	global_load_ushort v96, v[80:81], off
	global_load_ushort v97, v[80:81], off offset:2048
	v_mov_b32_e32 v80, v128
	s_nop 0
	v_ashrrev_i32_e32 v81, 31, v80
	v_lshl_add_u64 v[80:81], v[80:81], 0, s[68:69]
	v_lshl_add_u64 v[118:119], v[80:81], 2, s[50:51]
	v_lshl_add_u32 v119, v125, 4, s37
	ds_read_b128 v[146:149], v119
	ds_read_b128 v[160:163], v119 offset:32
	v_lshl_add_u32 v120, v125, 2, s36
	v_ashrrev_i32_e32 v121, 31, v120
	v_lshlrev_b64 v[120:121], 11, v[120:121]
	s_waitcnt lgkmcnt(1)
	v_mul_f32_e32 v64, v64, v146
	v_lshl_add_u64 v[120:121], s[66:67], 0, v[120:121]
	v_lshl_add_u64 v[80:81], v[80:81], 1, v[120:121]
	s_waitcnt vmcnt(0)
	s_waitcnt vmcnt(47)
	v_lshlrev_b32_e32 v123, 16, v190
	v_fmac_f32_e32 v123, v243, v64
	v_mul_f32_e32 v64, v65, v147
	s_waitcnt vmcnt(46)
	v_lshlrev_b32_e32 v122, 16, v122
	v_fmac_f32_e32 v122, v243, v64
	v_mul_f32_e32 v64, v66, v148
	s_waitcnt vmcnt(45)
	v_lshlrev_b32_e32 v126, 16, v126
	v_fmac_f32_e32 v126, v243, v64
	v_cvt_pk_bf16_f32 v120, v123, s0
	v_cvt_pk_bf16_f32 v121, v122, s0
	v_cvt_pk_bf16_f32 v122, v126, s0
	v_add_co_u32_e64 v64, s[0:1], s96, v80
	v_mul_f32_e32 v66, v67, v149
	s_nop 0
	v_addc_co_u32_e64 v65, s[0:1], 0, v81, s[0:1]
	s_waitcnt vmcnt(44)
	v_lshlrev_b32_e32 v124, 16, v124
	v_fmac_f32_e32 v124, v243, v66
	s_nop 0
	v_cvt_pk_bf16_f32 v123, v124, s0
	global_store_short v[64:65], v122, off offset:192
	global_store_short v[64:65], v123, off offset:2240
	s_waitcnt lgkmcnt(0)
	v_mul_f32_e32 v64, v68, v160
	s_waitcnt vmcnt(45)
	v_lshlrev_b32_e32 v134, 16, v134
	v_fmac_f32_e32 v134, v243, v64
	v_cvt_pk_bf16_f32 v124, v134, s0
	v_add_co_u32_e64 v64, s[0:1], s94, v80
	v_mul_f32_e32 v66, v69, v161
	s_nop 0
	v_addc_co_u32_e64 v65, s[0:1], 0, v81, s[0:1]
	s_waitcnt vmcnt(44)
	v_lshlrev_b32_e32 v127, 16, v127
	v_fmac_f32_e32 v127, v243, v66
	s_nop 0
	v_cvt_pk_bf16_f32 v125, v127, s0
	global_store_short v[64:65], v124, off offset:192
	global_store_short v[64:65], v125, off offset:2240
	v_mul_f32_e32 v64, v70, v162
	s_waitcnt vmcnt(45)
	v_lshlrev_b32_e32 v145, 16, v145
	v_fmac_f32_e32 v145, v243, v64
	v_cvt_pk_bf16_f32 v70, v145, s0
	v_add_co_u32_e64 v64, s[0:1], s57, v80
	v_mul_f32_e32 v66, v71, v163
	s_nop 0
	v_addc_co_u32_e64 v65, s[0:1], 0, v81, s[0:1]
	s_waitcnt vmcnt(44)
	v_lshlrev_b32_e32 v143, 16, v143
	v_fmac_f32_e32 v143, v243, v66
	s_nop 0
	v_cvt_pk_bf16_f32 v71, v143, s0
	global_store_short v[64:65], v70, off offset:192
	global_store_short v[64:65], v71, off offset:2240
	ds_read_b128 v[64:67], v119 offset:64
	global_store_short v[80:81], v120, off offset:192
	global_store_short v[80:81], v121, off offset:2240
	s_waitcnt lgkmcnt(0)
	v_mul_f32_e32 v64, v72, v64
	s_waitcnt vmcnt(47)
	v_lshlrev_b32_e32 v138, 16, v138
	v_fmac_f32_e32 v138, v243, v64
	v_mul_f32_e32 v64, v73, v65
	v_cvt_pk_bf16_f32 v72, v138, s0
	v_add_co_u32_e64 v68, s[0:1], s35, v80
	s_waitcnt vmcnt(46)
	v_lshlrev_b32_e32 v137, 16, v137
	v_fmac_f32_e32 v137, v243, v64
	v_mul_f32_e32 v64, v74, v66
	v_addc_co_u32_e64 v69, s[0:1], 0, v81, s[0:1]
	s_waitcnt vmcnt(45)
	v_lshlrev_b32_e32 v144, 16, v144
	v_fmac_f32_e32 v144, v243, v64
	s_nop 0
	v_cvt_pk_bf16_f32 v73, v137, s0
	v_cvt_pk_bf16_f32 v74, v144, s0
	v_add_co_u32_e64 v64, s[0:1], s58, v80
	v_mul_f32_e32 v66, v75, v67
	s_nop 0
	v_addc_co_u32_e64 v65, s[0:1], 0, v81, s[0:1]
	s_waitcnt vmcnt(44)
	v_lshlrev_b32_e32 v141, 16, v141
	v_fmac_f32_e32 v141, v243, v66
	s_nop 0
	v_cvt_pk_bf16_f32 v75, v141, s0
	global_store_short v[64:65], v74, off offset:192
	global_store_short v[64:65], v75, off offset:2240
	ds_read_b128 v[64:67], v119 offset:96
	global_store_short v[68:69], v72, off offset:192
	global_store_short v[68:69], v73, off offset:2240
	s_waitcnt lgkmcnt(0)
	v_mul_f32_e32 v64, v76, v64
	s_waitcnt vmcnt(47)
	v_lshlrev_b32_e32 v111, 16, v111
	v_fmac_f32_e32 v111, v243, v64
	v_mul_f32_e32 v64, v77, v65
	v_cvt_pk_bf16_f32 v76, v111, s0
	v_add_co_u32_e64 v68, s[0:1], s95, v80
	s_waitcnt vmcnt(46)
	v_lshlrev_b32_e32 v110, 16, v110
	v_fmac_f32_e32 v110, v243, v64
	v_mul_f32_e32 v64, v78, v66
	v_addc_co_u32_e64 v69, s[0:1], 0, v81, s[0:1]
	s_waitcnt vmcnt(45)
	v_lshlrev_b32_e32 v113, 16, v113
	v_fmac_f32_e32 v113, v243, v64
	s_nop 0
	v_cvt_pk_bf16_f32 v77, v110, s0
	v_cvt_pk_bf16_f32 v66, v113, s0
	v_add_co_u32_e64 v64, s[0:1], s59, v80
	v_mul_f32_e32 v67, v79, v67
	s_nop 0
	v_addc_co_u32_e64 v65, s[0:1], 0, v81, s[0:1]
	s_waitcnt vmcnt(44)
	v_lshlrev_b32_e32 v112, 16, v112
	v_fmac_f32_e32 v112, v243, v67
	s_nop 0
	v_cvt_pk_bf16_f32 v67, v112, s0
	global_store_short v[64:65], v66, off offset:192
	global_store_short v[64:65], v67, off offset:2240
	v_lshlrev_b32_e32 v64, 16, v67
	v_fmac_f32_e32 v109, v64, v64
	v_lshlrev_b32_e32 v64, 16, v66
	v_fmac_f32_e32 v108, v64, v64
	v_lshlrev_b32_e32 v64, 16, v77
	v_fmac_f32_e32 v107, v64, v64
	v_lshlrev_b32_e32 v64, 16, v76
	v_fmac_f32_e32 v106, v64, v64
	v_lshlrev_b32_e32 v64, 16, v75
	v_fmac_f32_e32 v103, v64, v64
	v_lshlrev_b32_e32 v64, 16, v74
	v_fmac_f32_e32 v104, v64, v64
	v_lshlrev_b32_e32 v64, 16, v73
	v_fmac_f32_e32 v105, v64, v64
	v_lshlrev_b32_e32 v64, 16, v72
	v_fmac_f32_e32 v117, v64, v64
	v_lshlrev_b32_e32 v64, 16, v71
	v_fmac_f32_e32 v102, v64, v64
	v_lshlrev_b32_e32 v64, 16, v70
	v_fmac_f32_e32 v116, v64, v64
	v_lshlrev_b32_e32 v64, 16, v125
	v_fmac_f32_e32 v101, v64, v64
	v_lshlrev_b32_e32 v64, 16, v124
	v_fmac_f32_e32 v100, v64, v64
	v_lshlrev_b32_e32 v64, 16, v123
	v_fmac_f32_e32 v99, v64, v64
	v_lshlrev_b32_e32 v64, 16, v122
	v_fmac_f32_e32 v98, v64, v64
	v_lshlrev_b32_e32 v64, 16, v121
	v_fmac_f32_e32 v115, v64, v64
	v_lshlrev_b32_e32 v64, 16, v120
	v_fmac_f32_e32 v114, v64, v64
	v_cndmask_b32_e64 v65, v114, v117, s[44:45]
	ds_bpermute_b32 v65, v157, v65
	v_cndmask_b32_e64 v66, v115, v105, s[44:45]
	ds_bpermute_b32 v66, v157, v66
	v_cndmask_b32_e64 v67, v98, v104, s[44:45]
	global_store_short v[68:69], v76, off offset:192
	global_store_short v[68:69], v77, off offset:2240
	ds_bpermute_b32 v67, v157, v67
	v_cndmask_b32_e64 v68, v99, v103, s[44:45]
	ds_bpermute_b32 v68, v157, v68
	v_cndmask_b32_e64 v69, v100, v106, s[44:45]
	v_cndmask_b32_e64 v64, v117, v114, s[44:45]
	ds_bpermute_b32 v69, v157, v69
	v_cndmask_b32_e64 v70, v101, v107, s[44:45]
	s_waitcnt lgkmcnt(4)
	v_add_f32_e32 v64, v64, v65
	v_cndmask_b32_e64 v65, v105, v115, s[44:45]
	ds_bpermute_b32 v70, v157, v70
	v_cndmask_b32_e64 v71, v116, v108, s[44:45]
	s_waitcnt lgkmcnt(4)
	v_add_f32_e32 v65, v65, v66
	v_cndmask_b32_e64 v66, v104, v98, s[44:45]
	ds_bpermute_b32 v71, v157, v71
	v_cndmask_b32_e64 v72, v102, v109, s[44:45]
	s_waitcnt lgkmcnt(4)
	v_add_f32_e32 v66, v66, v67
	v_cndmask_b32_e64 v67, v103, v99, s[44:45]
	ds_bpermute_b32 v72, v157, v72
	s_waitcnt lgkmcnt(4)
	v_add_f32_e32 v67, v67, v68
	v_cndmask_b32_e64 v68, v106, v100, s[44:45]
	s_waitcnt lgkmcnt(3)
	v_add_f32_e32 v68, v68, v69
	v_cndmask_b32_e64 v69, v107, v101, s[44:45]
	s_waitcnt lgkmcnt(2)
	v_add_f32_e32 v69, v69, v70
	v_cndmask_b32_e64 v70, v108, v116, s[44:45]
	s_waitcnt lgkmcnt(1)
	v_add_f32_e32 v70, v70, v71
	v_cndmask_b32_e64 v71, v109, v102, s[44:45]
	s_waitcnt lgkmcnt(0)
	v_add_f32_e32 v71, v71, v72
	v_cndmask_b32_e64 v72, v68, v64, s[42:43]
	v_cndmask_b32_e64 v64, v64, v68, s[42:43]
	v_cndmask_b32_e64 v68, v69, v65, s[42:43]
	v_cndmask_b32_e64 v65, v65, v69, s[42:43]
	ds_bpermute_b32 v65, v156, v65
	ds_bpermute_b32 v64, v156, v64
	s_waitcnt lgkmcnt(1)
	v_add_f32_e32 v65, v68, v65
	v_cndmask_b32_e64 v68, v70, v66, s[42:43]
	v_cndmask_b32_e64 v66, v66, v70, s[42:43]
	ds_bpermute_b32 v66, v156, v66
	s_waitcnt lgkmcnt(1)
	v_add_f32_e32 v64, v72, v64
	s_waitcnt lgkmcnt(0)
	v_add_f32_e32 v66, v68, v66
	v_cndmask_b32_e64 v68, v71, v67, s[42:43]
	v_cndmask_b32_e64 v67, v67, v71, s[42:43]
	ds_bpermute_b32 v67, v156, v67
	s_waitcnt lgkmcnt(0)
	v_add_f32_e32 v67, v68, v67
	v_cndmask_b32_e64 v68, v66, v64, s[40:41]
	v_cndmask_b32_e64 v64, v64, v66, s[40:41]
	v_cndmask_b32_e64 v66, v67, v65, s[40:41]
	v_cndmask_b32_e64 v65, v65, v67, s[40:41]
	ds_bpermute_b32 v64, v155, v64
	ds_bpermute_b32 v65, v155, v65
	s_waitcnt lgkmcnt(1)
	v_add_f32_e32 v64, v68, v64
	s_waitcnt lgkmcnt(0)
	v_add_f32_e32 v65, v66, v65
	v_cndmask_b32_e64 v66, v65, v64, s[38:39]
	v_cndmask_b32_e64 v64, v64, v65, s[38:39]
	ds_bpermute_b32 v64, v154, v64
	s_waitcnt lgkmcnt(0)
	v_add_f32_e32 v64, v66, v64
	ds_bpermute_b32 v65, v153, v64
	s_and_saveexec_b64 s[0:1], vcc
	s_cbranch_execz .LBB0_571
	v_lshlrev_b64 v[66:67], 6, v[132:133]
	v_lshl_add_u64 v[66:67], s[26:27], 0, v[66:67]
	s_waitcnt lgkmcnt(0)
	v_add_f32_e32 v64, v64, v65
	global_store_dword v[66:67], v64, off
.LBB0_571:
	s_or_b64 exec, exec, s[0:1]
	v_mov_b32_e32 v64, v130
	v_lshlrev_b32_e32 v108, 16, v85
	s_waitcnt lgkmcnt(0)
	v_ashrrev_i32_e32 v65, 31, v64
	v_lshl_add_u64 v[64:65], v[64:65], 1, s[46:47]
	global_load_ushort v85, v[64:65], off offset:64
	v_lshlrev_b32_e32 v103, 16, v84
	v_lshlrev_b32_e32 v98, 16, v82
	v_lshlrev_b32_e32 v99, 16, v83
	v_lshlrev_b32_e32 v102, 16, v87
	v_lshlrev_b32_e32 v101, 16, v88
	v_lshlrev_b32_e32 v100, 16, v89
	v_lshlrev_b32_e32 v89, 16, v90
	v_lshlrev_b32_e32 v88, 16, v91
	v_lshlrev_b32_e32 v87, 16, v92
	v_mov_b32_e32 v92, v158
	v_lshlrev_b32_e32 v109, 16, v86
	v_lshlrev_b32_e32 v86, 16, v93
	v_lshlrev_b32_e32 v68, 16, v97
	v_lshlrev_b32_e32 v71, 16, v95
	v_lshlrev_b32_e32 v73, 16, v94
	v_lshlrev_b32_e32 v70, 16, v96
	s_waitcnt vmcnt(18)
	global_load_ushort v84, v[64:65], off offset:2112
	s_waitcnt vmcnt(19)
	v_add_co_u32_e64 v66, s[0:1], s96, v64
	s_nop 1
	v_addc_co_u32_e64 v67, s[0:1], 0, v65, s[0:1]
	global_load_ushort v83, v[66:67], off offset:64
	s_waitcnt vmcnt(20)
	global_load_ushort v82, v[66:67], off offset:2112
	s_waitcnt vmcnt(21)
	v_add_co_u32_e64 v66, s[0:1], s94, v64
	s_nop 1
	v_addc_co_u32_e64 v67, s[0:1], 0, v65, s[0:1]
	global_load_ushort v81, v[66:67], off offset:64
	s_waitcnt vmcnt(22)
	global_load_ushort v78, v[66:67], off offset:2112
	s_waitcnt vmcnt(23)
	v_add_co_u32_e64 v66, s[0:1], s57, v64
	s_nop 1
	v_addc_co_u32_e64 v67, s[0:1], 0, v65, s[0:1]
	global_load_ushort v80, v[66:67], off offset:64
	s_waitcnt vmcnt(24)
	global_load_ushort v79, v[66:67], off offset:2112
	s_waitcnt vmcnt(25)
	v_add_co_u32_e64 v66, s[0:1], s35, v64
	s_nop 1
	v_addc_co_u32_e64 v67, s[0:1], 0, v65, s[0:1]
	global_load_ushort v76, v[66:67], off offset:64
	s_waitcnt vmcnt(26)
	global_load_ushort v74, v[66:67], off offset:2112
	s_waitcnt vmcnt(27)
	v_add_co_u32_e64 v66, s[0:1], s58, v64
	s_nop 1
	v_addc_co_u32_e64 v67, s[0:1], 0, v65, s[0:1]
	global_load_ushort v77, v[66:67], off offset:64
	s_waitcnt vmcnt(28)
	global_load_ushort v75, v[66:67], off offset:2112
	s_waitcnt vmcnt(29)
	v_add_co_u32_e64 v66, s[0:1], s95, v64
	s_nop 1
	v_addc_co_u32_e64 v67, s[0:1], 0, v65, s[0:1]
	v_add_co_u32_e64 v64, s[0:1], s59, v64
	global_load_ushort v72, v[66:67], off offset:64
	s_nop 0
	v_addc_co_u32_e64 v65, s[0:1], 0, v65, s[0:1]
	global_load_ushort v66, v[66:67], off offset:2112
	s_waitcnt vmcnt(31)
	global_load_ushort v69, v[64:65], off offset:64
	s_waitcnt vmcnt(32)
	global_load_ushort v189, v[64:65], off offset:2112
	s_waitcnt vmcnt(33)
	s_waitcnt vmcnt(33)
	v_mov_b32_e32 v64, v128
	s_nop 0
	v_add_u32_e32 v64, s68, v64
	v_ashrrev_i32_e32 v65, 31, v64
	v_lshl_add_u64 v[90:91], v[64:65], 2, s[50:51]
	v_lshl_add_u32 v90, v92, 2, s28
	v_ashrrev_i32_e32 v91, 31, v90
	v_lshlrev_b64 v[90:91], 11, v[90:91]
	v_lshl_add_u64 v[90:91], s[66:67], 0, v[90:91]
	v_lshl_add_u32 v111, v92, 4, s37
	v_lshl_add_u64 v[64:65], v[64:65], 1, v[90:91]
	ds_read_b128 v[90:93], v111 offset:128
	ds_read_b128 v[104:107], v111 offset:160
	s_waitcnt lgkmcnt(1)
	v_mul_f32_e32 v48, v48, v90
	s_waitcnt vmcnt(33)
	v_fmac_f32_e32 v98, v240, v48
	v_cvt_pk_bf16_f32 v48, v98, s0
	v_lshlrev_b32_e32 v97, 16, v48
	global_store_short v[64:65], v48, off
	v_mul_f32_e32 v48, v49, v91
	v_fmac_f32_e32 v99, v240, v48
	v_cvt_pk_bf16_f32 v48, v99, s0
	v_lshlrev_b32_e32 v95, 16, v48
	global_store_short v[64:65], v48, off offset:2048
	v_mul_f32_e32 v48, v50, v92
	v_fmac_f32_e32 v103, v240, v48
	v_cvt_pk_bf16_f32 v50, v103, s0
	v_add_co_u32_e64 v48, s[0:1], s96, v64
	v_lshlrev_b32_e32 v94, 16, v50
	s_nop 0
	v_addc_co_u32_e64 v49, s[0:1], 0, v65, s[0:1]
	global_store_short v[48:49], v50, off
	v_mul_f32_e32 v50, v51, v93
	v_fmac_f32_e32 v108, v240, v50
	v_cvt_pk_bf16_f32 v50, v108, s0
	global_store_short v[48:49], v50, off offset:2048
	s_waitcnt lgkmcnt(0)
	v_mul_f32_e32 v48, v52, v104
	v_fmac_f32_e32 v109, v240, v48
	v_cvt_pk_bf16_f32 v52, v109, s0
	v_add_co_u32_e64 v48, s[0:1], s94, v64
	v_lshlrev_b32_e32 v99, 16, v50
	s_nop 0
	v_addc_co_u32_e64 v49, s[0:1], 0, v65, s[0:1]
	v_add_co_u32_e64 v50, s[0:1], s57, v64
	v_lshlrev_b32_e32 v98, 16, v52
	s_nop 0
	v_addc_co_u32_e64 v51, s[0:1], 0, v65, s[0:1]
	global_store_short v[50:51], v52, off offset:-4096
	v_mul_f32_e32 v52, v53, v105
	v_fmac_f32_e32 v102, v240, v52
	v_cvt_pk_bf16_f32 v53, v102, s0
	global_store_short v[48:49], v53, off offset:2048
	v_mul_f32_e32 v48, v54, v106
	v_fmac_f32_e32 v101, v240, v48
	v_cvt_pk_bf16_f32 v48, v101, s0
	v_lshlrev_b32_e32 v96, 16, v48
	global_store_short v[50:51], v48, off
	v_mul_f32_e32 v48, v55, v107
	v_fmac_f32_e32 v100, v240, v48
	v_cvt_pk_bf16_f32 v48, v100, s0
	v_lshlrev_b32_e32 v52, 16, v53
	v_lshlrev_b32_e32 v53, 16, v48
	global_store_short v[50:51], v48, off offset:2048
	ds_read_b128 v[48:51], v111 offset:192
	s_waitcnt lgkmcnt(0)
	v_mul_f32_e32 v48, v56, v48
	v_fmac_f32_e32 v89, v240, v48
	v_cvt_pk_bf16_f32 v48, v89, s0
	v_add_co_u32_e64 v54, s[0:1], s35, v64
	v_lshlrev_b32_e32 v92, 16, v48
	s_nop 0
	v_addc_co_u32_e64 v55, s[0:1], 0, v65, s[0:1]
	v_add_co_u32_e64 v100, s[0:1], s58, v64
	s_nop 1
	v_addc_co_u32_e64 v101, s[0:1], 0, v65, s[0:1]
	global_store_short v[100:101], v48, off offset:-4096
	v_mul_f32_e32 v48, v57, v49
	v_fmac_f32_e32 v88, v240, v48
	v_cvt_pk_bf16_f32 v48, v88, s0
	v_lshlrev_b32_e32 v93, 16, v48
	global_store_short v[54:55], v48, off offset:2048
	v_mul_f32_e32 v48, v58, v50
	v_fmac_f32_e32 v87, v240, v48
	v_cvt_pk_bf16_f32 v48, v87, s0
	v_lshlrev_b32_e32 v91, 16, v48
	global_store_short v[100:101], v48, off
	v_mul_f32_e32 v48, v59, v51
	v_fmac_f32_e32 v86, v240, v48
	v_cvt_pk_bf16_f32 v48, v86, s0
	v_lshlrev_b32_e32 v90, 16, v48
	global_store_short v[100:101], v48, off offset:2048
	ds_read_b128 v[48:51], v111 offset:224
	v_mov_b32_e32 v101, v158
	s_waitcnt lgkmcnt(0)
	v_mul_f32_e32 v48, v60, v48
	v_fmac_f32_e32 v73, v240, v48
	v_cvt_pk_bf16_f32 v48, v73, s0
	v_add_co_u32_e64 v54, s[0:1], s95, v64
	v_lshlrev_b32_e32 v89, 16, v48
	s_nop 0
	v_addc_co_u32_e64 v55, s[0:1], 0, v65, s[0:1]
	v_add_co_u32_e64 v56, s[0:1], s59, v64
	s_nop 1
	v_addc_co_u32_e64 v57, s[0:1], 0, v65, s[0:1]
	global_store_short v[56:57], v48, off offset:-4096
	v_mul_f32_e32 v48, v61, v49
	v_fmac_f32_e32 v71, v240, v48
	v_cvt_pk_bf16_f32 v48, v71, s0
	v_lshlrev_b32_e32 v88, 16, v48
	global_store_short v[54:55], v48, off offset:2048
	v_mul_f32_e32 v48, v62, v50
	v_fmac_f32_e32 v70, v240, v48
	v_cvt_pk_bf16_f32 v48, v70, s0
	v_lshlrev_b32_e32 v87, 16, v48
	global_store_short v[56:57], v48, off
	v_mul_f32_e32 v48, v63, v51
	v_fmac_f32_e32 v68, v240, v48
	v_cvt_pk_bf16_f32 v48, v68, s0
	v_lshlrev_b32_e32 v86, 16, v48
	global_store_short v[56:57], v48, off offset:2048
	v_mov_b32_e32 v48, v130
	s_nop 0
	v_ashrrev_i32_e32 v49, 31, v48
	v_lshl_add_u64 v[48:49], v[48:49], 1, s[46:47]
	global_load_ushort v73, v[48:49], off offset:128
	s_waitcnt vmcnt(50)
	global_load_ushort v70, v[48:49], off offset:2176
	s_waitcnt vmcnt(51)
	v_add_co_u32_e64 v50, s[0:1], s96, v48
	s_nop 1
	v_addc_co_u32_e64 v51, s[0:1], 0, v49, s[0:1]
	global_load_ushort v71, v[50:51], off offset:128
	s_waitcnt vmcnt(52)
	global_load_ushort v63, v[50:51], off offset:2176
	s_waitcnt vmcnt(53)
	v_add_co_u32_e64 v50, s[0:1], s94, v48
	s_nop 1
	v_addc_co_u32_e64 v51, s[0:1], 0, v49, s[0:1]
	global_load_ushort v65, v[50:51], off offset:128
	s_waitcnt vmcnt(54)
	global_load_ushort v62, v[50:51], off offset:2176
	s_waitcnt vmcnt(55)
	v_add_co_u32_e64 v50, s[0:1], s57, v48
	s_nop 1
	v_addc_co_u32_e64 v51, s[0:1], 0, v49, s[0:1]
	global_load_ushort v68, v[50:51], off offset:128
	s_waitcnt vmcnt(56)
	global_load_ushort v64, v[50:51], off offset:2176
	s_waitcnt vmcnt(57)
	v_add_co_u32_e64 v50, s[0:1], s35, v48
	s_nop 1
	v_addc_co_u32_e64 v51, s[0:1], 0, v49, s[0:1]
	global_load_ushort v59, v[50:51], off offset:128
	s_waitcnt vmcnt(58)
	global_load_ushort v58, v[50:51], off offset:2176
	s_waitcnt vmcnt(59)
	v_add_co_u32_e64 v50, s[0:1], s58, v48
	s_nop 1
	v_addc_co_u32_e64 v51, s[0:1], 0, v49, s[0:1]
	global_load_ushort v61, v[50:51], off offset:128
	s_waitcnt vmcnt(60)
	global_load_ushort v60, v[50:51], off offset:2176
	s_waitcnt vmcnt(61)
	v_add_co_u32_e64 v50, s[0:1], s95, v48
	s_nop 1
	v_addc_co_u32_e64 v51, s[0:1], 0, v49, s[0:1]
	global_load_ushort v56, v[50:51], off offset:128
	v_add_co_u32_e64 v48, s[0:1], s59, v48
	global_load_ushort v54, v[50:51], off offset:2176
	s_nop 0
	v_addc_co_u32_e64 v49, s[0:1], 0, v49, s[0:1]
	s_waitcnt vmcnt(1)
	global_load_ushort v57, v[48:49], off offset:128
	s_waitcnt vmcnt(2)
	global_load_ushort v55, v[48:49], off offset:2176
	s_waitcnt vmcnt(3)
	v_mov_b32_e32 v48, v128
	s_nop 0
	v_ashrrev_i32_e32 v49, 31, v48
	v_lshl_add_u64 v[48:49], v[48:49], 0, s[68:69]
	v_lshl_add_u64 v[50:51], v[48:49], 2, s[50:51]
	v_lshl_add_u32 v50, v101, 2, s28
	v_lshl_add_u32 v101, v101, 4, s37
	ds_read_b128 v[102:105], v101 offset:128
	ds_read_b128 v[106:109], v101 offset:160
	v_ashrrev_i32_e32 v51, 31, v50
	v_lshlrev_b64 v[50:51], 11, v[50:51]
	v_lshl_add_u64 v[50:51], s[66:67], 0, v[50:51]
	s_waitcnt lgkmcnt(1)
	v_mul_f32_e32 v32, v32, v102
	v_lshl_add_u64 v[48:49], v[48:49], 1, v[50:51]
	v_mul_f32_e32 v35, v35, v105
	s_waitcnt lgkmcnt(0)
	v_mul_f32_e32 v37, v37, v107
	s_waitcnt vmcnt(3)
	s_waitcnt vmcnt(47)
	v_lshlrev_b32_e32 v85, 16, v85
	v_fmac_f32_e32 v85, v241, v32
	v_cvt_pk_bf16_f32 v32, v85, s0
	v_lshlrev_b32_e32 v50, 16, v32
	global_store_short v[48:49], v32, off offset:64
	v_mul_f32_e32 v32, v33, v103
	s_waitcnt vmcnt(47)
	v_lshlrev_b32_e32 v84, 16, v84
	v_fmac_f32_e32 v84, v241, v32
	v_cvt_pk_bf16_f32 v32, v84, s0
	v_lshlrev_b32_e32 v33, 16, v32
	global_store_short v[48:49], v32, off offset:2112
	v_mul_f32_e32 v32, v34, v104
	s_waitcnt vmcnt(47)
	v_lshlrev_b32_e32 v83, 16, v83
	v_fmac_f32_e32 v83, v241, v32
	v_cvt_pk_bf16_f32 v34, v83, s0
	v_add_co_u32_e64 v32, s[0:1], s96, v48
	v_mul_f32_e32 v51, v33, v33
	s_nop 0
	v_addc_co_u32_e64 v33, s[0:1], 0, v49, s[0:1]
	s_waitcnt vmcnt(46)
	v_lshlrev_b32_e32 v82, 16, v82
	v_fmac_f32_e32 v82, v241, v35
	s_nop 0
	v_cvt_pk_bf16_f32 v35, v82, s0
	global_store_short v[32:33], v34, off offset:64
	global_store_short v[32:33], v35, off offset:2112
	v_mul_f32_e32 v32, v36, v106
	s_waitcnt vmcnt(47)
	v_lshlrev_b32_e32 v81, 16, v81
	v_fmac_f32_e32 v81, v241, v32
	v_cvt_pk_bf16_f32 v36, v81, s0
	v_add_co_u32_e64 v32, s[0:1], s94, v48
	s_waitcnt vmcnt(46)
	v_lshlrev_b32_e32 v78, 16, v78
	v_fmac_f32_e32 v78, v241, v37
	s_nop 0
	v_addc_co_u32_e64 v33, s[0:1], 0, v49, s[0:1]
	global_store_short v[32:33], v36, off offset:64
	s_nop 0
	v_cvt_pk_bf16_f32 v37, v78, s0
	global_store_short v[32:33], v37, off offset:2112
	v_mul_f32_e32 v32, v38, v108
	s_waitcnt vmcnt(47)
	v_lshlrev_b32_e32 v80, 16, v80
	v_fmac_f32_e32 v80, v241, v32
	v_lshlrev_b32_e32 v78, 16, v37
	v_cvt_pk_bf16_f32 v38, v80, s0
	v_add_co_u32_e64 v32, s[0:1], s57, v48
	v_mul_f32_e32 v37, v78, v78
	s_nop 0
	v_addc_co_u32_e64 v33, s[0:1], 0, v49, s[0:1]
	v_fmac_f32_e32 v37, v52, v52
	v_lshlrev_b32_e32 v52, 16, v38
	global_store_short v[32:33], v38, off offset:64
	v_mul_f32_e32 v38, v39, v109
	v_lshlrev_b32_e32 v81, 16, v36
	s_waitcnt vmcnt(47)
	v_lshlrev_b32_e32 v79, 16, v79
	v_fmac_f32_e32 v79, v241, v38
	v_mul_f32_e32 v36, v81, v81
	v_cvt_pk_bf16_f32 v38, v79, s0
	ds_read_b128 v[78:81], v101 offset:192
	global_store_short v[32:33], v38, off offset:2112
	v_lshlrev_b32_e32 v39, 16, v38
	v_mul_f32_e32 v38, v39, v39
	v_fmac_f32_e32 v38, v53, v53
	s_waitcnt lgkmcnt(0)
	v_mul_f32_e32 v32, v40, v78
	s_waitcnt vmcnt(47)
	v_lshlrev_b32_e32 v76, 16, v76
	v_fmac_f32_e32 v76, v241, v32
	v_cvt_pk_bf16_f32 v39, v76, s0
	v_add_co_u32_e64 v32, s[0:1], s35, v48
	v_lshlrev_b32_e32 v40, 16, v39
	s_nop 0
	v_addc_co_u32_e64 v33, s[0:1], 0, v49, s[0:1]
	global_store_short v[32:33], v39, off offset:64
	v_mul_f32_e32 v39, v41, v79
	s_waitcnt vmcnt(47)
	v_lshlrev_b32_e32 v74, 16, v74
	v_fmac_f32_e32 v74, v241, v39
	v_cvt_pk_bf16_f32 v39, v74, s0
	global_store_short v[32:33], v39, off offset:2112
	v_mul_f32_e32 v32, v42, v80
	s_waitcnt vmcnt(47)
	v_lshlrev_b32_e32 v77, 16, v77
	v_fmac_f32_e32 v77, v241, v32
	v_mul_f32_e32 v53, v40, v40
	v_lshlrev_b32_e32 v40, 16, v39
	v_cvt_pk_bf16_f32 v39, v77, s0
	v_add_co_u32_e64 v32, s[0:1], s58, v48
	v_mul_f32_e32 v41, v40, v40
	s_nop 0
	v_addc_co_u32_e64 v33, s[0:1], 0, v49, s[0:1]
	v_lshlrev_b32_e32 v40, 16, v39
	global_store_short v[32:33], v39, off offset:64
	v_mul_f32_e32 v39, v43, v81
	s_waitcnt vmcnt(47)
	v_lshlrev_b32_e32 v75, 16, v75
	v_fmac_f32_e32 v75, v241, v39
	v_cvt_pk_bf16_f32 v39, v75, s0
	ds_read_b128 v[74:77], v101 offset:224
	global_store_short v[32:33], v39, off offset:2112
	v_lshlrev_b32_e32 v42, 16, v39
	v_mul_f32_e32 v39, v42, v42
	v_lshlrev_b32_e32 v83, 16, v34
	s_waitcnt lgkmcnt(0)
	v_mul_f32_e32 v32, v44, v74
	s_waitcnt vmcnt(47)
	v_lshlrev_b32_e32 v72, 16, v72
	v_fmac_f32_e32 v72, v241, v32
	v_cvt_pk_bf16_f32 v42, v72, s0
	v_add_co_u32_e64 v32, s[0:1], s95, v48
	v_lshlrev_b32_e32 v43, 16, v42
	s_nop 0
	v_addc_co_u32_e64 v33, s[0:1], 0, v49, s[0:1]
	global_store_short v[32:33], v42, off offset:64
	v_mul_f32_e32 v42, v43, v43
	v_mul_f32_e32 v43, v45, v75
	s_waitcnt vmcnt(47)
	v_lshlrev_b32_e32 v66, 16, v66
	v_fmac_f32_e32 v66, v241, v43
	v_cvt_pk_bf16_f32 v43, v66, s0
	global_store_short v[32:33], v43, off offset:2112
	v_mul_f32_e32 v32, v46, v76
	v_lshlrev_b32_e32 v44, 16, v43
	s_waitcnt vmcnt(47)
	v_lshlrev_b32_e32 v69, 16, v69
	v_fmac_f32_e32 v69, v241, v32
	v_mul_f32_e32 v43, v44, v44
	v_cvt_pk_bf16_f32 v44, v69, s0
	v_add_co_u32_e64 v32, s[0:1], s59, v48
	v_lshlrev_b32_e32 v45, 16, v44
	s_nop 0
	v_addc_co_u32_e64 v33, s[0:1], 0, v49, s[0:1]
	global_store_short v[32:33], v44, off offset:64
	v_mul_f32_e32 v44, v45, v45
	v_mul_f32_e32 v45, v47, v77
	s_waitcnt vmcnt(47)
	v_lshlrev_b32_e32 v67, 16, v189
	v_fmac_f32_e32 v67, v241, v45
	v_cvt_pk_bf16_f32 v45, v67, s0
	global_store_short v[32:33], v45, off offset:2112
	v_lshlrev_b32_e32 v46, 16, v45
	v_ashrrev_i32_e32 v131, 31, v130
	v_lshl_add_u64 v[32:33], v[130:131], 1, s[46:47]
	v_mul_f32_e32 v45, v46, v46
	global_load_ushort v67, v[32:33], off offset:192
	v_lshlrev_b32_e32 v82, 16, v35
	v_mul_f32_e32 v34, v83, v83
	v_mul_f32_e32 v35, v82, v82
	v_fmac_f32_e32 v45, v86, v86
	v_mov_b32_e32 v86, v158
	v_mul_f32_e32 v40, v40, v40
	v_fmac_f32_e32 v40, v91, v91
	v_fmac_f32_e32 v39, v90, v90
	v_fmac_f32_e32 v42, v89, v89
	v_fmac_f32_e32 v43, v88, v88
	v_fmac_f32_e32 v44, v87, v87
	v_fmac_f32_e32 v51, v95, v95
	v_fmac_f32_e32 v35, v99, v99
	v_fmac_f32_e32 v36, v98, v98
	v_mul_f32_e32 v52, v52, v52
	v_fmac_f32_e32 v52, v96, v96
	v_fmac_f32_e32 v41, v93, v93
	v_fmac_f32_e32 v53, v92, v92
	v_mul_f32_e32 v50, v50, v50
	v_fmac_f32_e32 v50, v97, v97
	v_fmac_f32_e32 v34, v94, v94
	s_waitcnt vmcnt(20)
	global_load_ushort v66, v[32:33], off offset:2240
	s_waitcnt vmcnt(21)
	v_add_co_u32_e64 v46, s[0:1], s96, v32
	s_nop 1
	v_addc_co_u32_e64 v47, s[0:1], 0, v33, s[0:1]
	global_load_ushort v72, v[46:47], off offset:192
	s_waitcnt vmcnt(22)
	global_load_ushort v69, v[46:47], off offset:2240
	s_waitcnt vmcnt(23)
	v_add_co_u32_e64 v46, s[0:1], s94, v32
	s_nop 1
	v_addc_co_u32_e64 v47, s[0:1], 0, v33, s[0:1]
	global_load_ushort v75, v[46:47], off offset:192
	s_waitcnt vmcnt(24)
	global_load_ushort v74, v[46:47], off offset:2240
	s_waitcnt vmcnt(25)
	v_add_co_u32_e64 v46, s[0:1], s57, v32
	s_nop 1
	v_addc_co_u32_e64 v47, s[0:1], 0, v33, s[0:1]
	global_load_ushort v81, v[46:47], off offset:192
	s_waitcnt vmcnt(26)
	global_load_ushort v79, v[46:47], off offset:2240
	s_waitcnt vmcnt(27)
	v_add_co_u32_e64 v46, s[0:1], s35, v32
	s_nop 1
	v_addc_co_u32_e64 v47, s[0:1], 0, v33, s[0:1]
	global_load_ushort v77, v[46:47], off offset:192
	s_waitcnt vmcnt(28)
	global_load_ushort v76, v[46:47], off offset:2240
	s_waitcnt vmcnt(29)
	v_add_co_u32_e64 v46, s[0:1], s58, v32
	s_nop 1
	v_addc_co_u32_e64 v47, s[0:1], 0, v33, s[0:1]
	global_load_ushort v80, v[46:47], off offset:192
	s_waitcnt vmcnt(30)
	global_load_ushort v78, v[46:47], off offset:2240
	v_add_co_u32_e64 v48, s[0:1], s95, v32
	s_waitcnt vmcnt(31)
	v_addc_co_u32_e64 v49, s[0:1], 0, v33, s[0:1]
	global_load_ushort v47, v[48:49], off offset:192
	v_add_co_u32_e64 v32, s[0:1], s59, v32
	s_waitcnt vmcnt(32)
	v_addc_co_u32_e64 v33, s[0:1], 0, v33, s[0:1]
	global_load_ushort v46, v[48:49], off offset:2240
	s_waitcnt vmcnt(33)
	global_load_ushort v49, v[32:33], off offset:192
	s_waitcnt vmcnt(34)
	global_load_ushort v48, v[32:33], off offset:2240
	s_waitcnt vmcnt(35)
	v_mov_b32_e32 v32, v128
	s_nop 0
	v_ashrrev_i32_e32 v33, 31, v32
	v_lshl_add_u64 v[32:33], v[32:33], 0, s[68:69]
	v_lshl_add_u64 v[82:83], v[32:33], 2, s[50:51]
	v_lshl_add_u32 v84, v86, 2, s28
	v_ashrrev_i32_e32 v85, 31, v84
	v_lshlrev_b64 v[84:85], 11, v[84:85]
	v_lshl_add_u64 v[84:85], s[66:67], 0, v[84:85]
	v_lshl_add_u32 v83, v86, 4, s37
	v_lshl_add_u64 v[32:33], v[32:33], 1, v[84:85]
	ds_read_b128 v[84:87], v83 offset:128
	ds_read_b128 v[88:91], v83 offset:160
	s_waitcnt lgkmcnt(1)
	v_mul_f32_e32 v16, v16, v84
	s_waitcnt vmcnt(35)
	s_waitcnt vmcnt(47)
	v_lshlrev_b32_e32 v73, 16, v73
	v_fmac_f32_e32 v73, v242, v16
	v_cvt_pk_bf16_f32 v16, v73, s0
	v_lshlrev_b32_e32 v73, 16, v16
	global_store_short v[32:33], v16, off offset:128
	v_mul_f32_e32 v16, v17, v85
	s_waitcnt vmcnt(47)
	v_lshlrev_b32_e32 v70, 16, v70
	v_fmac_f32_e32 v70, v242, v16
	v_cvt_pk_bf16_f32 v16, v70, s0
	v_lshlrev_b32_e32 v17, 16, v16
	global_store_short v[32:33], v16, off offset:2176
	v_mul_f32_e32 v16, v18, v86
	s_waitcnt vmcnt(47)
	v_lshlrev_b32_e32 v71, 16, v71
	v_fmac_f32_e32 v71, v242, v16
	v_cvt_pk_bf16_f32 v18, v71, s0
	v_add_co_u32_e64 v16, s[0:1], s96, v32
	v_fmac_f32_e32 v51, v17, v17
	s_nop 0
	v_addc_co_u32_e64 v17, s[0:1], 0, v33, s[0:1]
	v_lshlrev_b32_e32 v70, 16, v18
	global_store_short v[16:17], v18, off offset:128
	v_mul_f32_e32 v18, v19, v87
	s_waitcnt vmcnt(47)
	v_lshlrev_b32_e32 v63, 16, v63
	v_fmac_f32_e32 v63, v242, v18
	v_cvt_pk_bf16_f32 v18, v63, s0
	global_store_short v[16:17], v18, off offset:2176
	s_waitcnt lgkmcnt(0)
	v_mul_f32_e32 v16, v20, v88
	s_waitcnt vmcnt(47)
	v_lshlrev_b32_e32 v65, 16, v65
	v_fmac_f32_e32 v65, v242, v16
	v_lshlrev_b32_e32 v19, 16, v18
	v_cvt_pk_bf16_f32 v18, v65, s0
	v_add_co_u32_e64 v16, s[0:1], s94, v32
	v_fmac_f32_e32 v35, v19, v19
	s_nop 0
	v_addc_co_u32_e64 v17, s[0:1], 0, v33, s[0:1]
	v_lshlrev_b32_e32 v19, 16, v18
	global_store_short v[16:17], v18, off offset:128
	v_mul_f32_e32 v18, v21, v89
	s_waitcnt vmcnt(47)
	v_lshlrev_b32_e32 v62, 16, v62
	v_fmac_f32_e32 v62, v242, v18
	v_cvt_pk_bf16_f32 v18, v62, s0
	global_store_short v[16:17], v18, off offset:2176
	v_mul_f32_e32 v16, v22, v90
	s_waitcnt vmcnt(47)
	v_lshlrev_b32_e32 v68, 16, v68
	v_fmac_f32_e32 v68, v242, v16
	v_fmac_f32_e32 v36, v19, v19
	v_lshlrev_b32_e32 v19, 16, v18
	v_cvt_pk_bf16_f32 v18, v68, s0
	v_add_co_u32_e64 v16, s[0:1], s57, v32
	v_fmac_f32_e32 v37, v19, v19
	s_nop 0
	v_addc_co_u32_e64 v17, s[0:1], 0, v33, s[0:1]
	v_lshlrev_b32_e32 v19, 16, v18
	global_store_short v[16:17], v18, off offset:128
	v_mul_f32_e32 v18, v23, v91
	s_waitcnt vmcnt(47)
	v_lshlrev_b32_e32 v64, 16, v64
	v_fmac_f32_e32 v64, v242, v18
	v_cvt_pk_bf16_f32 v18, v64, s0
	v_fmac_f32_e32 v52, v19, v19
	v_lshlrev_b32_e32 v19, 16, v18
	global_store_short v[16:17], v18, off offset:2176
	v_fmac_f32_e32 v38, v19, v19
	ds_read_b128 v[16:19], v83 offset:192
	v_fmac_f32_e32 v50, v73, v73
	v_fmac_f32_e32 v34, v70, v70
	s_waitcnt lgkmcnt(0)
	v_mul_f32_e32 v16, v24, v16
	s_waitcnt vmcnt(47)
	v_lshlrev_b32_e32 v59, 16, v59
	v_fmac_f32_e32 v59, v242, v16
	v_cvt_pk_bf16_f32 v16, v59, s0
	v_add_co_u32_e64 v20, s[0:1], s35, v32
	v_lshlrev_b32_e32 v22, 16, v16
	s_nop 0
	v_addc_co_u32_e64 v21, s[0:1], 0, v33, s[0:1]
	global_store_short v[20:21], v16, off offset:128
	v_mul_f32_e32 v16, v25, v17
	s_waitcnt vmcnt(47)
	v_lshlrev_b32_e32 v58, 16, v58
	v_fmac_f32_e32 v58, v242, v16
	v_cvt_pk_bf16_f32 v16, v58, s0
	v_lshlrev_b32_e32 v17, 16, v16
	global_store_short v[20:21], v16, off offset:2176
	v_mul_f32_e32 v16, v26, v18
	s_waitcnt vmcnt(47)
	v_lshlrev_b32_e32 v61, 16, v61
	v_fmac_f32_e32 v61, v242, v16
	v_cvt_pk_bf16_f32 v18, v61, s0
	v_add_co_u32_e64 v16, s[0:1], s58, v32
	v_fmac_f32_e32 v41, v17, v17
	s_nop 0
	v_addc_co_u32_e64 v17, s[0:1], 0, v33, s[0:1]
	v_lshlrev_b32_e32 v20, 16, v18
	global_store_short v[16:17], v18, off offset:128
	v_mul_f32_e32 v18, v27, v19
	s_waitcnt vmcnt(47)
	v_lshlrev_b32_e32 v60, 16, v60
	v_fmac_f32_e32 v60, v242, v18
	v_cvt_pk_bf16_f32 v18, v60, s0
	v_lshlrev_b32_e32 v19, 16, v18
	global_store_short v[16:17], v18, off offset:2176
	v_fmac_f32_e32 v39, v19, v19
	ds_read_b128 v[16:19], v83 offset:224
	v_fmac_f32_e32 v40, v20, v20
	v_fmac_f32_e32 v53, v22, v22
	s_waitcnt lgkmcnt(0)
	v_mul_f32_e32 v16, v28, v16
	s_waitcnt vmcnt(47)
	v_lshlrev_b32_e32 v56, 16, v56
	v_fmac_f32_e32 v56, v242, v16
	v_cvt_pk_bf16_f32 v16, v56, s0
	v_add_co_u32_e64 v20, s[0:1], s95, v32
	v_lshlrev_b32_e32 v22, 16, v16
	s_nop 0
	v_addc_co_u32_e64 v21, s[0:1], 0, v33, s[0:1]
	global_store_short v[20:21], v16, off offset:128
	v_mul_f32_e32 v16, v29, v17
	s_waitcnt vmcnt(47)
	v_lshlrev_b32_e32 v54, 16, v54
	v_fmac_f32_e32 v54, v242, v16
	v_cvt_pk_bf16_f32 v16, v54, s0
	v_lshlrev_b32_e32 v17, 16, v16
	global_store_short v[20:21], v16, off offset:2176
	v_mul_f32_e32 v16, v30, v18
	s_waitcnt vmcnt(47)
	v_lshlrev_b32_e32 v57, 16, v57
	v_fmac_f32_e32 v57, v242, v16
	v_cvt_pk_bf16_f32 v18, v57, s0
	v_add_co_u32_e64 v16, s[0:1], s59, v32
	v_fmac_f32_e32 v43, v17, v17
	s_nop 0
	v_addc_co_u32_e64 v17, s[0:1], 0, v33, s[0:1]
	v_lshlrev_b32_e32 v20, 16, v18
	global_store_short v[16:17], v18, off offset:128
	v_mul_f32_e32 v18, v31, v19
	s_waitcnt vmcnt(47)
	v_lshlrev_b32_e32 v55, 16, v55
	v_fmac_f32_e32 v55, v242, v18
	v_cvt_pk_bf16_f32 v18, v55, s0
	global_store_short v[16:17], v18, off offset:2176
	v_lshlrev_b32_e32 v19, 16, v18
	v_ashrrev_i32_e32 v129, 31, v128
	v_lshl_add_u64 v[16:17], v[128:129], 0, s[68:69]
	v_fmac_f32_e32 v45, v19, v19
	v_lshl_add_u64 v[18:19], v[16:17], 2, s[50:51]
	v_fmac_f32_e32 v44, v20, v20
	v_lshl_add_u32 v20, v158, 2, s28
	v_ashrrev_i32_e32 v21, 31, v20
	v_lshlrev_b64 v[20:21], 11, v[20:21]
	v_lshl_add_u64 v[20:21], s[66:67], 0, v[20:21]
	v_lshl_add_u32 v19, v158, 4, s37
	v_fmac_f32_e32 v42, v22, v22
	v_lshl_add_u64 v[16:17], v[16:17], 1, v[20:21]
	ds_read_b128 v[20:23], v19 offset:128
	ds_read_b128 v[24:27], v19 offset:160
	s_waitcnt lgkmcnt(1)
	v_mul_f32_e32 v0, v0, v20
	s_waitcnt vmcnt(51)
	s_waitcnt vmcnt(31)
	v_lshlrev_b32_e32 v67, 16, v67
	v_fmac_f32_e32 v67, v243, v0
	v_mul_f32_e32 v0, v1, v21
	s_waitcnt vmcnt(30)
	v_lshlrev_b32_e32 v66, 16, v66
	v_fmac_f32_e32 v66, v243, v0
	v_mul_f32_e32 v0, v2, v22
	s_waitcnt vmcnt(29)
	v_lshlrev_b32_e32 v72, 16, v72
	v_fmac_f32_e32 v72, v243, v0
	v_cvt_pk_bf16_f32 v20, v67, s0
	v_cvt_pk_bf16_f32 v21, v66, s0
	v_cvt_pk_bf16_f32 v22, v72, s0
	v_add_co_u32_e64 v0, s[0:1], s96, v16
	v_mul_f32_e32 v2, v3, v23
	s_nop 0
	v_addc_co_u32_e64 v1, s[0:1], 0, v17, s[0:1]
	s_waitcnt vmcnt(28)
	v_lshlrev_b32_e32 v69, 16, v69
	v_fmac_f32_e32 v69, v243, v2
	s_nop 0
	v_cvt_pk_bf16_f32 v23, v69, s0
	global_store_short v[0:1], v22, off offset:192
	global_store_short v[0:1], v23, off offset:2240
	s_waitcnt lgkmcnt(0)
	v_mul_f32_e32 v0, v4, v24
	s_waitcnt vmcnt(29)
	v_lshlrev_b32_e32 v75, 16, v75
	v_fmac_f32_e32 v75, v243, v0
	v_cvt_pk_bf16_f32 v24, v75, s0
	v_add_co_u32_e64 v0, s[0:1], s94, v16
	v_mul_f32_e32 v2, v5, v25
	s_nop 0
	v_addc_co_u32_e64 v1, s[0:1], 0, v17, s[0:1]
	s_waitcnt vmcnt(28)
	v_lshlrev_b32_e32 v74, 16, v74
	v_fmac_f32_e32 v74, v243, v2
	s_nop 0
	v_cvt_pk_bf16_f32 v25, v74, s0
	global_store_short v[0:1], v24, off offset:192
	global_store_short v[0:1], v25, off offset:2240
	v_mul_f32_e32 v0, v6, v26
	s_waitcnt vmcnt(29)
	v_lshlrev_b32_e32 v81, 16, v81
	v_fmac_f32_e32 v81, v243, v0
	v_cvt_pk_bf16_f32 v6, v81, s0
	v_add_co_u32_e64 v0, s[0:1], s57, v16
	v_mul_f32_e32 v2, v7, v27
	s_nop 0
	v_addc_co_u32_e64 v1, s[0:1], 0, v17, s[0:1]
	s_waitcnt vmcnt(28)
	v_lshlrev_b32_e32 v79, 16, v79
	v_fmac_f32_e32 v79, v243, v2
	s_nop 0
	v_cvt_pk_bf16_f32 v7, v79, s0
	global_store_short v[0:1], v6, off offset:192
	global_store_short v[0:1], v7, off offset:2240
	ds_read_b128 v[0:3], v19 offset:192
	global_store_short v[16:17], v20, off offset:192
	global_store_short v[16:17], v21, off offset:2240
	s_waitcnt lgkmcnt(0)
	v_mul_f32_e32 v0, v8, v0
	s_waitcnt vmcnt(31)
	v_lshlrev_b32_e32 v77, 16, v77
	v_fmac_f32_e32 v77, v243, v0
	v_mul_f32_e32 v0, v9, v1
	v_cvt_pk_bf16_f32 v8, v77, s0
	v_add_co_u32_e64 v4, s[0:1], s35, v16
	s_waitcnt vmcnt(30)
	v_lshlrev_b32_e32 v76, 16, v76
	v_fmac_f32_e32 v76, v243, v0
	v_mul_f32_e32 v0, v10, v2
	v_addc_co_u32_e64 v5, s[0:1], 0, v17, s[0:1]
	s_waitcnt vmcnt(29)
	v_lshlrev_b32_e32 v80, 16, v80
	v_fmac_f32_e32 v80, v243, v0
	s_nop 0
	v_cvt_pk_bf16_f32 v9, v76, s0
	v_cvt_pk_bf16_f32 v10, v80, s0
	v_add_co_u32_e64 v0, s[0:1], s58, v16
	v_mul_f32_e32 v2, v11, v3
	s_nop 0
	v_addc_co_u32_e64 v1, s[0:1], 0, v17, s[0:1]
	s_waitcnt vmcnt(28)
	v_lshlrev_b32_e32 v78, 16, v78
	v_fmac_f32_e32 v78, v243, v2
	s_nop 0
	v_cvt_pk_bf16_f32 v11, v78, s0
	global_store_short v[0:1], v10, off offset:192
	global_store_short v[0:1], v11, off offset:2240
	ds_read_b128 v[0:3], v19 offset:224
	global_store_short v[4:5], v8, off offset:192
	global_store_short v[4:5], v9, off offset:2240
	s_waitcnt lgkmcnt(0)
	v_mul_f32_e32 v0, v12, v0
	s_waitcnt vmcnt(31)
	v_lshlrev_b32_e32 v47, 16, v47
	v_fmac_f32_e32 v47, v243, v0
	v_mul_f32_e32 v0, v13, v1
	v_cvt_pk_bf16_f32 v12, v47, s0
	v_add_co_u32_e64 v4, s[0:1], s95, v16
	s_waitcnt vmcnt(30)
	v_lshlrev_b32_e32 v46, 16, v46
	v_fmac_f32_e32 v46, v243, v0
	v_mul_f32_e32 v0, v14, v2
	v_addc_co_u32_e64 v5, s[0:1], 0, v17, s[0:1]
	s_waitcnt vmcnt(29)
	v_lshlrev_b32_e32 v49, 16, v49
	v_fmac_f32_e32 v49, v243, v0
	s_nop 0
	v_cvt_pk_bf16_f32 v13, v46, s0
	v_cvt_pk_bf16_f32 v2, v49, s0
	v_add_co_u32_e64 v0, s[0:1], s59, v16
	v_mul_f32_e32 v3, v15, v3
	s_nop 0
	v_addc_co_u32_e64 v1, s[0:1], 0, v17, s[0:1]
	s_waitcnt vmcnt(28)
	v_lshlrev_b32_e32 v48, 16, v48
	v_fmac_f32_e32 v48, v243, v3
	s_nop 0
	v_cvt_pk_bf16_f32 v3, v48, s0
	global_store_short v[0:1], v2, off offset:192
	global_store_short v[0:1], v3, off offset:2240
	v_lshlrev_b32_e32 v0, 16, v20
	v_fmac_f32_e32 v50, v0, v0
	v_lshlrev_b32_e32 v0, 16, v21
	v_fmac_f32_e32 v51, v0, v0
	v_lshlrev_b32_e32 v0, 16, v22
	v_fmac_f32_e32 v34, v0, v0
	v_lshlrev_b32_e32 v0, 16, v23
	v_fmac_f32_e32 v35, v0, v0
	v_lshlrev_b32_e32 v0, 16, v24
	v_fmac_f32_e32 v36, v0, v0
	v_lshlrev_b32_e32 v0, 16, v25
	v_fmac_f32_e32 v37, v0, v0
	v_lshlrev_b32_e32 v0, 16, v6
	v_fmac_f32_e32 v52, v0, v0
	v_lshlrev_b32_e32 v0, 16, v7
	v_fmac_f32_e32 v38, v0, v0
	v_lshlrev_b32_e32 v0, 16, v8
	v_fmac_f32_e32 v53, v0, v0
	v_lshlrev_b32_e32 v0, 16, v9
	v_fmac_f32_e32 v41, v0, v0
	v_lshlrev_b32_e32 v0, 16, v10
	v_fmac_f32_e32 v40, v0, v0
	v_lshlrev_b32_e32 v0, 16, v11
	v_fmac_f32_e32 v39, v0, v0
	v_lshlrev_b32_e32 v0, 16, v12
	v_fmac_f32_e32 v42, v0, v0
	v_lshlrev_b32_e32 v0, 16, v13
	v_cndmask_b32_e64 v1, v50, v53, s[44:45]
	v_fmac_f32_e32 v43, v0, v0
	v_lshlrev_b32_e32 v0, 16, v2
	ds_bpermute_b32 v1, v157, v1
	v_cndmask_b32_e64 v2, v51, v41, s[44:45]
	v_fmac_f32_e32 v44, v0, v0
	v_lshlrev_b32_e32 v0, 16, v3
	ds_bpermute_b32 v2, v157, v2
	v_cndmask_b32_e64 v3, v34, v40, s[44:45]
	global_store_short v[4:5], v12, off offset:192
	global_store_short v[4:5], v13, off offset:2240
	ds_bpermute_b32 v3, v157, v3
	v_cndmask_b32_e64 v4, v35, v39, s[44:45]
	ds_bpermute_b32 v4, v157, v4
	v_cndmask_b32_e64 v5, v36, v42, s[44:45]
	v_fmac_f32_e32 v45, v0, v0
	v_cndmask_b32_e64 v0, v53, v50, s[44:45]
	ds_bpermute_b32 v5, v157, v5
	v_cndmask_b32_e64 v6, v37, v43, s[44:45]
	s_waitcnt lgkmcnt(4)
	v_add_f32_e32 v0, v0, v1
	v_cndmask_b32_e64 v1, v41, v51, s[44:45]
	ds_bpermute_b32 v6, v157, v6
	v_cndmask_b32_e64 v7, v52, v44, s[44:45]
	s_waitcnt lgkmcnt(4)
	v_add_f32_e32 v1, v1, v2
	v_cndmask_b32_e64 v2, v40, v34, s[44:45]
	ds_bpermute_b32 v7, v157, v7
	v_cndmask_b32_e64 v8, v38, v45, s[44:45]
	s_waitcnt lgkmcnt(4)
	v_add_f32_e32 v2, v2, v3
	v_cndmask_b32_e64 v3, v39, v35, s[44:45]
	ds_bpermute_b32 v8, v157, v8
	s_waitcnt lgkmcnt(4)
	v_add_f32_e32 v3, v3, v4
	v_cndmask_b32_e64 v4, v42, v36, s[44:45]
	s_waitcnt lgkmcnt(3)
	v_add_f32_e32 v4, v4, v5
	v_cndmask_b32_e64 v5, v43, v37, s[44:45]
	s_waitcnt lgkmcnt(2)
	v_add_f32_e32 v5, v5, v6
	v_cndmask_b32_e64 v6, v44, v52, s[44:45]
	s_waitcnt lgkmcnt(1)
	v_add_f32_e32 v6, v6, v7
	v_cndmask_b32_e64 v7, v45, v38, s[44:45]
	s_waitcnt lgkmcnt(0)
	v_add_f32_e32 v7, v7, v8
	v_cndmask_b32_e64 v8, v4, v0, s[42:43]
	v_cndmask_b32_e64 v0, v0, v4, s[42:43]
	v_cndmask_b32_e64 v4, v5, v1, s[42:43]
	v_cndmask_b32_e64 v1, v1, v5, s[42:43]
	ds_bpermute_b32 v1, v156, v1
	ds_bpermute_b32 v0, v156, v0
	s_waitcnt lgkmcnt(1)
	v_add_f32_e32 v1, v4, v1
	v_cndmask_b32_e64 v4, v6, v2, s[42:43]
	v_cndmask_b32_e64 v2, v2, v6, s[42:43]
	ds_bpermute_b32 v2, v156, v2
	s_waitcnt lgkmcnt(1)
	v_add_f32_e32 v0, v8, v0
	s_waitcnt lgkmcnt(0)
	v_add_f32_e32 v2, v4, v2
	v_cndmask_b32_e64 v4, v7, v3, s[42:43]
	v_cndmask_b32_e64 v3, v3, v7, s[42:43]
	ds_bpermute_b32 v3, v156, v3
	s_waitcnt lgkmcnt(0)
	v_add_f32_e32 v3, v4, v3
	v_cndmask_b32_e64 v4, v2, v0, s[40:41]
	v_cndmask_b32_e64 v0, v0, v2, s[40:41]
	v_cndmask_b32_e64 v2, v3, v1, s[40:41]
	v_cndmask_b32_e64 v1, v1, v3, s[40:41]
	ds_bpermute_b32 v0, v155, v0
	ds_bpermute_b32 v1, v155, v1
	s_waitcnt lgkmcnt(1)
	v_add_f32_e32 v0, v4, v0
	s_waitcnt lgkmcnt(0)
	v_add_f32_e32 v1, v2, v1
	v_cndmask_b32_e64 v2, v1, v0, s[38:39]
	v_cndmask_b32_e64 v0, v0, v1, s[38:39]
	ds_bpermute_b32 v0, v154, v0
	s_waitcnt lgkmcnt(0)
	v_add_f32_e32 v0, v2, v0
	ds_bpermute_b32 v1, v153, v0
	s_and_saveexec_b64 s[0:1], vcc
	s_cbranch_execz .LBB0_550
	v_or_b32_e32 v2, s28, v152
	v_ashrrev_i32_e32 v3, 31, v2
	v_lshlrev_b64 v[2:3], 6, v[2:3]
	v_lshl_add_u64 v[2:3], s[26:27], 0, v[2:3]
	s_waitcnt lgkmcnt(0)
	v_add_f32_e32 v0, v0, v1
	global_store_dword v[2:3], v0, off
	s_branch .LBB0_550
